# instruction selection: packed f32 mul/add in the G1/G4 scaling epilogues and the G2 gate mid hook / epilogue split into scalar pairs
# baseline (speedup 1.0000x reference)
.LBB0_400:
	s_lshl_b32 s13, s8, 8
	s_add_i32 s13, s13, s46
	v_or_b32_e32 v154, s13, v141
	v_and_b32_e32 v234, -16, v154
	v_lshlrev_b32_e32 v234, 6, v234
	v_lshl_add_u32 v234, v186, 4, v234
	v_add_u32_e32 v235, 0x2000, v234
	global_load_dwordx4 v[202:205], v234, s[0:1]
	global_load_dwordx4 v[206:209], v234, s[0:1] offset:1024
	global_load_dwordx4 v[210:213], v234, s[0:1] offset:2048
	global_load_dwordx4 v[214:217], v234, s[0:1] offset:3072
	global_load_dwordx4 v[218:221], v235, s[0:1]
	global_load_dwordx4 v[222:225], v235, s[0:1] offset:1024
	global_load_dwordx4 v[226:229], v235, s[0:1] offset:2048
	global_load_dwordx4 v[230:233], v235, s[0:1] offset:3072
	v_and_b32_e32 v236, 15, v186
	v_lshlrev_b32_e32 v236, 4, v236
	s_waitcnt vmcnt(0)
	v_add_f32_e32 v202, v202, v203
	v_add_f32_e32 v204, v204, v205
	v_add_f32_e32 v206, v206, v207
	v_add_f32_e32 v208, v208, v209
	v_add_f32_e32 v210, v210, v211
	v_add_f32_e32 v212, v212, v213
	v_add_f32_e32 v214, v214, v215
	v_add_f32_e32 v216, v216, v217
	v_add_f32_e32 v218, v218, v219
	v_add_f32_e32 v220, v220, v221
	v_add_f32_e32 v222, v222, v223
	v_add_f32_e32 v224, v224, v225
	v_add_f32_e32 v226, v226, v227
	v_add_f32_e32 v228, v228, v229
	v_add_f32_e32 v230, v230, v231
	v_add_f32_e32 v232, v232, v233
	v_add_f32_e32 v202, v202, v204
	v_add_f32_e32 v206, v206, v208
	v_add_f32_e32 v210, v210, v212
	v_add_f32_e32 v214, v214, v216
	v_add_f32_e32 v218, v218, v220
	v_add_f32_e32 v222, v222, v224
	v_add_f32_e32 v226, v226, v228
	v_add_f32_e32 v230, v230, v232
	v_add_f32_dpp v202, v202, v202 quad_perm:[1,0,3,2] row_mask:0xf bank_mask:0xf
	v_add_f32_dpp v206, v206, v206 quad_perm:[1,0,3,2] row_mask:0xf bank_mask:0xf
	v_add_f32_dpp v210, v210, v210 quad_perm:[1,0,3,2] row_mask:0xf bank_mask:0xf
	v_add_f32_dpp v214, v214, v214 quad_perm:[1,0,3,2] row_mask:0xf bank_mask:0xf
	v_add_f32_dpp v218, v218, v218 quad_perm:[1,0,3,2] row_mask:0xf bank_mask:0xf
	v_add_f32_dpp v222, v222, v222 quad_perm:[1,0,3,2] row_mask:0xf bank_mask:0xf
	v_add_f32_dpp v226, v226, v226 quad_perm:[1,0,3,2] row_mask:0xf bank_mask:0xf
	v_add_f32_dpp v230, v230, v230 quad_perm:[1,0,3,2] row_mask:0xf bank_mask:0xf
	v_add_f32_dpp v202, v202, v202 quad_perm:[2,3,0,1] row_mask:0xf bank_mask:0xf
	v_add_f32_dpp v206, v206, v206 quad_perm:[2,3,0,1] row_mask:0xf bank_mask:0xf
	v_add_f32_dpp v210, v210, v210 quad_perm:[2,3,0,1] row_mask:0xf bank_mask:0xf
	v_add_f32_dpp v214, v214, v214 quad_perm:[2,3,0,1] row_mask:0xf bank_mask:0xf
	v_add_f32_dpp v218, v218, v218 quad_perm:[2,3,0,1] row_mask:0xf bank_mask:0xf
	v_add_f32_dpp v222, v222, v222 quad_perm:[2,3,0,1] row_mask:0xf bank_mask:0xf
	v_add_f32_dpp v226, v226, v226 quad_perm:[2,3,0,1] row_mask:0xf bank_mask:0xf
	v_add_f32_dpp v230, v230, v230 quad_perm:[2,3,0,1] row_mask:0xf bank_mask:0xf
	v_fmamk_f32 v202, v202, 0x3a800000, v182
	v_fmamk_f32 v206, v206, 0x3a800000, v182
	v_fmamk_f32 v210, v210, 0x3a800000, v182
	v_fmamk_f32 v214, v214, 0x3a800000, v182
	v_fmamk_f32 v218, v218, 0x3a800000, v182
	v_fmamk_f32 v222, v222, 0x3a800000, v182
	v_fmamk_f32 v226, v226, 0x3a800000, v182
	v_fmamk_f32 v230, v230, 0x3a800000, v182
	v_mul_f32_e32 v203, 0x4b800000, v202
	v_mul_f32_e32 v207, 0x4b800000, v206
	v_mul_f32_e32 v211, 0x4b800000, v210
	v_mul_f32_e32 v215, 0x4b800000, v214
	v_mul_f32_e32 v219, 0x4b800000, v218
	v_mul_f32_e32 v223, 0x4b800000, v222
	v_mul_f32_e32 v227, 0x4b800000, v226
	v_mul_f32_e32 v231, 0x4b800000, v230
	v_cmp_gt_f32_e32 vcc, 0x800000, v202
	s_nop 1
	v_cndmask_b32_e32 v204, v202, v203, vcc
	v_rsq_f32_e32 v204, v204
	s_nop 0
	v_mul_f32_e32 v205, 0x45800000, v204
	v_cndmask_b32_e32 v204, v204, v205, vcc
	v_cmp_gt_f32_e32 vcc, 0x800000, v206
	s_nop 1
	v_cndmask_b32_e32 v208, v206, v207, vcc
	v_rsq_f32_e32 v208, v208
	s_nop 0
	v_mul_f32_e32 v209, 0x45800000, v208
	v_cndmask_b32_e32 v208, v208, v209, vcc
	v_cmp_gt_f32_e32 vcc, 0x800000, v210
	s_nop 1
	v_cndmask_b32_e32 v212, v210, v211, vcc
	v_rsq_f32_e32 v212, v212
	s_nop 0
	v_mul_f32_e32 v213, 0x45800000, v212
	v_cndmask_b32_e32 v212, v212, v213, vcc
	v_cmp_gt_f32_e32 vcc, 0x800000, v214
	s_nop 1
	v_cndmask_b32_e32 v216, v214, v215, vcc
	v_rsq_f32_e32 v216, v216
	s_nop 0
	v_mul_f32_e32 v217, 0x45800000, v216
	v_cndmask_b32_e32 v216, v216, v217, vcc
	v_cmp_gt_f32_e32 vcc, 0x800000, v218
	s_nop 1
	v_cndmask_b32_e32 v220, v218, v219, vcc
	v_rsq_f32_e32 v220, v220
	s_nop 0
	v_mul_f32_e32 v221, 0x45800000, v220
	v_cndmask_b32_e32 v220, v220, v221, vcc
	v_cmp_gt_f32_e32 vcc, 0x800000, v222
	s_nop 1
	v_cndmask_b32_e32 v224, v222, v223, vcc
	v_rsq_f32_e32 v224, v224
	s_nop 0
	v_mul_f32_e32 v225, 0x45800000, v224
	v_cndmask_b32_e32 v224, v224, v225, vcc
	v_cmp_gt_f32_e32 vcc, 0x800000, v226
	s_nop 1
	v_cndmask_b32_e32 v228, v226, v227, vcc
	v_rsq_f32_e32 v228, v228
	s_nop 0
	v_mul_f32_e32 v229, 0x45800000, v228
	v_cndmask_b32_e32 v228, v228, v229, vcc
	v_cmp_gt_f32_e32 vcc, 0x800000, v230
	s_nop 1
	v_cndmask_b32_e32 v232, v230, v231, vcc
	v_rsq_f32_e32 v232, v232
	s_nop 0
	v_mul_f32_e32 v233, 0x45800000, v232
	v_cndmask_b32_e32 v232, v232, v233, vcc
	s_nop 1
	ds_bpermute_b32 v238, v236, v204
	ds_bpermute_b32 v239, v236, v208
	ds_bpermute_b32 v240, v236, v212
	ds_bpermute_b32 v241, v236, v216
	ds_bpermute_b32 v242, v236, v220
	ds_bpermute_b32 v243, v236, v224
	ds_bpermute_b32 v244, v236, v228
	ds_bpermute_b32 v245, v236, v232
	s_waitcnt lgkmcnt(0)
	v_ashrrev_i32_e32 v155, 31, v154
	v_lshlrev_b64 v[152:153], 6, v[154:155]
	v_lshl_add_u64 v[152:153], s[0:1], 0, v[152:153]
	s_lshl_b32 s24, s12, 8
	v_or_b32_e32 v155, s13, v145
	s_movk_i32 s8, 0x1320
	v_or_b32_e32 v152, s24, v138
	v_cmp_gt_i32_e64 s[8:9], s8, v152
	v_mov_b32_e32 v156, v238
	v_mov_b32_e32 v157, v156
	s_and_saveexec_b64 s[10:11], s[8:9]
	s_cbranch_execz .LBB0_405
	v_mov_b32_e32 v166, v156
	v_mov_b32_e32 v167, v156
	v_mul_f32_e32 v128, v128, v166
	v_mul_f32_e32 v129, v129, v167
	v_mul_f32_e32 v126, v126, v156
	v_mul_f32_e32 v127, v127, v157
	v_mul_f32_e32 v166, v124, v166
	v_mul_f32_e32 v167, v125, v167
	v_mul_f32_e32 v124, v122, v156
	v_mul_f32_e32 v125, v123, v157
	s_and_b32 s17, s12, 0xfffffe
	v_cvt_pk_bf16_f32 v122, v126, v127
	v_cvt_pk_bf16_f32 v123, v128, v129
	v_cvt_pk_bf16_f32 v124, v124, v125
	v_cvt_pk_bf16_f32 v125, v166, v167
	s_cmp_lg_u32 s17, 4
	s_mov_b64 s[26:27], -1
	s_cbranch_scc0 .LBB0_403
	v_mov_b64_e32 v[126:127], s[4:5]
	v_mad_i64_i32 v[126:127], s[26:27], v154, s90, v[126:127]
	v_ashrrev_i32_e32 v153, 31, v152
	v_lshl_add_u64 v[126:127], v[152:153], 1, v[126:127]
	global_store_dwordx4 v[126:127], v[122:125], off
	s_mov_b64 s[26:27], 0

.LBB0_405:
	s_or_b64 exec, exec, s[10:11]
	s_or_b32 s17, s24, 0x80
	v_or_b32_e32 v122, s17, v138
	s_movk_i32 s10, 0x1320
	v_cmp_gt_i32_e64 s[10:11], s10, v122
	s_and_saveexec_b64 s[26:27], s[10:11]
	s_cbranch_execz .LBB0_415
	v_mov_b32_e32 v124, v156
	v_mov_b32_e32 v125, v156
	v_mul_f32_e32 v120, v120, v124
	v_mul_f32_e32 v121, v121, v125
	v_mul_f32_e32 v118, v118, v156
	v_mul_f32_e32 v119, v119, v157
	v_mul_f32_e32 v124, v116, v124
	v_mul_f32_e32 v125, v117, v125
	v_mul_f32_e32 v116, v114, v156
	v_mul_f32_e32 v117, v115, v157
	s_and_b32 s19, s12, 0xfffffe
	v_cvt_pk_bf16_f32 v114, v118, v119
	v_cvt_pk_bf16_f32 v115, v120, v121
	v_cvt_pk_bf16_f32 v116, v116, v117
	v_cvt_pk_bf16_f32 v117, v124, v125
	s_cmp_eq_u32 s19, 4
	s_mov_b64 s[28:29], -1
	s_cbranch_scc1 .LBB0_413
	s_cmpk_lt_i32 s17, 0xa80
	s_cbranch_scc1 .LBB0_409
	s_cmpk_lg_i32 s17, 0xa80
	s_cselect_b64 s[30:31], -1, 0
	s_cbranch_execz .LBB0_410
	s_branch .LBB0_411

.LBB0_415:
	s_or_b64 exec, exec, s[26:27]
	v_or_b32_e32 v114, s13, v147
	v_ashrrev_i32_e32 v115, 31, v114
	v_lshlrev_b64 v[116:117], 6, v[114:115]
	v_lshl_add_u64 v[120:121], s[0:1], 0, v[116:117]
	v_mov_b32_e32 v116, v239
	v_mov_b32_e32 v117, v116
	s_and_saveexec_b64 s[26:27], s[8:9]
	s_cbranch_execz .LBB0_420
	v_mov_b32_e32 v118, v116
	v_mov_b32_e32 v119, v116
	v_mul_f32_e32 v112, v112, v118
	v_mul_f32_e32 v113, v113, v119
	v_mul_f32_e32 v110, v110, v116
	v_mul_f32_e32 v111, v111, v117
	v_mul_f32_e32 v118, v108, v118
	v_mul_f32_e32 v119, v109, v119
	v_mul_f32_e32 v108, v106, v116
	v_mul_f32_e32 v109, v107, v117
	s_and_b32 s19, s12, 0xfffffe
	v_cvt_pk_bf16_f32 v106, v110, v111
	v_cvt_pk_bf16_f32 v107, v112, v113
	v_cvt_pk_bf16_f32 v108, v108, v109
	v_cvt_pk_bf16_f32 v109, v118, v119
	s_cmp_eq_u32 s19, 4
	s_mov_b64 s[28:29], -1
	s_cbranch_scc1 .LBB0_418
	v_mov_b64_e32 v[110:111], s[4:5]
	v_mad_i64_i32 v[110:111], s[28:29], v114, s90, v[110:111]
	v_ashrrev_i32_e32 v153, 31, v152
	v_lshl_add_u64 v[110:111], v[152:153], 1, v[110:111]
	s_mov_b64 s[28:29], 0
	global_store_dwordx4 v[110:111], v[106:109], off

.LBB0_420:
	s_or_b64 exec, exec, s[26:27]
	s_and_saveexec_b64 s[26:27], s[10:11]
	s_cbranch_execz .LBB0_430
	v_mov_b32_e32 v106, v116
	v_mov_b32_e32 v107, v116
	v_mul_f32_e32 v104, v104, v106
	v_mul_f32_e32 v105, v105, v107
	v_mul_f32_e32 v102, v102, v116
	v_mul_f32_e32 v103, v103, v117
	v_mul_f32_e32 v106, v100, v106
	v_mul_f32_e32 v107, v101, v107
	v_mul_f32_e32 v100, v98, v116
	v_mul_f32_e32 v101, v99, v117
	s_and_b32 s19, s12, 0xfffffe
	v_cvt_pk_bf16_f32 v98, v102, v103
	v_cvt_pk_bf16_f32 v99, v104, v105
	v_cvt_pk_bf16_f32 v100, v100, v101
	v_cvt_pk_bf16_f32 v101, v106, v107
	s_cmp_eq_u32 s19, 4
	s_mov_b64 s[28:29], -1
	s_cbranch_scc1 .LBB0_428
	s_cmpk_lt_i32 s17, 0xa80
	s_cbranch_scc1 .LBB0_424
	s_cmpk_lg_i32 s17, 0xa80
	s_cselect_b64 s[30:31], -1, 0
	s_cbranch_execz .LBB0_425
	s_branch .LBB0_426

.LBB0_430:
	s_or_b64 exec, exec, s[26:27]
	v_or_b32_e32 v98, s13, v158
	v_ashrrev_i32_e32 v99, 31, v98
	v_lshlrev_b64 v[100:101], 6, v[98:99]
	v_lshl_add_u64 v[112:113], s[0:1], 0, v[100:101]
	v_mov_b32_e32 v100, v240
	v_mov_b32_e32 v101, v100
	s_and_saveexec_b64 s[26:27], s[8:9]
	s_cbranch_execz .LBB0_435
	v_mov_b32_e32 v102, v100
	v_mov_b32_e32 v103, v100
	v_mul_f32_e32 v96, v96, v102
	v_mul_f32_e32 v97, v97, v103
	v_mul_f32_e32 v94, v94, v100
	v_mul_f32_e32 v95, v95, v101
	v_mul_f32_e32 v102, v92, v102
	v_mul_f32_e32 v103, v93, v103
	v_mul_f32_e32 v92, v90, v100
	v_mul_f32_e32 v93, v91, v101
	s_and_b32 s19, s12, 0xfffffe
	v_cvt_pk_bf16_f32 v90, v94, v95
	v_cvt_pk_bf16_f32 v91, v96, v97
	v_cvt_pk_bf16_f32 v92, v92, v93
	v_cvt_pk_bf16_f32 v93, v102, v103
	s_cmp_eq_u32 s19, 4
	s_mov_b64 s[28:29], -1
	s_cbranch_scc1 .LBB0_433
	v_mov_b64_e32 v[94:95], s[4:5]
	v_mad_i64_i32 v[94:95], s[28:29], v98, s90, v[94:95]
	v_ashrrev_i32_e32 v153, 31, v152
	v_lshl_add_u64 v[94:95], v[152:153], 1, v[94:95]
	s_mov_b64 s[28:29], 0
	global_store_dwordx4 v[94:95], v[90:93], off

.LBB0_435:
	s_or_b64 exec, exec, s[26:27]
	s_and_saveexec_b64 s[26:27], s[10:11]
	s_cbranch_execz .LBB0_445
	v_mov_b32_e32 v90, v100
	v_mov_b32_e32 v91, v100
	v_mul_f32_e32 v88, v88, v90
	v_mul_f32_e32 v89, v89, v91
	v_mul_f32_e32 v86, v86, v100
	v_mul_f32_e32 v87, v87, v101
	v_mul_f32_e32 v90, v84, v90
	v_mul_f32_e32 v91, v85, v91
	v_mul_f32_e32 v84, v82, v100
	v_mul_f32_e32 v85, v83, v101
	s_and_b32 s19, s12, 0xfffffe
	v_cvt_pk_bf16_f32 v82, v86, v87
	v_cvt_pk_bf16_f32 v83, v88, v89
	v_cvt_pk_bf16_f32 v84, v84, v85
	v_cvt_pk_bf16_f32 v85, v90, v91
	s_cmp_eq_u32 s19, 4
	s_mov_b64 s[28:29], -1
	s_cbranch_scc1 .LBB0_443
	s_cmpk_lt_i32 s17, 0xa80
	s_cbranch_scc1 .LBB0_439
	s_cmpk_lg_i32 s17, 0xa80
	s_cselect_b64 s[30:31], -1, 0
	s_cbranch_execz .LBB0_440
	s_branch .LBB0_441

.LBB0_445:
	s_or_b64 exec, exec, s[26:27]
	v_or_b32_e32 v82, s13, v159
	v_ashrrev_i32_e32 v83, 31, v82
	v_lshlrev_b64 v[84:85], 6, v[82:83]
	v_lshl_add_u64 v[96:97], s[0:1], 0, v[84:85]
	v_mov_b32_e32 v84, v241
	v_mov_b32_e32 v85, v84
	s_and_saveexec_b64 s[26:27], s[8:9]
	s_cbranch_execz .LBB0_450
	v_mov_b32_e32 v86, v84
	v_mov_b32_e32 v87, v84
	v_mul_f32_e32 v80, v80, v86
	v_mul_f32_e32 v81, v81, v87
	v_mul_f32_e32 v78, v78, v84
	v_mul_f32_e32 v79, v79, v85
	v_mul_f32_e32 v86, v76, v86
	v_mul_f32_e32 v87, v77, v87
	v_mul_f32_e32 v76, v74, v84
	v_mul_f32_e32 v77, v75, v85
	s_and_b32 s19, s12, 0xfffffe
	v_cvt_pk_bf16_f32 v74, v78, v79
	v_cvt_pk_bf16_f32 v75, v80, v81
	v_cvt_pk_bf16_f32 v76, v76, v77
	v_cvt_pk_bf16_f32 v77, v86, v87
	s_cmp_eq_u32 s19, 4
	s_mov_b64 s[28:29], -1
	s_cbranch_scc1 .LBB0_448
	v_mov_b64_e32 v[78:79], s[4:5]
	v_mad_i64_i32 v[78:79], s[28:29], v82, s90, v[78:79]
	v_ashrrev_i32_e32 v153, 31, v152
	v_lshl_add_u64 v[78:79], v[152:153], 1, v[78:79]
	s_mov_b64 s[28:29], 0
	global_store_dwordx4 v[78:79], v[74:77], off

.LBB0_450:
	s_or_b64 exec, exec, s[26:27]
	s_and_saveexec_b64 s[26:27], s[10:11]
	s_cbranch_execz .LBB0_460
	v_mov_b32_e32 v74, v84
	v_mov_b32_e32 v75, v84
	v_mul_f32_e32 v72, v72, v74
	v_mul_f32_e32 v73, v73, v75
	v_mul_f32_e32 v70, v70, v84
	v_mul_f32_e32 v71, v71, v85
	v_mul_f32_e32 v74, v68, v74
	v_mul_f32_e32 v75, v69, v75
	v_mul_f32_e32 v68, v66, v84
	v_mul_f32_e32 v69, v67, v85
	s_and_b32 s19, s12, 0xfffffe
	v_cvt_pk_bf16_f32 v66, v70, v71
	v_cvt_pk_bf16_f32 v67, v72, v73
	v_cvt_pk_bf16_f32 v68, v68, v69
	v_cvt_pk_bf16_f32 v69, v74, v75
	s_cmp_eq_u32 s19, 4
	s_mov_b64 s[28:29], -1
	s_cbranch_scc1 .LBB0_458
	s_cmpk_lt_i32 s17, 0xa80
	s_cbranch_scc1 .LBB0_454
	s_cmpk_lg_i32 s17, 0xa80
	s_cselect_b64 s[30:31], -1, 0
	s_cbranch_execz .LBB0_455
	s_branch .LBB0_456

.LBB0_460:
	s_or_b64 exec, exec, s[26:27]
	s_addk_i32 s13, 0x80
	v_or_b32_e32 v66, s13, v141
	v_ashrrev_i32_e32 v67, 31, v66
	v_lshlrev_b64 v[68:69], 6, v[66:67]
	v_lshl_add_u64 v[80:81], s[0:1], 0, v[68:69]
	v_mov_b32_e32 v68, v242
	v_mov_b32_e32 v69, v68
	v_or_b32_e32 v67, s13, v145
	s_and_saveexec_b64 s[26:27], s[8:9]
	s_cbranch_execz .LBB0_465
	v_mov_b32_e32 v70, v68
	v_mov_b32_e32 v71, v68
	v_mul_f32_e32 v64, v64, v70
	v_mul_f32_e32 v65, v65, v71
	v_mul_f32_e32 v62, v62, v68
	v_mul_f32_e32 v63, v63, v69
	v_mul_f32_e32 v70, v60, v70
	v_mul_f32_e32 v71, v61, v71
	v_mul_f32_e32 v60, v58, v68
	v_mul_f32_e32 v61, v59, v69
	s_and_b32 s19, s12, 0xfffffe
	v_cvt_pk_bf16_f32 v58, v62, v63
	v_cvt_pk_bf16_f32 v59, v64, v65
	v_cvt_pk_bf16_f32 v60, v60, v61
	v_cvt_pk_bf16_f32 v61, v70, v71
	s_cmp_eq_u32 s19, 4
	s_mov_b64 s[28:29], -1
	s_cbranch_scc1 .LBB0_463
	v_mov_b64_e32 v[62:63], s[4:5]
	v_mad_i64_i32 v[62:63], s[28:29], v66, s90, v[62:63]
	v_ashrrev_i32_e32 v153, 31, v152
	v_lshl_add_u64 v[62:63], v[152:153], 1, v[62:63]
	s_mov_b64 s[28:29], 0
	global_store_dwordx4 v[62:63], v[58:61], off

.LBB0_465:
	s_or_b64 exec, exec, s[26:27]
	s_and_saveexec_b64 s[26:27], s[10:11]
	s_cbranch_execz .LBB0_475
	v_mov_b32_e32 v58, v68
	v_mov_b32_e32 v59, v68
	v_mul_f32_e32 v56, v56, v58
	v_mul_f32_e32 v57, v57, v59
	v_mul_f32_e32 v54, v54, v68
	v_mul_f32_e32 v55, v55, v69
	v_mul_f32_e32 v58, v52, v58
	v_mul_f32_e32 v59, v53, v59
	v_mul_f32_e32 v52, v50, v68
	v_mul_f32_e32 v53, v51, v69
	s_and_b32 s19, s12, 0xfffffe
	v_cvt_pk_bf16_f32 v50, v54, v55
	v_cvt_pk_bf16_f32 v51, v56, v57
	v_cvt_pk_bf16_f32 v52, v52, v53
	v_cvt_pk_bf16_f32 v53, v58, v59
	s_cmp_eq_u32 s19, 4
	s_mov_b64 s[28:29], -1
	s_cbranch_scc1 .LBB0_473
	s_cmpk_lt_i32 s17, 0xa80
	s_cbranch_scc1 .LBB0_469
	s_cmpk_lg_i32 s17, 0xa80
	s_cselect_b64 s[30:31], -1, 0
	s_cbranch_execz .LBB0_470
	s_branch .LBB0_471

.LBB0_475:
	s_or_b64 exec, exec, s[26:27]
	v_or_b32_e32 v50, s13, v147
	v_ashrrev_i32_e32 v51, 31, v50
	v_lshlrev_b64 v[52:53], 6, v[50:51]
	v_lshl_add_u64 v[64:65], s[0:1], 0, v[52:53]
	v_mov_b32_e32 v52, v243
	v_mov_b32_e32 v53, v52
	s_and_saveexec_b64 s[26:27], s[8:9]
	s_cbranch_execz .LBB0_480
	v_mov_b32_e32 v54, v52
	v_mov_b32_e32 v55, v52
	v_mul_f32_e32 v48, v48, v54
	v_mul_f32_e32 v49, v49, v55
	v_mul_f32_e32 v46, v46, v52
	v_mul_f32_e32 v47, v47, v53
	v_mul_f32_e32 v54, v44, v54
	v_mul_f32_e32 v55, v45, v55
	v_mul_f32_e32 v44, v42, v52
	v_mul_f32_e32 v45, v43, v53
	s_and_b32 s19, s12, 0xfffffe
	v_cvt_pk_bf16_f32 v42, v46, v47
	v_cvt_pk_bf16_f32 v43, v48, v49
	v_cvt_pk_bf16_f32 v44, v44, v45
	v_cvt_pk_bf16_f32 v45, v54, v55
	s_cmp_eq_u32 s19, 4
	s_mov_b64 s[28:29], -1
	s_cbranch_scc1 .LBB0_478
	v_mov_b64_e32 v[46:47], s[4:5]
	v_mad_i64_i32 v[46:47], s[28:29], v50, s90, v[46:47]
	v_ashrrev_i32_e32 v153, 31, v152
	v_lshl_add_u64 v[46:47], v[152:153], 1, v[46:47]
	s_mov_b64 s[28:29], 0
	global_store_dwordx4 v[46:47], v[42:45], off

.LBB0_480:
	s_or_b64 exec, exec, s[26:27]
	s_and_saveexec_b64 s[26:27], s[10:11]
	s_cbranch_execz .LBB0_490
	v_mov_b32_e32 v42, v52
	v_mov_b32_e32 v43, v52
	v_mul_f32_e32 v40, v40, v42
	v_mul_f32_e32 v41, v41, v43
	v_mul_f32_e32 v38, v38, v52
	v_mul_f32_e32 v39, v39, v53
	v_mul_f32_e32 v42, v36, v42
	v_mul_f32_e32 v43, v37, v43
	v_mul_f32_e32 v36, v34, v52
	v_mul_f32_e32 v37, v35, v53
	s_and_b32 s19, s12, 0xfffffe
	v_cvt_pk_bf16_f32 v34, v38, v39
	v_cvt_pk_bf16_f32 v35, v40, v41
	v_cvt_pk_bf16_f32 v36, v36, v37
	v_cvt_pk_bf16_f32 v37, v42, v43
	s_cmp_eq_u32 s19, 4
	s_mov_b64 s[28:29], -1
	s_cbranch_scc1 .LBB0_488
	s_cmpk_lt_i32 s17, 0xa80
	s_cbranch_scc1 .LBB0_484
	s_cmpk_lg_i32 s17, 0xa80
	s_cselect_b64 s[30:31], -1, 0
	s_cbranch_execz .LBB0_485
	s_branch .LBB0_486

.LBB0_490:
	s_or_b64 exec, exec, s[26:27]
	v_or_b32_e32 v34, s13, v158
	v_ashrrev_i32_e32 v35, 31, v34
	v_lshlrev_b64 v[36:37], 6, v[34:35]
	v_lshl_add_u64 v[48:49], s[0:1], 0, v[36:37]
	v_mov_b32_e32 v36, v244
	v_mov_b32_e32 v37, v36
	s_and_saveexec_b64 s[26:27], s[8:9]
	s_cbranch_execz .LBB0_495
	v_mov_b32_e32 v38, v36
	v_mov_b32_e32 v39, v36
	v_mul_f32_e32 v32, v32, v38
	v_mul_f32_e32 v33, v33, v39
	v_mul_f32_e32 v30, v30, v36
	v_mul_f32_e32 v31, v31, v37
	v_mul_f32_e32 v38, v28, v38
	v_mul_f32_e32 v39, v29, v39
	v_mul_f32_e32 v28, v26, v36
	v_mul_f32_e32 v29, v27, v37
	s_and_b32 s19, s12, 0xfffffe
	v_cvt_pk_bf16_f32 v26, v30, v31
	v_cvt_pk_bf16_f32 v27, v32, v33
	v_cvt_pk_bf16_f32 v28, v28, v29
	v_cvt_pk_bf16_f32 v29, v38, v39
	s_cmp_eq_u32 s19, 4
	s_mov_b64 s[28:29], -1
	s_cbranch_scc1 .LBB0_493
	v_mov_b64_e32 v[30:31], s[4:5]
	v_mad_i64_i32 v[30:31], s[28:29], v34, s90, v[30:31]
	v_ashrrev_i32_e32 v153, 31, v152
	v_lshl_add_u64 v[30:31], v[152:153], 1, v[30:31]
	s_mov_b64 s[28:29], 0
	global_store_dwordx4 v[30:31], v[26:29], off

.LBB0_495:
	s_or_b64 exec, exec, s[26:27]
	s_and_saveexec_b64 s[26:27], s[10:11]
	s_cbranch_execz .LBB0_505
	v_mov_b32_e32 v26, v36
	v_mov_b32_e32 v27, v36
	v_mul_f32_e32 v24, v24, v26
	v_mul_f32_e32 v25, v25, v27
	v_mul_f32_e32 v22, v22, v36
	v_mul_f32_e32 v23, v23, v37
	v_mul_f32_e32 v26, v20, v26
	v_mul_f32_e32 v27, v21, v27
	v_mul_f32_e32 v20, v18, v36
	v_mul_f32_e32 v21, v19, v37
	s_and_b32 s19, s12, 0xfffffe
	v_cvt_pk_bf16_f32 v18, v22, v23
	v_cvt_pk_bf16_f32 v19, v24, v25
	v_cvt_pk_bf16_f32 v20, v20, v21
	v_cvt_pk_bf16_f32 v21, v26, v27
	s_cmp_eq_u32 s19, 4
	s_mov_b64 s[28:29], -1
	s_cbranch_scc1 .LBB0_503
	s_cmpk_lt_i32 s17, 0xa80
	s_cbranch_scc1 .LBB0_499
	s_cmpk_lg_i32 s17, 0xa80
	s_cselect_b64 s[30:31], -1, 0
	s_cbranch_execz .LBB0_500
	s_branch .LBB0_501

.LBB0_505:
	s_or_b64 exec, exec, s[26:27]
	v_or_b32_e32 v18, s13, v159
	v_ashrrev_i32_e32 v19, 31, v18
	v_lshlrev_b64 v[20:21], 6, v[18:19]
	v_lshl_add_u64 v[32:33], s[0:1], 0, v[20:21]
	v_mov_b32_e32 v20, v245
	v_mov_b32_e32 v21, v20
	s_and_saveexec_b64 s[26:27], s[8:9]
	s_cbranch_execz .LBB0_510
	v_mov_b32_e32 v22, v20
	v_mov_b32_e32 v23, v20
	v_mul_f32_e32 v16, v16, v22
	v_mul_f32_e32 v17, v17, v23
	v_mul_f32_e32 v14, v14, v20
	v_mul_f32_e32 v15, v15, v21
	v_mul_f32_e32 v22, v12, v22
	v_mul_f32_e32 v23, v13, v23
	v_mul_f32_e32 v12, v10, v20
	v_mul_f32_e32 v13, v11, v21
	s_and_b32 s8, s12, 0xfffffe
	v_cvt_pk_bf16_f32 v10, v14, v15
	v_cvt_pk_bf16_f32 v11, v16, v17
	v_cvt_pk_bf16_f32 v12, v12, v13
	v_cvt_pk_bf16_f32 v13, v22, v23
	s_cmp_eq_u32 s8, 4
	s_mov_b64 s[8:9], -1
	s_cbranch_scc1 .LBB0_508
	v_mov_b64_e32 v[14:15], s[4:5]
	v_mad_i64_i32 v[14:15], s[8:9], v18, s90, v[14:15]
	v_ashrrev_i32_e32 v153, 31, v152
	v_lshl_add_u64 v[14:15], v[152:153], 1, v[14:15]
	s_mov_b64 s[8:9], 0
	global_store_dwordx4 v[14:15], v[10:13], off

.LBB0_510:
	s_or_b64 exec, exec, s[26:27]
	s_and_saveexec_b64 s[8:9], s[10:11]
	s_cbranch_execz .LBB0_520
	v_mov_b32_e32 v10, v20
	v_mov_b32_e32 v11, v20
	v_mul_f32_e32 v8, v8, v10
	v_mul_f32_e32 v9, v9, v11
	v_mul_f32_e32 v6, v6, v20
	v_mul_f32_e32 v7, v7, v21
	v_mul_f32_e32 v10, v4, v10
	v_mul_f32_e32 v11, v5, v11
	v_mul_f32_e32 v4, v2, v20
	v_mul_f32_e32 v5, v3, v21
	s_and_b32 s10, s12, 0xfffffe
	v_cvt_pk_bf16_f32 v2, v6, v7
	v_cvt_pk_bf16_f32 v3, v8, v9
	v_cvt_pk_bf16_f32 v4, v4, v5
	v_cvt_pk_bf16_f32 v5, v10, v11
	s_cmp_eq_u32 s10, 4
	s_mov_b64 s[10:11], -1
	s_cbranch_scc1 .LBB0_518
	s_cmpk_lt_i32 s17, 0xa80
	s_cbranch_scc1 .LBB0_514
	s_cmpk_lg_i32 s17, 0xa80
	s_cselect_b64 s[12:13], -1, 0
	s_cbranch_execz .LBB0_515
	s_branch .LBB0_516

.LBB0_1080:
	s_andn2_b64 vcc, exec, s[26:27]
	s_cbranch_vccnz .LBB0_1082
	v_mov_b32_e32 v0, v151
	s_movk_i32 s30, 0x1320
	s_nop 0
	v_mad_u64_u32 v[2:3], s[28:29], v0, s30, v[136:137]
	v_mov_b32_e32 v215, 0
	v_add_u32_e32 v214, s13, v2
	v_lshlrev_b64 v[216:217], 1, v[214:215]
	v_lshl_add_u64 v[218:219], s[4:5], 0, v[216:217]
	v_lshl_add_u64 v[220:221], s[8:9], 0, v[216:217]
	global_load_dwordx2 v[218:219], v[218:219], off
	global_load_dwordx2 v[220:221], v[220:221], off
	v_add_u32_e32 v214, s56, v2
	v_lshlrev_b64 v[216:217], 1, v[214:215]
	v_lshl_add_u64 v[222:223], s[4:5], 0, v[216:217]
	v_lshl_add_u64 v[224:225], s[8:9], 0, v[216:217]
	global_load_dwordx2 v[222:223], v[222:223], off
	global_load_dwordx2 v[224:225], v[224:225], off
	v_add_u32_e32 v214, s57, v2
	v_lshlrev_b64 v[216:217], 1, v[214:215]
	v_lshl_add_u64 v[226:227], s[4:5], 0, v[216:217]
	v_lshl_add_u64 v[228:229], s[8:9], 0, v[216:217]
	global_load_dwordx2 v[226:227], v[226:227], off
	global_load_dwordx2 v[228:229], v[228:229], off
	v_add_u32_e32 v214, s58, v2
	v_lshlrev_b64 v[216:217], 1, v[214:215]
	v_lshl_add_u64 v[230:231], s[4:5], 0, v[216:217]
	v_lshl_add_u64 v[232:233], s[8:9], 0, v[216:217]
	global_load_dwordx2 v[230:231], v[230:231], off
	global_load_dwordx2 v[232:233], v[232:233], off
	s_nop 0
	s_nop 0
	s_nop 0
	s_nop 0
	s_waitcnt vmcnt(6)
	v_lshlrev_b32_e32 v0, 16, v220
	v_mul_f32_e32 v0, 0xbfb8aa3b, v0
	v_exp_f32_e32 v0, v0
	s_nop 0
	v_min_f32_e32 v168, 0x7149f2ca, v0
	v_lshlrev_b32_e32 v0, 16, v218
	v_mul_f32_e32 v0, 0xbfb8aa3b, v0
	v_exp_f32_e32 v0, v0
	s_nop 0
	v_min_f32_e32 v0, 0x7149f2ca, v0
	v_add_f32_e32 v0, 1.0, v0
	v_rcp_f32_e32 v170, v0
	v_and_b32_e32 v0, 0xffff0000, v220
	v_mul_f32_e32 v0, 0xbfb8aa3b, v0
	v_exp_f32_e32 v0, v0
	s_nop 0
	v_min_f32_e32 v169, 0x7149f2ca, v0
	v_and_b32_e32 v0, 0xffff0000, v218
	v_mul_f32_e32 v0, 0xbfb8aa3b, v0
	v_exp_f32_e32 v0, v0
	v_add_f32_e32 v168, 1.0, v168
	v_add_f32_e32 v169, 1.0, v169
	v_min_f32_e32 v0, 0x7149f2ca, v0
	v_add_f32_e32 v0, 1.0, v0
	v_rcp_f32_e32 v171, v0
	v_lshlrev_b32_e32 v0, 16, v221
	v_mul_f32_e32 v0, 0xbfb8aa3b, v0
	v_exp_f32_e32 v0, v0
	v_mul_f32_e32 v168, v168, v170
	v_mul_f32_e32 v169, v169, v171
	v_min_f32_e32 v146, 0x7149f2ca, v0
	v_lshlrev_b32_e32 v0, 16, v219
	v_mul_f32_e32 v0, 0xbfb8aa3b, v0
	v_exp_f32_e32 v0, v0
	v_mul_f32_e32 v128, v128, v168
	v_mul_f32_e32 v129, v129, v169
	v_min_f32_e32 v0, 0x7149f2ca, v0
	v_add_f32_e32 v0, 1.0, v0
	v_rcp_f32_e32 v166, v0
	v_and_b32_e32 v0, 0xffff0000, v221
	v_mul_f32_e32 v0, 0xbfb8aa3b, v0
	v_exp_f32_e32 v0, v0
	s_nop 0
	v_min_f32_e32 v147, 0x7149f2ca, v0
	v_and_b32_e32 v0, 0xffff0000, v219
	v_mul_f32_e32 v0, 0xbfb8aa3b, v0
	v_exp_f32_e32 v0, v0
	v_add_f32_e32 v146, 1.0, v146
	v_add_f32_e32 v147, 1.0, v147
	v_min_f32_e32 v0, 0x7149f2ca, v0
	v_add_f32_e32 v0, 1.0, v0
	v_rcp_f32_e32 v167, v0
	s_nop 0
	v_mul_f32_e32 v146, v146, v166
	v_mul_f32_e32 v147, v147, v167
	s_nop 0
	v_mul_f32_e32 v130, v130, v146
	v_mul_f32_e32 v131, v131, v147
	s_nop 0
	s_nop 0
	s_nop 0
	s_waitcnt vmcnt(4)
	v_lshlrev_b32_e32 v0, 16, v224
	v_mul_f32_e32 v0, 0xbfb8aa3b, v0
	v_exp_f32_e32 v0, v0
	s_nop 0
	v_min_f32_e32 v168, 0x7149f2ca, v0
	v_lshlrev_b32_e32 v0, 16, v222
	v_mul_f32_e32 v0, 0xbfb8aa3b, v0
	v_exp_f32_e32 v0, v0
	s_nop 0
	v_min_f32_e32 v0, 0x7149f2ca, v0
	v_add_f32_e32 v0, 1.0, v0
	v_rcp_f32_e32 v170, v0
	v_and_b32_e32 v0, 0xffff0000, v224
	v_mul_f32_e32 v0, 0xbfb8aa3b, v0
	v_exp_f32_e32 v0, v0
	s_nop 0
	v_min_f32_e32 v169, 0x7149f2ca, v0
	v_and_b32_e32 v0, 0xffff0000, v222
	v_mul_f32_e32 v0, 0xbfb8aa3b, v0
	v_exp_f32_e32 v0, v0
	v_add_f32_e32 v168, 1.0, v168
	v_add_f32_e32 v169, 1.0, v169
	v_min_f32_e32 v0, 0x7149f2ca, v0
	v_add_f32_e32 v0, 1.0, v0
	v_rcp_f32_e32 v171, v0
	v_lshlrev_b32_e32 v0, 16, v225
	v_mul_f32_e32 v0, 0xbfb8aa3b, v0
	v_exp_f32_e32 v0, v0
	v_mul_f32_e32 v168, v168, v170
	v_mul_f32_e32 v169, v169, v171
	v_min_f32_e32 v146, 0x7149f2ca, v0
	v_lshlrev_b32_e32 v0, 16, v223
	v_mul_f32_e32 v0, 0xbfb8aa3b, v0
	v_exp_f32_e32 v0, v0
	v_mul_f32_e32 v124, v124, v168
	v_mul_f32_e32 v125, v125, v169
	v_min_f32_e32 v0, 0x7149f2ca, v0
	v_add_f32_e32 v0, 1.0, v0
	v_rcp_f32_e32 v166, v0
	v_and_b32_e32 v0, 0xffff0000, v225
	v_mul_f32_e32 v0, 0xbfb8aa3b, v0
	v_exp_f32_e32 v0, v0
	s_nop 0
	v_min_f32_e32 v147, 0x7149f2ca, v0
	v_and_b32_e32 v0, 0xffff0000, v223
	v_mul_f32_e32 v0, 0xbfb8aa3b, v0
	v_exp_f32_e32 v0, v0
	v_add_f32_e32 v146, 1.0, v146
	v_add_f32_e32 v147, 1.0, v147
	v_min_f32_e32 v0, 0x7149f2ca, v0
	v_add_f32_e32 v0, 1.0, v0
	v_rcp_f32_e32 v167, v0
	s_nop 0
	v_mul_f32_e32 v146, v146, v166
	v_mul_f32_e32 v147, v147, v167
	s_nop 0
	v_mul_f32_e32 v126, v126, v146
	v_mul_f32_e32 v127, v127, v147
	s_nop 0
	s_nop 0
	s_nop 0
	s_waitcnt vmcnt(2)
	v_lshlrev_b32_e32 v0, 16, v228
	v_mul_f32_e32 v0, 0xbfb8aa3b, v0
	v_exp_f32_e32 v0, v0
	s_nop 0
	v_min_f32_e32 v168, 0x7149f2ca, v0
	v_lshlrev_b32_e32 v0, 16, v226
	v_mul_f32_e32 v0, 0xbfb8aa3b, v0
	v_exp_f32_e32 v0, v0
	s_nop 0
	v_min_f32_e32 v0, 0x7149f2ca, v0
	v_add_f32_e32 v0, 1.0, v0
	v_rcp_f32_e32 v170, v0
	v_and_b32_e32 v0, 0xffff0000, v228
	v_mul_f32_e32 v0, 0xbfb8aa3b, v0
	v_exp_f32_e32 v0, v0
	s_nop 0
	v_min_f32_e32 v169, 0x7149f2ca, v0
	v_and_b32_e32 v0, 0xffff0000, v226
	v_mul_f32_e32 v0, 0xbfb8aa3b, v0
	v_exp_f32_e32 v0, v0
	v_add_f32_e32 v168, 1.0, v168
	v_add_f32_e32 v169, 1.0, v169
	v_min_f32_e32 v0, 0x7149f2ca, v0
	v_add_f32_e32 v0, 1.0, v0
	v_rcp_f32_e32 v171, v0
	v_lshlrev_b32_e32 v0, 16, v229
	v_mul_f32_e32 v0, 0xbfb8aa3b, v0
	v_exp_f32_e32 v0, v0
	v_mul_f32_e32 v168, v168, v170
	v_mul_f32_e32 v169, v169, v171
	v_min_f32_e32 v146, 0x7149f2ca, v0
	v_lshlrev_b32_e32 v0, 16, v227
	v_mul_f32_e32 v0, 0xbfb8aa3b, v0
	v_exp_f32_e32 v0, v0
	v_mul_f32_e32 v120, v120, v168
	v_mul_f32_e32 v121, v121, v169
	v_min_f32_e32 v0, 0x7149f2ca, v0
	v_add_f32_e32 v0, 1.0, v0
	v_rcp_f32_e32 v166, v0
	v_and_b32_e32 v0, 0xffff0000, v229
	v_mul_f32_e32 v0, 0xbfb8aa3b, v0
	v_exp_f32_e32 v0, v0
	s_nop 0
	v_min_f32_e32 v147, 0x7149f2ca, v0
	v_and_b32_e32 v0, 0xffff0000, v227
	v_mul_f32_e32 v0, 0xbfb8aa3b, v0
	v_exp_f32_e32 v0, v0
	v_add_f32_e32 v146, 1.0, v146
	v_add_f32_e32 v147, 1.0, v147
	v_min_f32_e32 v0, 0x7149f2ca, v0
	v_add_f32_e32 v0, 1.0, v0
	v_rcp_f32_e32 v167, v0
	s_nop 0
	s_nop 0
	v_mul_f32_e32 v146, v146, v166
	v_mul_f32_e32 v147, v147, v167
	s_nop 0
	v_mul_f32_e32 v122, v122, v146
	v_mul_f32_e32 v123, v123, v147
	s_nop 0
	s_nop 0
	s_waitcnt vmcnt(0)
	v_lshlrev_b32_e32 v0, 16, v232
	v_mul_f32_e32 v0, 0xbfb8aa3b, v0
	v_exp_f32_e32 v0, v0
	s_nop 0
	v_min_f32_e32 v166, 0x7149f2ca, v0
	v_lshlrev_b32_e32 v0, 16, v230
	v_mul_f32_e32 v0, 0xbfb8aa3b, v0
	v_exp_f32_e32 v0, v0
	s_nop 0
	v_min_f32_e32 v0, 0x7149f2ca, v0
	v_add_f32_e32 v0, 1.0, v0
	v_rcp_f32_e32 v168, v0
	v_and_b32_e32 v0, 0xffff0000, v232
	v_mul_f32_e32 v0, 0xbfb8aa3b, v0
	v_exp_f32_e32 v0, v0
	s_nop 0
	v_min_f32_e32 v167, 0x7149f2ca, v0
	v_and_b32_e32 v0, 0xffff0000, v230
	v_mul_f32_e32 v0, 0xbfb8aa3b, v0
	v_exp_f32_e32 v0, v0
	v_add_f32_e32 v166, 1.0, v166
	v_add_f32_e32 v167, 1.0, v167
	v_min_f32_e32 v0, 0x7149f2ca, v0
	v_add_f32_e32 v0, 1.0, v0
	v_rcp_f32_e32 v169, v0
	v_lshlrev_b32_e32 v0, 16, v233
	v_mul_f32_e32 v0, 0xbfb8aa3b, v0
	v_exp_f32_e32 v0, v0
	v_mul_f32_e32 v166, v166, v168
	v_mul_f32_e32 v167, v167, v169
	v_min_f32_e32 v2, 0x7149f2ca, v0
	v_lshlrev_b32_e32 v0, 16, v231
	v_mul_f32_e32 v0, 0xbfb8aa3b, v0
	v_exp_f32_e32 v0, v0
	v_mul_f32_e32 v116, v116, v166
	v_mul_f32_e32 v117, v117, v167
	v_min_f32_e32 v0, 0x7149f2ca, v0
	v_add_f32_e32 v0, 1.0, v0
	v_rcp_f32_e32 v146, v0
	v_and_b32_e32 v0, 0xffff0000, v233
	v_mul_f32_e32 v0, 0xbfb8aa3b, v0
	v_exp_f32_e32 v0, v0
	s_nop 0
	v_min_f32_e32 v3, 0x7149f2ca, v0
	v_and_b32_e32 v0, 0xffff0000, v231
	v_mul_f32_e32 v0, 0xbfb8aa3b, v0
	v_exp_f32_e32 v0, v0
	v_add_f32_e32 v2, 1.0, v2
	v_add_f32_e32 v3, 1.0, v3
	v_min_f32_e32 v0, 0x7149f2ca, v0
	v_add_f32_e32 v0, 1.0, v0
	v_rcp_f32_e32 v147, v0
	v_mov_b32_e32 v0, v152
	v_mul_f32_e32 v2, v2, v146
	v_mul_f32_e32 v3, v3, v147
	s_nop 0
	v_mul_f32_e32 v118, v118, v2
	v_mul_f32_e32 v119, v119, v3
	s_nop 0
	s_nop 0
	v_mad_u64_u32 v[2:3], s[28:29], v0, s30, v[136:137]
	v_mov_b32_e32 v215, 0
	v_add_u32_e32 v214, s13, v2
	v_lshlrev_b64 v[216:217], 1, v[214:215]
	v_lshl_add_u64 v[218:219], s[4:5], 0, v[216:217]
	v_lshl_add_u64 v[220:221], s[8:9], 0, v[216:217]
	global_load_dwordx2 v[218:219], v[218:219], off
	global_load_dwordx2 v[220:221], v[220:221], off
	v_add_u32_e32 v214, s56, v2
	v_lshlrev_b64 v[216:217], 1, v[214:215]
	v_lshl_add_u64 v[222:223], s[4:5], 0, v[216:217]
	v_lshl_add_u64 v[224:225], s[8:9], 0, v[216:217]
	global_load_dwordx2 v[222:223], v[222:223], off
	global_load_dwordx2 v[224:225], v[224:225], off
	v_add_u32_e32 v214, s57, v2
	v_lshlrev_b64 v[216:217], 1, v[214:215]
	v_lshl_add_u64 v[226:227], s[4:5], 0, v[216:217]
	v_lshl_add_u64 v[228:229], s[8:9], 0, v[216:217]
	global_load_dwordx2 v[226:227], v[226:227], off
	global_load_dwordx2 v[228:229], v[228:229], off
	v_add_u32_e32 v214, s58, v2
	v_lshlrev_b64 v[216:217], 1, v[214:215]
	v_lshl_add_u64 v[230:231], s[4:5], 0, v[216:217]
	v_lshl_add_u64 v[232:233], s[8:9], 0, v[216:217]
	global_load_dwordx2 v[230:231], v[230:231], off
	global_load_dwordx2 v[232:233], v[232:233], off
	s_nop 0
	s_nop 0
	s_nop 0
	s_nop 0
	s_waitcnt vmcnt(6)
	v_lshlrev_b32_e32 v0, 16, v220
	v_mul_f32_e32 v0, 0xbfb8aa3b, v0
	v_exp_f32_e32 v0, v0
	s_nop 0
	v_min_f32_e32 v168, 0x7149f2ca, v0
	v_lshlrev_b32_e32 v0, 16, v218
	v_mul_f32_e32 v0, 0xbfb8aa3b, v0
	v_exp_f32_e32 v0, v0
	s_nop 0
	v_min_f32_e32 v0, 0x7149f2ca, v0
	v_add_f32_e32 v0, 1.0, v0
	v_rcp_f32_e32 v170, v0
	v_and_b32_e32 v0, 0xffff0000, v220
	v_mul_f32_e32 v0, 0xbfb8aa3b, v0
	v_exp_f32_e32 v0, v0
	s_nop 0
	v_min_f32_e32 v169, 0x7149f2ca, v0
	v_and_b32_e32 v0, 0xffff0000, v218
	v_mul_f32_e32 v0, 0xbfb8aa3b, v0
	v_exp_f32_e32 v0, v0
	v_add_f32_e32 v168, 1.0, v168
	v_add_f32_e32 v169, 1.0, v169
	v_min_f32_e32 v0, 0x7149f2ca, v0
	v_add_f32_e32 v0, 1.0, v0
	v_rcp_f32_e32 v171, v0
	v_lshlrev_b32_e32 v0, 16, v221
	v_mul_f32_e32 v0, 0xbfb8aa3b, v0
	v_exp_f32_e32 v0, v0
	v_mul_f32_e32 v168, v168, v170
	v_mul_f32_e32 v169, v169, v171
	v_min_f32_e32 v146, 0x7149f2ca, v0
	v_lshlrev_b32_e32 v0, 16, v219
	v_mul_f32_e32 v0, 0xbfb8aa3b, v0
	v_exp_f32_e32 v0, v0
	v_mul_f32_e32 v112, v112, v168
	v_mul_f32_e32 v113, v113, v169
	v_min_f32_e32 v0, 0x7149f2ca, v0
	v_add_f32_e32 v0, 1.0, v0
	v_rcp_f32_e32 v166, v0
	v_and_b32_e32 v0, 0xffff0000, v221
	v_mul_f32_e32 v0, 0xbfb8aa3b, v0
	v_exp_f32_e32 v0, v0
	s_nop 0
	v_min_f32_e32 v147, 0x7149f2ca, v0
	v_and_b32_e32 v0, 0xffff0000, v219
	v_mul_f32_e32 v0, 0xbfb8aa3b, v0
	v_exp_f32_e32 v0, v0
	v_add_f32_e32 v146, 1.0, v146
	v_add_f32_e32 v147, 1.0, v147
	v_min_f32_e32 v0, 0x7149f2ca, v0
	v_add_f32_e32 v0, 1.0, v0
	v_rcp_f32_e32 v167, v0
	s_nop 0
	v_mul_f32_e32 v146, v146, v166
	v_mul_f32_e32 v147, v147, v167
	s_nop 0
	v_mul_f32_e32 v114, v114, v146
	v_mul_f32_e32 v115, v115, v147
	s_nop 0
	s_nop 0
	s_nop 0
	s_waitcnt vmcnt(4)
	v_lshlrev_b32_e32 v0, 16, v224
	v_mul_f32_e32 v0, 0xbfb8aa3b, v0
	v_exp_f32_e32 v0, v0
	s_nop 0
	v_min_f32_e32 v168, 0x7149f2ca, v0
	v_lshlrev_b32_e32 v0, 16, v222
	v_mul_f32_e32 v0, 0xbfb8aa3b, v0
	v_exp_f32_e32 v0, v0
	s_nop 0
	v_min_f32_e32 v0, 0x7149f2ca, v0
	v_add_f32_e32 v0, 1.0, v0
	v_rcp_f32_e32 v170, v0
	v_and_b32_e32 v0, 0xffff0000, v224
	v_mul_f32_e32 v0, 0xbfb8aa3b, v0
	v_exp_f32_e32 v0, v0
	s_nop 0
	v_min_f32_e32 v169, 0x7149f2ca, v0
	v_and_b32_e32 v0, 0xffff0000, v222
	v_mul_f32_e32 v0, 0xbfb8aa3b, v0
	v_exp_f32_e32 v0, v0
	v_add_f32_e32 v168, 1.0, v168
	v_add_f32_e32 v169, 1.0, v169
	v_min_f32_e32 v0, 0x7149f2ca, v0
	v_add_f32_e32 v0, 1.0, v0
	v_rcp_f32_e32 v171, v0
	v_lshlrev_b32_e32 v0, 16, v225
	v_mul_f32_e32 v0, 0xbfb8aa3b, v0
	v_exp_f32_e32 v0, v0
	v_mul_f32_e32 v168, v168, v170
	v_mul_f32_e32 v169, v169, v171
	v_min_f32_e32 v146, 0x7149f2ca, v0
	v_lshlrev_b32_e32 v0, 16, v223
	v_mul_f32_e32 v0, 0xbfb8aa3b, v0
	v_exp_f32_e32 v0, v0
	v_mul_f32_e32 v108, v108, v168
	v_mul_f32_e32 v109, v109, v169
	v_min_f32_e32 v0, 0x7149f2ca, v0
	v_add_f32_e32 v0, 1.0, v0
	v_rcp_f32_e32 v166, v0
	v_and_b32_e32 v0, 0xffff0000, v225
	v_mul_f32_e32 v0, 0xbfb8aa3b, v0
	v_exp_f32_e32 v0, v0
	s_nop 0
	v_min_f32_e32 v147, 0x7149f2ca, v0
	v_and_b32_e32 v0, 0xffff0000, v223
	v_mul_f32_e32 v0, 0xbfb8aa3b, v0
	v_exp_f32_e32 v0, v0
	v_add_f32_e32 v146, 1.0, v146
	v_add_f32_e32 v147, 1.0, v147
	v_min_f32_e32 v0, 0x7149f2ca, v0
	v_add_f32_e32 v0, 1.0, v0
	v_rcp_f32_e32 v167, v0
	s_nop 0
	v_mul_f32_e32 v146, v146, v166
	v_mul_f32_e32 v147, v147, v167
	s_nop 0
	v_mul_f32_e32 v110, v110, v146
	v_mul_f32_e32 v111, v111, v147
	s_nop 0
	s_nop 0
	s_nop 0
	s_waitcnt vmcnt(2)
	v_lshlrev_b32_e32 v0, 16, v228
	v_mul_f32_e32 v0, 0xbfb8aa3b, v0
	v_exp_f32_e32 v0, v0
	s_nop 0
	v_min_f32_e32 v168, 0x7149f2ca, v0
	v_lshlrev_b32_e32 v0, 16, v226
	v_mul_f32_e32 v0, 0xbfb8aa3b, v0
	v_exp_f32_e32 v0, v0
	s_nop 0
	v_min_f32_e32 v0, 0x7149f2ca, v0
	v_add_f32_e32 v0, 1.0, v0
	v_rcp_f32_e32 v170, v0
	v_and_b32_e32 v0, 0xffff0000, v228
	v_mul_f32_e32 v0, 0xbfb8aa3b, v0
	v_exp_f32_e32 v0, v0
	s_nop 0
	v_min_f32_e32 v169, 0x7149f2ca, v0
	v_and_b32_e32 v0, 0xffff0000, v226
	v_mul_f32_e32 v0, 0xbfb8aa3b, v0
	v_exp_f32_e32 v0, v0
	v_add_f32_e32 v168, 1.0, v168
	v_add_f32_e32 v169, 1.0, v169
	v_min_f32_e32 v0, 0x7149f2ca, v0
	v_add_f32_e32 v0, 1.0, v0
	v_rcp_f32_e32 v171, v0
	v_lshlrev_b32_e32 v0, 16, v229
	v_mul_f32_e32 v0, 0xbfb8aa3b, v0
	v_exp_f32_e32 v0, v0
	v_mul_f32_e32 v168, v168, v170
	v_mul_f32_e32 v169, v169, v171
	v_min_f32_e32 v146, 0x7149f2ca, v0
	v_lshlrev_b32_e32 v0, 16, v227
	v_mul_f32_e32 v0, 0xbfb8aa3b, v0
	v_exp_f32_e32 v0, v0
	v_mul_f32_e32 v104, v104, v168
	v_mul_f32_e32 v105, v105, v169
	v_min_f32_e32 v0, 0x7149f2ca, v0
	v_add_f32_e32 v0, 1.0, v0
	v_rcp_f32_e32 v166, v0
	v_and_b32_e32 v0, 0xffff0000, v229
	v_mul_f32_e32 v0, 0xbfb8aa3b, v0
	v_exp_f32_e32 v0, v0
	s_nop 0
	v_min_f32_e32 v147, 0x7149f2ca, v0
	v_and_b32_e32 v0, 0xffff0000, v227
	v_mul_f32_e32 v0, 0xbfb8aa3b, v0
	v_exp_f32_e32 v0, v0
	v_add_f32_e32 v146, 1.0, v146
	v_add_f32_e32 v147, 1.0, v147
	v_min_f32_e32 v0, 0x7149f2ca, v0
	v_add_f32_e32 v0, 1.0, v0
	v_rcp_f32_e32 v167, v0
	s_nop 0
	s_nop 0
	v_mul_f32_e32 v146, v146, v166
	v_mul_f32_e32 v147, v147, v167
	s_nop 0
	v_mul_f32_e32 v106, v106, v146
	v_mul_f32_e32 v107, v107, v147
	s_nop 0
	s_nop 0
	s_waitcnt vmcnt(0)
	v_lshlrev_b32_e32 v0, 16, v232
	v_mul_f32_e32 v0, 0xbfb8aa3b, v0
	v_exp_f32_e32 v0, v0
	s_nop 0
	v_min_f32_e32 v166, 0x7149f2ca, v0
	v_lshlrev_b32_e32 v0, 16, v230
	v_mul_f32_e32 v0, 0xbfb8aa3b, v0
	v_exp_f32_e32 v0, v0
	s_nop 0
	v_min_f32_e32 v0, 0x7149f2ca, v0
	v_add_f32_e32 v0, 1.0, v0
	v_rcp_f32_e32 v168, v0
	v_and_b32_e32 v0, 0xffff0000, v232
	v_mul_f32_e32 v0, 0xbfb8aa3b, v0
	v_exp_f32_e32 v0, v0
	s_nop 0
	v_min_f32_e32 v167, 0x7149f2ca, v0
	v_and_b32_e32 v0, 0xffff0000, v230
	v_mul_f32_e32 v0, 0xbfb8aa3b, v0
	v_exp_f32_e32 v0, v0
	v_add_f32_e32 v166, 1.0, v166
	v_add_f32_e32 v167, 1.0, v167
	v_min_f32_e32 v0, 0x7149f2ca, v0
	v_add_f32_e32 v0, 1.0, v0
	v_rcp_f32_e32 v169, v0
	v_lshlrev_b32_e32 v0, 16, v233
	v_mul_f32_e32 v0, 0xbfb8aa3b, v0
	v_exp_f32_e32 v0, v0
	v_mul_f32_e32 v166, v166, v168
	v_mul_f32_e32 v167, v167, v169
	v_min_f32_e32 v2, 0x7149f2ca, v0
	v_lshlrev_b32_e32 v0, 16, v231
	v_mul_f32_e32 v0, 0xbfb8aa3b, v0
	v_exp_f32_e32 v0, v0
	v_mul_f32_e32 v100, v100, v166
	v_mul_f32_e32 v101, v101, v167
	v_min_f32_e32 v0, 0x7149f2ca, v0
	v_add_f32_e32 v0, 1.0, v0
	v_rcp_f32_e32 v146, v0
	v_and_b32_e32 v0, 0xffff0000, v233
	v_mul_f32_e32 v0, 0xbfb8aa3b, v0
	v_exp_f32_e32 v0, v0
	s_nop 0
	v_min_f32_e32 v3, 0x7149f2ca, v0
	v_and_b32_e32 v0, 0xffff0000, v231
	v_mul_f32_e32 v0, 0xbfb8aa3b, v0
	v_exp_f32_e32 v0, v0
	v_add_f32_e32 v2, 1.0, v2
	v_add_f32_e32 v3, 1.0, v3
	v_min_f32_e32 v0, 0x7149f2ca, v0
	v_add_f32_e32 v0, 1.0, v0
	v_rcp_f32_e32 v147, v0
	v_mov_b32_e32 v0, v153
	v_mul_f32_e32 v2, v2, v146
	v_mul_f32_e32 v3, v3, v147
	s_nop 0
	v_mul_f32_e32 v102, v102, v2
	v_mul_f32_e32 v103, v103, v3
	s_nop 0
	s_nop 0
	v_mad_u64_u32 v[2:3], s[28:29], v0, s30, v[136:137]
	v_mov_b32_e32 v215, 0
	v_add_u32_e32 v214, s13, v2
	v_lshlrev_b64 v[216:217], 1, v[214:215]
	v_lshl_add_u64 v[218:219], s[4:5], 0, v[216:217]
	v_lshl_add_u64 v[220:221], s[8:9], 0, v[216:217]
	global_load_dwordx2 v[218:219], v[218:219], off
	global_load_dwordx2 v[220:221], v[220:221], off
	v_add_u32_e32 v214, s56, v2
	v_lshlrev_b64 v[216:217], 1, v[214:215]
	v_lshl_add_u64 v[222:223], s[4:5], 0, v[216:217]
	v_lshl_add_u64 v[224:225], s[8:9], 0, v[216:217]
	global_load_dwordx2 v[222:223], v[222:223], off
	global_load_dwordx2 v[224:225], v[224:225], off
	v_add_u32_e32 v214, s57, v2
	v_lshlrev_b64 v[216:217], 1, v[214:215]
	v_lshl_add_u64 v[226:227], s[4:5], 0, v[216:217]
	v_lshl_add_u64 v[228:229], s[8:9], 0, v[216:217]
	global_load_dwordx2 v[226:227], v[226:227], off
	global_load_dwordx2 v[228:229], v[228:229], off
	v_add_u32_e32 v214, s58, v2
	v_lshlrev_b64 v[216:217], 1, v[214:215]
	v_lshl_add_u64 v[230:231], s[4:5], 0, v[216:217]
	v_lshl_add_u64 v[232:233], s[8:9], 0, v[216:217]
	global_load_dwordx2 v[230:231], v[230:231], off
	global_load_dwordx2 v[232:233], v[232:233], off
	s_nop 0
	s_nop 0
	s_nop 0
	s_nop 0
	s_waitcnt vmcnt(6)
	v_lshlrev_b32_e32 v0, 16, v220
	v_mul_f32_e32 v0, 0xbfb8aa3b, v0
	v_exp_f32_e32 v0, v0
	s_nop 0
	v_min_f32_e32 v168, 0x7149f2ca, v0
	v_lshlrev_b32_e32 v0, 16, v218
	v_mul_f32_e32 v0, 0xbfb8aa3b, v0
	v_exp_f32_e32 v0, v0
	s_nop 0
	v_min_f32_e32 v0, 0x7149f2ca, v0
	v_add_f32_e32 v0, 1.0, v0
	v_rcp_f32_e32 v170, v0
	v_and_b32_e32 v0, 0xffff0000, v220
	v_mul_f32_e32 v0, 0xbfb8aa3b, v0
	v_exp_f32_e32 v0, v0
	s_nop 0
	v_min_f32_e32 v169, 0x7149f2ca, v0
	v_and_b32_e32 v0, 0xffff0000, v218
	v_mul_f32_e32 v0, 0xbfb8aa3b, v0
	v_exp_f32_e32 v0, v0
	v_add_f32_e32 v168, 1.0, v168
	v_add_f32_e32 v169, 1.0, v169
	v_min_f32_e32 v0, 0x7149f2ca, v0
	v_add_f32_e32 v0, 1.0, v0
	v_rcp_f32_e32 v171, v0
	v_lshlrev_b32_e32 v0, 16, v221
	v_mul_f32_e32 v0, 0xbfb8aa3b, v0
	v_exp_f32_e32 v0, v0
	v_mul_f32_e32 v168, v168, v170
	v_mul_f32_e32 v169, v169, v171
	v_min_f32_e32 v146, 0x7149f2ca, v0
	v_lshlrev_b32_e32 v0, 16, v219
	v_mul_f32_e32 v0, 0xbfb8aa3b, v0
	v_exp_f32_e32 v0, v0
	v_mul_f32_e32 v96, v96, v168
	v_mul_f32_e32 v97, v97, v169
	v_min_f32_e32 v0, 0x7149f2ca, v0
	v_add_f32_e32 v0, 1.0, v0
	v_rcp_f32_e32 v166, v0
	v_and_b32_e32 v0, 0xffff0000, v221
	v_mul_f32_e32 v0, 0xbfb8aa3b, v0
	v_exp_f32_e32 v0, v0
	s_nop 0
	v_min_f32_e32 v147, 0x7149f2ca, v0
	v_and_b32_e32 v0, 0xffff0000, v219
	v_mul_f32_e32 v0, 0xbfb8aa3b, v0
	v_exp_f32_e32 v0, v0
	v_add_f32_e32 v146, 1.0, v146
	v_add_f32_e32 v147, 1.0, v147
	v_min_f32_e32 v0, 0x7149f2ca, v0
	v_add_f32_e32 v0, 1.0, v0
	v_rcp_f32_e32 v167, v0
	s_nop 0
	v_mul_f32_e32 v146, v146, v166
	v_mul_f32_e32 v147, v147, v167
	s_nop 0
	v_mul_f32_e32 v98, v98, v146
	v_mul_f32_e32 v99, v99, v147
	s_nop 0
	s_nop 0
	s_nop 0
	s_waitcnt vmcnt(4)
	v_lshlrev_b32_e32 v0, 16, v224
	v_mul_f32_e32 v0, 0xbfb8aa3b, v0
	v_exp_f32_e32 v0, v0
	s_nop 0
	v_min_f32_e32 v168, 0x7149f2ca, v0
	v_lshlrev_b32_e32 v0, 16, v222
	v_mul_f32_e32 v0, 0xbfb8aa3b, v0
	v_exp_f32_e32 v0, v0
	s_nop 0
	v_min_f32_e32 v0, 0x7149f2ca, v0
	v_add_f32_e32 v0, 1.0, v0
	v_rcp_f32_e32 v170, v0
	v_and_b32_e32 v0, 0xffff0000, v224
	v_mul_f32_e32 v0, 0xbfb8aa3b, v0
	v_exp_f32_e32 v0, v0
	s_nop 0
	v_min_f32_e32 v169, 0x7149f2ca, v0
	v_and_b32_e32 v0, 0xffff0000, v222
	v_mul_f32_e32 v0, 0xbfb8aa3b, v0
	v_exp_f32_e32 v0, v0
	v_add_f32_e32 v168, 1.0, v168
	v_add_f32_e32 v169, 1.0, v169
	v_min_f32_e32 v0, 0x7149f2ca, v0
	v_add_f32_e32 v0, 1.0, v0
	v_rcp_f32_e32 v171, v0
	v_lshlrev_b32_e32 v0, 16, v225
	v_mul_f32_e32 v0, 0xbfb8aa3b, v0
	v_exp_f32_e32 v0, v0
	v_mul_f32_e32 v168, v168, v170
	v_mul_f32_e32 v169, v169, v171
	v_min_f32_e32 v146, 0x7149f2ca, v0
	v_lshlrev_b32_e32 v0, 16, v223
	v_mul_f32_e32 v0, 0xbfb8aa3b, v0
	v_exp_f32_e32 v0, v0
	v_mul_f32_e32 v92, v92, v168
	v_mul_f32_e32 v93, v93, v169
	v_min_f32_e32 v0, 0x7149f2ca, v0
	v_add_f32_e32 v0, 1.0, v0
	v_rcp_f32_e32 v166, v0
	v_and_b32_e32 v0, 0xffff0000, v225
	v_mul_f32_e32 v0, 0xbfb8aa3b, v0
	v_exp_f32_e32 v0, v0
	s_nop 0
	v_min_f32_e32 v147, 0x7149f2ca, v0
	v_and_b32_e32 v0, 0xffff0000, v223
	v_mul_f32_e32 v0, 0xbfb8aa3b, v0
	v_exp_f32_e32 v0, v0
	v_add_f32_e32 v146, 1.0, v146
	v_add_f32_e32 v147, 1.0, v147
	v_min_f32_e32 v0, 0x7149f2ca, v0
	v_add_f32_e32 v0, 1.0, v0
	v_rcp_f32_e32 v167, v0
	s_nop 0
	v_mul_f32_e32 v146, v146, v166
	v_mul_f32_e32 v147, v147, v167
	s_nop 0
	v_mul_f32_e32 v94, v94, v146
	v_mul_f32_e32 v95, v95, v147
	s_nop 0
	s_nop 0
	s_nop 0
	s_waitcnt vmcnt(2)
	v_lshlrev_b32_e32 v0, 16, v228
	v_mul_f32_e32 v0, 0xbfb8aa3b, v0
	v_exp_f32_e32 v0, v0
	s_nop 0
	v_min_f32_e32 v168, 0x7149f2ca, v0
	v_lshlrev_b32_e32 v0, 16, v226
	v_mul_f32_e32 v0, 0xbfb8aa3b, v0
	v_exp_f32_e32 v0, v0
	s_nop 0
	v_min_f32_e32 v0, 0x7149f2ca, v0
	v_add_f32_e32 v0, 1.0, v0
	v_rcp_f32_e32 v170, v0
	v_and_b32_e32 v0, 0xffff0000, v228
	v_mul_f32_e32 v0, 0xbfb8aa3b, v0
	v_exp_f32_e32 v0, v0
	s_nop 0
	v_min_f32_e32 v169, 0x7149f2ca, v0
	v_and_b32_e32 v0, 0xffff0000, v226
	v_mul_f32_e32 v0, 0xbfb8aa3b, v0
	v_exp_f32_e32 v0, v0
	v_add_f32_e32 v168, 1.0, v168
	v_add_f32_e32 v169, 1.0, v169
	v_min_f32_e32 v0, 0x7149f2ca, v0
	v_add_f32_e32 v0, 1.0, v0
	v_rcp_f32_e32 v171, v0
	v_lshlrev_b32_e32 v0, 16, v229
	v_mul_f32_e32 v0, 0xbfb8aa3b, v0
	v_exp_f32_e32 v0, v0
	v_mul_f32_e32 v168, v168, v170
	v_mul_f32_e32 v169, v169, v171
	v_min_f32_e32 v146, 0x7149f2ca, v0
	v_lshlrev_b32_e32 v0, 16, v227
	v_mul_f32_e32 v0, 0xbfb8aa3b, v0
	v_exp_f32_e32 v0, v0
	v_mul_f32_e32 v88, v88, v168
	v_mul_f32_e32 v89, v89, v169
	v_min_f32_e32 v0, 0x7149f2ca, v0
	v_add_f32_e32 v0, 1.0, v0
	v_rcp_f32_e32 v166, v0
	v_and_b32_e32 v0, 0xffff0000, v229
	v_mul_f32_e32 v0, 0xbfb8aa3b, v0
	v_exp_f32_e32 v0, v0
	s_nop 0
	v_min_f32_e32 v147, 0x7149f2ca, v0
	v_and_b32_e32 v0, 0xffff0000, v227
	v_mul_f32_e32 v0, 0xbfb8aa3b, v0
	v_exp_f32_e32 v0, v0
	v_add_f32_e32 v146, 1.0, v146
	v_add_f32_e32 v147, 1.0, v147
	v_min_f32_e32 v0, 0x7149f2ca, v0
	v_add_f32_e32 v0, 1.0, v0
	v_rcp_f32_e32 v167, v0
	s_nop 0
	s_nop 0
	v_mul_f32_e32 v146, v146, v166
	v_mul_f32_e32 v147, v147, v167
	s_nop 0
	v_mul_f32_e32 v90, v90, v146
	v_mul_f32_e32 v91, v91, v147
	s_nop 0
	s_nop 0
	s_waitcnt vmcnt(0)
	v_lshlrev_b32_e32 v0, 16, v232
	v_mul_f32_e32 v0, 0xbfb8aa3b, v0
	v_exp_f32_e32 v0, v0
	s_nop 0
	v_min_f32_e32 v166, 0x7149f2ca, v0
	v_lshlrev_b32_e32 v0, 16, v230
	v_mul_f32_e32 v0, 0xbfb8aa3b, v0
	v_exp_f32_e32 v0, v0
	s_nop 0
	v_min_f32_e32 v0, 0x7149f2ca, v0
	v_add_f32_e32 v0, 1.0, v0
	v_rcp_f32_e32 v168, v0
	v_and_b32_e32 v0, 0xffff0000, v232
	v_mul_f32_e32 v0, 0xbfb8aa3b, v0
	v_exp_f32_e32 v0, v0
	s_nop 0
	v_min_f32_e32 v167, 0x7149f2ca, v0
	v_and_b32_e32 v0, 0xffff0000, v230
	v_mul_f32_e32 v0, 0xbfb8aa3b, v0
	v_exp_f32_e32 v0, v0
	v_add_f32_e32 v166, 1.0, v166
	v_add_f32_e32 v167, 1.0, v167
	v_min_f32_e32 v0, 0x7149f2ca, v0
	v_add_f32_e32 v0, 1.0, v0
	v_rcp_f32_e32 v169, v0
	v_lshlrev_b32_e32 v0, 16, v233
	v_mul_f32_e32 v0, 0xbfb8aa3b, v0
	v_exp_f32_e32 v0, v0
	v_mul_f32_e32 v166, v166, v168
	v_mul_f32_e32 v167, v167, v169
	v_min_f32_e32 v2, 0x7149f2ca, v0
	v_lshlrev_b32_e32 v0, 16, v231
	v_mul_f32_e32 v0, 0xbfb8aa3b, v0
	v_exp_f32_e32 v0, v0
	v_mul_f32_e32 v84, v84, v166
	v_mul_f32_e32 v85, v85, v167
	v_min_f32_e32 v0, 0x7149f2ca, v0
	v_add_f32_e32 v0, 1.0, v0
	v_rcp_f32_e32 v146, v0
	v_and_b32_e32 v0, 0xffff0000, v233
	v_mul_f32_e32 v0, 0xbfb8aa3b, v0
	v_exp_f32_e32 v0, v0
	s_nop 0
	v_min_f32_e32 v3, 0x7149f2ca, v0
	v_and_b32_e32 v0, 0xffff0000, v231
	v_mul_f32_e32 v0, 0xbfb8aa3b, v0
	v_exp_f32_e32 v0, v0
	v_add_f32_e32 v2, 1.0, v2
	v_add_f32_e32 v3, 1.0, v3
	v_min_f32_e32 v0, 0x7149f2ca, v0
	v_add_f32_e32 v0, 1.0, v0
	v_rcp_f32_e32 v147, v0
	v_mov_b32_e32 v0, v154
	v_mul_f32_e32 v2, v2, v146
	v_mul_f32_e32 v3, v3, v147
	s_nop 0
	v_mul_f32_e32 v86, v86, v2
	v_mul_f32_e32 v87, v87, v3
	s_nop 0
	s_nop 0
	v_mad_u64_u32 v[2:3], s[28:29], v0, s30, v[136:137]
	v_mov_b32_e32 v215, 0
	v_add_u32_e32 v214, s13, v2
	v_lshlrev_b64 v[216:217], 1, v[214:215]
	v_lshl_add_u64 v[218:219], s[4:5], 0, v[216:217]
	v_lshl_add_u64 v[220:221], s[8:9], 0, v[216:217]
	global_load_dwordx2 v[218:219], v[218:219], off
	global_load_dwordx2 v[220:221], v[220:221], off
	v_add_u32_e32 v214, s56, v2
	v_lshlrev_b64 v[216:217], 1, v[214:215]
	v_lshl_add_u64 v[222:223], s[4:5], 0, v[216:217]
	v_lshl_add_u64 v[224:225], s[8:9], 0, v[216:217]
	global_load_dwordx2 v[222:223], v[222:223], off
	global_load_dwordx2 v[224:225], v[224:225], off
	v_add_u32_e32 v214, s57, v2
	v_lshlrev_b64 v[216:217], 1, v[214:215]
	v_lshl_add_u64 v[226:227], s[4:5], 0, v[216:217]
	v_lshl_add_u64 v[228:229], s[8:9], 0, v[216:217]
	global_load_dwordx2 v[226:227], v[226:227], off
	global_load_dwordx2 v[228:229], v[228:229], off
	v_add_u32_e32 v214, s58, v2
	v_lshlrev_b64 v[216:217], 1, v[214:215]
	v_lshl_add_u64 v[230:231], s[4:5], 0, v[216:217]
	v_lshl_add_u64 v[232:233], s[8:9], 0, v[216:217]
	global_load_dwordx2 v[230:231], v[230:231], off
	global_load_dwordx2 v[232:233], v[232:233], off
	s_nop 0
	s_nop 0
	s_nop 0
	s_nop 0
	s_waitcnt vmcnt(6)
	v_lshlrev_b32_e32 v0, 16, v220
	v_mul_f32_e32 v0, 0xbfb8aa3b, v0
	v_exp_f32_e32 v0, v0
	s_nop 0
	v_min_f32_e32 v168, 0x7149f2ca, v0
	v_lshlrev_b32_e32 v0, 16, v218
	v_mul_f32_e32 v0, 0xbfb8aa3b, v0
	v_exp_f32_e32 v0, v0
	s_nop 0
	v_min_f32_e32 v0, 0x7149f2ca, v0
	v_add_f32_e32 v0, 1.0, v0
	v_rcp_f32_e32 v170, v0
	v_and_b32_e32 v0, 0xffff0000, v220
	v_mul_f32_e32 v0, 0xbfb8aa3b, v0
	v_exp_f32_e32 v0, v0
	s_nop 0
	v_min_f32_e32 v169, 0x7149f2ca, v0
	v_and_b32_e32 v0, 0xffff0000, v218
	v_mul_f32_e32 v0, 0xbfb8aa3b, v0
	v_exp_f32_e32 v0, v0
	v_add_f32_e32 v168, 1.0, v168
	v_add_f32_e32 v169, 1.0, v169
	v_min_f32_e32 v0, 0x7149f2ca, v0
	v_add_f32_e32 v0, 1.0, v0
	v_rcp_f32_e32 v171, v0
	v_lshlrev_b32_e32 v0, 16, v221
	v_mul_f32_e32 v0, 0xbfb8aa3b, v0
	v_exp_f32_e32 v0, v0
	v_mul_f32_e32 v168, v168, v170
	v_mul_f32_e32 v169, v169, v171
	v_min_f32_e32 v146, 0x7149f2ca, v0
	v_lshlrev_b32_e32 v0, 16, v219
	v_mul_f32_e32 v0, 0xbfb8aa3b, v0
	v_exp_f32_e32 v0, v0
	v_mul_f32_e32 v80, v80, v168
	v_mul_f32_e32 v81, v81, v169
	v_min_f32_e32 v0, 0x7149f2ca, v0
	v_add_f32_e32 v0, 1.0, v0
	v_rcp_f32_e32 v166, v0
	v_and_b32_e32 v0, 0xffff0000, v221
	v_mul_f32_e32 v0, 0xbfb8aa3b, v0
	v_exp_f32_e32 v0, v0
	s_nop 0
	v_min_f32_e32 v147, 0x7149f2ca, v0
	v_and_b32_e32 v0, 0xffff0000, v219
	v_mul_f32_e32 v0, 0xbfb8aa3b, v0
	v_exp_f32_e32 v0, v0
	v_add_f32_e32 v146, 1.0, v146
	v_add_f32_e32 v147, 1.0, v147
	v_min_f32_e32 v0, 0x7149f2ca, v0
	v_add_f32_e32 v0, 1.0, v0
	v_rcp_f32_e32 v167, v0
	s_nop 0
	v_mul_f32_e32 v146, v146, v166
	v_mul_f32_e32 v147, v147, v167
	s_nop 0
	v_mul_f32_e32 v82, v82, v146
	v_mul_f32_e32 v83, v83, v147
	s_nop 0
	s_nop 0
	s_nop 0
	s_waitcnt vmcnt(4)
	v_lshlrev_b32_e32 v0, 16, v224
	v_mul_f32_e32 v0, 0xbfb8aa3b, v0
	v_exp_f32_e32 v0, v0
	s_nop 0
	v_min_f32_e32 v168, 0x7149f2ca, v0
	v_lshlrev_b32_e32 v0, 16, v222
	v_mul_f32_e32 v0, 0xbfb8aa3b, v0
	v_exp_f32_e32 v0, v0
	s_nop 0
	v_min_f32_e32 v0, 0x7149f2ca, v0
	v_add_f32_e32 v0, 1.0, v0
	v_rcp_f32_e32 v170, v0
	v_and_b32_e32 v0, 0xffff0000, v224
	v_mul_f32_e32 v0, 0xbfb8aa3b, v0
	v_exp_f32_e32 v0, v0
	s_nop 0
	v_min_f32_e32 v169, 0x7149f2ca, v0
	v_and_b32_e32 v0, 0xffff0000, v222
	v_mul_f32_e32 v0, 0xbfb8aa3b, v0
	v_exp_f32_e32 v0, v0
	v_add_f32_e32 v168, 1.0, v168
	v_add_f32_e32 v169, 1.0, v169
	v_min_f32_e32 v0, 0x7149f2ca, v0
	v_add_f32_e32 v0, 1.0, v0
	v_rcp_f32_e32 v171, v0
	v_lshlrev_b32_e32 v0, 16, v225
	v_mul_f32_e32 v0, 0xbfb8aa3b, v0
	v_exp_f32_e32 v0, v0
	v_mul_f32_e32 v168, v168, v170
	v_mul_f32_e32 v169, v169, v171
	v_min_f32_e32 v146, 0x7149f2ca, v0
	v_lshlrev_b32_e32 v0, 16, v223
	v_mul_f32_e32 v0, 0xbfb8aa3b, v0
	v_exp_f32_e32 v0, v0
	v_mul_f32_e32 v76, v76, v168
	v_mul_f32_e32 v77, v77, v169
	v_min_f32_e32 v0, 0x7149f2ca, v0
	v_add_f32_e32 v0, 1.0, v0
	v_rcp_f32_e32 v166, v0
	v_and_b32_e32 v0, 0xffff0000, v225
	v_mul_f32_e32 v0, 0xbfb8aa3b, v0
	v_exp_f32_e32 v0, v0
	s_nop 0
	v_min_f32_e32 v147, 0x7149f2ca, v0
	v_and_b32_e32 v0, 0xffff0000, v223
	v_mul_f32_e32 v0, 0xbfb8aa3b, v0
	v_exp_f32_e32 v0, v0
	v_add_f32_e32 v146, 1.0, v146
	v_add_f32_e32 v147, 1.0, v147
	v_min_f32_e32 v0, 0x7149f2ca, v0
	v_add_f32_e32 v0, 1.0, v0
	v_rcp_f32_e32 v167, v0
	s_nop 0
	v_mul_f32_e32 v146, v146, v166
	v_mul_f32_e32 v147, v147, v167
	s_nop 0
	v_mul_f32_e32 v78, v78, v146
	v_mul_f32_e32 v79, v79, v147
	s_nop 0
	s_nop 0
	s_nop 0
	s_waitcnt vmcnt(2)
	v_lshlrev_b32_e32 v0, 16, v228
	v_mul_f32_e32 v0, 0xbfb8aa3b, v0
	v_exp_f32_e32 v0, v0
	s_nop 0
	v_min_f32_e32 v168, 0x7149f2ca, v0
	v_lshlrev_b32_e32 v0, 16, v226
	v_mul_f32_e32 v0, 0xbfb8aa3b, v0
	v_exp_f32_e32 v0, v0
	s_nop 0
	v_min_f32_e32 v0, 0x7149f2ca, v0
	v_add_f32_e32 v0, 1.0, v0
	v_rcp_f32_e32 v170, v0
	v_and_b32_e32 v0, 0xffff0000, v228
	v_mul_f32_e32 v0, 0xbfb8aa3b, v0
	v_exp_f32_e32 v0, v0
	s_nop 0
	v_min_f32_e32 v169, 0x7149f2ca, v0
	v_and_b32_e32 v0, 0xffff0000, v226
	v_mul_f32_e32 v0, 0xbfb8aa3b, v0
	v_exp_f32_e32 v0, v0
	v_add_f32_e32 v168, 1.0, v168
	v_add_f32_e32 v169, 1.0, v169
	v_min_f32_e32 v0, 0x7149f2ca, v0
	v_add_f32_e32 v0, 1.0, v0
	v_rcp_f32_e32 v171, v0
	v_lshlrev_b32_e32 v0, 16, v229
	v_mul_f32_e32 v0, 0xbfb8aa3b, v0
	v_exp_f32_e32 v0, v0
	v_mul_f32_e32 v168, v168, v170
	v_mul_f32_e32 v169, v169, v171
	v_min_f32_e32 v146, 0x7149f2ca, v0
	v_lshlrev_b32_e32 v0, 16, v227
	v_mul_f32_e32 v0, 0xbfb8aa3b, v0
	v_exp_f32_e32 v0, v0
	v_mul_f32_e32 v72, v72, v168
	v_mul_f32_e32 v73, v73, v169
	v_min_f32_e32 v0, 0x7149f2ca, v0
	v_add_f32_e32 v0, 1.0, v0
	v_rcp_f32_e32 v166, v0
	v_and_b32_e32 v0, 0xffff0000, v229
	v_mul_f32_e32 v0, 0xbfb8aa3b, v0
	v_exp_f32_e32 v0, v0
	s_nop 0
	v_min_f32_e32 v147, 0x7149f2ca, v0
	v_and_b32_e32 v0, 0xffff0000, v227
	v_mul_f32_e32 v0, 0xbfb8aa3b, v0
	v_exp_f32_e32 v0, v0
	v_add_f32_e32 v146, 1.0, v146
	v_add_f32_e32 v147, 1.0, v147
	v_min_f32_e32 v0, 0x7149f2ca, v0
	v_add_f32_e32 v0, 1.0, v0
	v_rcp_f32_e32 v167, v0
	s_nop 0
	s_nop 0
	v_mul_f32_e32 v146, v146, v166
	v_mul_f32_e32 v147, v147, v167
	s_nop 0
	v_mul_f32_e32 v74, v74, v146
	v_mul_f32_e32 v75, v75, v147
	s_nop 0
	s_nop 0
	s_waitcnt vmcnt(0)
	v_lshlrev_b32_e32 v0, 16, v232
	v_mul_f32_e32 v0, 0xbfb8aa3b, v0
	v_exp_f32_e32 v0, v0
	s_nop 0
	v_min_f32_e32 v166, 0x7149f2ca, v0
	v_lshlrev_b32_e32 v0, 16, v230
	v_mul_f32_e32 v0, 0xbfb8aa3b, v0
	v_exp_f32_e32 v0, v0
	s_nop 0
	v_min_f32_e32 v0, 0x7149f2ca, v0
	v_add_f32_e32 v0, 1.0, v0
	v_rcp_f32_e32 v168, v0
	v_and_b32_e32 v0, 0xffff0000, v232
	v_mul_f32_e32 v0, 0xbfb8aa3b, v0
	v_exp_f32_e32 v0, v0
	s_nop 0
	v_min_f32_e32 v167, 0x7149f2ca, v0
	v_and_b32_e32 v0, 0xffff0000, v230
	v_mul_f32_e32 v0, 0xbfb8aa3b, v0
	v_exp_f32_e32 v0, v0
	v_add_f32_e32 v166, 1.0, v166
	v_add_f32_e32 v167, 1.0, v167
	v_min_f32_e32 v0, 0x7149f2ca, v0
	v_add_f32_e32 v0, 1.0, v0
	v_rcp_f32_e32 v169, v0
	v_lshlrev_b32_e32 v0, 16, v233
	v_mul_f32_e32 v0, 0xbfb8aa3b, v0
	v_exp_f32_e32 v0, v0
	v_mul_f32_e32 v166, v166, v168
	v_mul_f32_e32 v167, v167, v169
	v_min_f32_e32 v2, 0x7149f2ca, v0
	v_lshlrev_b32_e32 v0, 16, v231
	v_mul_f32_e32 v0, 0xbfb8aa3b, v0
	v_exp_f32_e32 v0, v0
	v_mul_f32_e32 v68, v68, v166
	v_mul_f32_e32 v69, v69, v167
	v_min_f32_e32 v0, 0x7149f2ca, v0
	v_add_f32_e32 v0, 1.0, v0
	v_rcp_f32_e32 v146, v0
	v_and_b32_e32 v0, 0xffff0000, v233
	v_mul_f32_e32 v0, 0xbfb8aa3b, v0
	v_exp_f32_e32 v0, v0
	s_nop 0
	v_min_f32_e32 v3, 0x7149f2ca, v0
	v_and_b32_e32 v0, 0xffff0000, v231
	v_mul_f32_e32 v0, 0xbfb8aa3b, v0
	v_exp_f32_e32 v0, v0
	v_add_f32_e32 v2, 1.0, v2
	v_add_f32_e32 v3, 1.0, v3
	v_min_f32_e32 v0, 0x7149f2ca, v0
	v_add_f32_e32 v0, 1.0, v0
	v_rcp_f32_e32 v147, v0
	v_mov_b32_e32 v0, v155
	v_mul_f32_e32 v2, v2, v146
	v_mul_f32_e32 v3, v3, v147
	s_nop 0
	v_mul_f32_e32 v70, v70, v2
	v_mul_f32_e32 v71, v71, v3
	s_nop 0
	s_nop 0
	v_mad_u64_u32 v[2:3], s[28:29], v0, s30, v[136:137]
	v_mov_b32_e32 v215, 0
	v_add_u32_e32 v214, s13, v2
	v_lshlrev_b64 v[216:217], 1, v[214:215]
	v_lshl_add_u64 v[218:219], s[4:5], 0, v[216:217]
	v_lshl_add_u64 v[220:221], s[8:9], 0, v[216:217]
	global_load_dwordx2 v[218:219], v[218:219], off
	global_load_dwordx2 v[220:221], v[220:221], off
	v_add_u32_e32 v214, s56, v2
	v_lshlrev_b64 v[216:217], 1, v[214:215]
	v_lshl_add_u64 v[222:223], s[4:5], 0, v[216:217]
	v_lshl_add_u64 v[224:225], s[8:9], 0, v[216:217]
	global_load_dwordx2 v[222:223], v[222:223], off
	global_load_dwordx2 v[224:225], v[224:225], off
	v_add_u32_e32 v214, s57, v2
	v_lshlrev_b64 v[216:217], 1, v[214:215]
	v_lshl_add_u64 v[226:227], s[4:5], 0, v[216:217]
	v_lshl_add_u64 v[228:229], s[8:9], 0, v[216:217]
	global_load_dwordx2 v[226:227], v[226:227], off
	global_load_dwordx2 v[228:229], v[228:229], off
	v_add_u32_e32 v214, s58, v2
	v_lshlrev_b64 v[216:217], 1, v[214:215]
	v_lshl_add_u64 v[230:231], s[4:5], 0, v[216:217]
	v_lshl_add_u64 v[232:233], s[8:9], 0, v[216:217]
	global_load_dwordx2 v[230:231], v[230:231], off
	global_load_dwordx2 v[232:233], v[232:233], off
	s_nop 0
	s_nop 0
	s_nop 0
	s_nop 0
	s_waitcnt vmcnt(6)
	v_lshlrev_b32_e32 v0, 16, v220
	v_mul_f32_e32 v0, 0xbfb8aa3b, v0
	v_exp_f32_e32 v0, v0
	s_nop 0
	v_min_f32_e32 v168, 0x7149f2ca, v0
	v_lshlrev_b32_e32 v0, 16, v218
	v_mul_f32_e32 v0, 0xbfb8aa3b, v0
	v_exp_f32_e32 v0, v0
	s_nop 0
	v_min_f32_e32 v0, 0x7149f2ca, v0
	v_add_f32_e32 v0, 1.0, v0
	v_rcp_f32_e32 v170, v0
	v_and_b32_e32 v0, 0xffff0000, v220
	v_mul_f32_e32 v0, 0xbfb8aa3b, v0
	v_exp_f32_e32 v0, v0
	s_nop 0
	v_min_f32_e32 v169, 0x7149f2ca, v0
	v_and_b32_e32 v0, 0xffff0000, v218
	v_mul_f32_e32 v0, 0xbfb8aa3b, v0
	v_exp_f32_e32 v0, v0
	v_add_f32_e32 v168, 1.0, v168
	v_add_f32_e32 v169, 1.0, v169
	v_min_f32_e32 v0, 0x7149f2ca, v0
	v_add_f32_e32 v0, 1.0, v0
	v_rcp_f32_e32 v171, v0
	v_lshlrev_b32_e32 v0, 16, v221
	v_mul_f32_e32 v0, 0xbfb8aa3b, v0
	v_exp_f32_e32 v0, v0
	v_mul_f32_e32 v168, v168, v170
	v_mul_f32_e32 v169, v169, v171
	v_min_f32_e32 v146, 0x7149f2ca, v0
	v_lshlrev_b32_e32 v0, 16, v219
	v_mul_f32_e32 v0, 0xbfb8aa3b, v0
	v_exp_f32_e32 v0, v0
	v_mul_f32_e32 v64, v64, v168
	v_mul_f32_e32 v65, v65, v169
	v_min_f32_e32 v0, 0x7149f2ca, v0
	v_add_f32_e32 v0, 1.0, v0
	v_rcp_f32_e32 v166, v0
	v_and_b32_e32 v0, 0xffff0000, v221
	v_mul_f32_e32 v0, 0xbfb8aa3b, v0
	v_exp_f32_e32 v0, v0
	s_nop 0
	v_min_f32_e32 v147, 0x7149f2ca, v0
	v_and_b32_e32 v0, 0xffff0000, v219
	v_mul_f32_e32 v0, 0xbfb8aa3b, v0
	v_exp_f32_e32 v0, v0
	v_add_f32_e32 v146, 1.0, v146
	v_add_f32_e32 v147, 1.0, v147
	v_min_f32_e32 v0, 0x7149f2ca, v0
	v_add_f32_e32 v0, 1.0, v0
	v_rcp_f32_e32 v167, v0
	s_nop 0
	v_mul_f32_e32 v146, v146, v166
	v_mul_f32_e32 v147, v147, v167
	s_nop 0
	v_mul_f32_e32 v66, v66, v146
	v_mul_f32_e32 v67, v67, v147
	s_nop 0
	s_nop 0
	s_nop 0
	s_waitcnt vmcnt(4)
	v_lshlrev_b32_e32 v0, 16, v224
	v_mul_f32_e32 v0, 0xbfb8aa3b, v0
	v_exp_f32_e32 v0, v0
	s_nop 0
	v_min_f32_e32 v168, 0x7149f2ca, v0
	v_lshlrev_b32_e32 v0, 16, v222
	v_mul_f32_e32 v0, 0xbfb8aa3b, v0
	v_exp_f32_e32 v0, v0
	s_nop 0
	v_min_f32_e32 v0, 0x7149f2ca, v0
	v_add_f32_e32 v0, 1.0, v0
	v_rcp_f32_e32 v170, v0
	v_and_b32_e32 v0, 0xffff0000, v224
	v_mul_f32_e32 v0, 0xbfb8aa3b, v0
	v_exp_f32_e32 v0, v0
	s_nop 0
	v_min_f32_e32 v169, 0x7149f2ca, v0
	v_and_b32_e32 v0, 0xffff0000, v222
	v_mul_f32_e32 v0, 0xbfb8aa3b, v0
	v_exp_f32_e32 v0, v0
	v_add_f32_e32 v168, 1.0, v168
	v_add_f32_e32 v169, 1.0, v169
	v_min_f32_e32 v0, 0x7149f2ca, v0
	v_add_f32_e32 v0, 1.0, v0
	v_rcp_f32_e32 v171, v0
	v_lshlrev_b32_e32 v0, 16, v225
	v_mul_f32_e32 v0, 0xbfb8aa3b, v0
	v_exp_f32_e32 v0, v0
	v_mul_f32_e32 v168, v168, v170
	v_mul_f32_e32 v169, v169, v171
	v_min_f32_e32 v146, 0x7149f2ca, v0
	v_lshlrev_b32_e32 v0, 16, v223
	v_mul_f32_e32 v0, 0xbfb8aa3b, v0
	v_exp_f32_e32 v0, v0
	v_mul_f32_e32 v60, v60, v168
	v_mul_f32_e32 v61, v61, v169
	v_min_f32_e32 v0, 0x7149f2ca, v0
	v_add_f32_e32 v0, 1.0, v0
	v_rcp_f32_e32 v166, v0
	v_and_b32_e32 v0, 0xffff0000, v225
	v_mul_f32_e32 v0, 0xbfb8aa3b, v0
	v_exp_f32_e32 v0, v0
	s_nop 0
	v_min_f32_e32 v147, 0x7149f2ca, v0
	v_and_b32_e32 v0, 0xffff0000, v223
	v_mul_f32_e32 v0, 0xbfb8aa3b, v0
	v_exp_f32_e32 v0, v0
	v_add_f32_e32 v146, 1.0, v146
	v_add_f32_e32 v147, 1.0, v147
	v_min_f32_e32 v0, 0x7149f2ca, v0
	v_add_f32_e32 v0, 1.0, v0
	v_rcp_f32_e32 v167, v0
	s_nop 0
	v_mul_f32_e32 v146, v146, v166
	v_mul_f32_e32 v147, v147, v167
	s_nop 0
	v_mul_f32_e32 v62, v62, v146
	v_mul_f32_e32 v63, v63, v147
	s_nop 0
	s_nop 0
	s_nop 0
	s_waitcnt vmcnt(2)
	v_lshlrev_b32_e32 v0, 16, v228
	v_mul_f32_e32 v0, 0xbfb8aa3b, v0
	v_exp_f32_e32 v0, v0
	s_nop 0
	v_min_f32_e32 v168, 0x7149f2ca, v0
	v_lshlrev_b32_e32 v0, 16, v226
	v_mul_f32_e32 v0, 0xbfb8aa3b, v0
	v_exp_f32_e32 v0, v0
	s_nop 0
	v_min_f32_e32 v0, 0x7149f2ca, v0
	v_add_f32_e32 v0, 1.0, v0
	v_rcp_f32_e32 v170, v0
	v_and_b32_e32 v0, 0xffff0000, v228
	v_mul_f32_e32 v0, 0xbfb8aa3b, v0
	v_exp_f32_e32 v0, v0
	s_nop 0
	v_min_f32_e32 v169, 0x7149f2ca, v0
	v_and_b32_e32 v0, 0xffff0000, v226
	v_mul_f32_e32 v0, 0xbfb8aa3b, v0
	v_exp_f32_e32 v0, v0
	v_add_f32_e32 v168, 1.0, v168
	v_add_f32_e32 v169, 1.0, v169
	v_min_f32_e32 v0, 0x7149f2ca, v0
	v_add_f32_e32 v0, 1.0, v0
	v_rcp_f32_e32 v171, v0
	v_lshlrev_b32_e32 v0, 16, v229
	v_mul_f32_e32 v0, 0xbfb8aa3b, v0
	v_exp_f32_e32 v0, v0
	v_mul_f32_e32 v168, v168, v170
	v_mul_f32_e32 v169, v169, v171
	v_min_f32_e32 v146, 0x7149f2ca, v0
	v_lshlrev_b32_e32 v0, 16, v227
	v_mul_f32_e32 v0, 0xbfb8aa3b, v0
	v_exp_f32_e32 v0, v0
	v_mul_f32_e32 v56, v56, v168
	v_mul_f32_e32 v57, v57, v169
	v_min_f32_e32 v0, 0x7149f2ca, v0
	v_add_f32_e32 v0, 1.0, v0
	v_rcp_f32_e32 v166, v0
	v_and_b32_e32 v0, 0xffff0000, v229
	v_mul_f32_e32 v0, 0xbfb8aa3b, v0
	v_exp_f32_e32 v0, v0
	s_nop 0
	v_min_f32_e32 v147, 0x7149f2ca, v0
	v_and_b32_e32 v0, 0xffff0000, v227
	v_mul_f32_e32 v0, 0xbfb8aa3b, v0
	v_exp_f32_e32 v0, v0
	v_add_f32_e32 v146, 1.0, v146
	v_add_f32_e32 v147, 1.0, v147
	v_min_f32_e32 v0, 0x7149f2ca, v0
	v_add_f32_e32 v0, 1.0, v0
	v_rcp_f32_e32 v167, v0
	s_nop 0
	s_nop 0
	v_mul_f32_e32 v146, v146, v166
	v_mul_f32_e32 v147, v147, v167
	s_nop 0
	v_mul_f32_e32 v58, v58, v146
	v_mul_f32_e32 v59, v59, v147
	s_nop 0
	s_nop 0
	s_waitcnt vmcnt(0)
	v_lshlrev_b32_e32 v0, 16, v232
	v_mul_f32_e32 v0, 0xbfb8aa3b, v0
	v_exp_f32_e32 v0, v0
	s_nop 0
	v_min_f32_e32 v166, 0x7149f2ca, v0
	v_lshlrev_b32_e32 v0, 16, v230
	v_mul_f32_e32 v0, 0xbfb8aa3b, v0
	v_exp_f32_e32 v0, v0
	s_nop 0
	v_min_f32_e32 v0, 0x7149f2ca, v0
	v_add_f32_e32 v0, 1.0, v0
	v_rcp_f32_e32 v168, v0
	v_and_b32_e32 v0, 0xffff0000, v232
	v_mul_f32_e32 v0, 0xbfb8aa3b, v0
	v_exp_f32_e32 v0, v0
	s_nop 0
	v_min_f32_e32 v167, 0x7149f2ca, v0
	v_and_b32_e32 v0, 0xffff0000, v230
	v_mul_f32_e32 v0, 0xbfb8aa3b, v0
	v_exp_f32_e32 v0, v0
	v_add_f32_e32 v166, 1.0, v166
	v_add_f32_e32 v167, 1.0, v167
	v_min_f32_e32 v0, 0x7149f2ca, v0
	v_add_f32_e32 v0, 1.0, v0
	v_rcp_f32_e32 v169, v0
	v_lshlrev_b32_e32 v0, 16, v233
	v_mul_f32_e32 v0, 0xbfb8aa3b, v0
	v_exp_f32_e32 v0, v0
	v_mul_f32_e32 v166, v166, v168
	v_mul_f32_e32 v167, v167, v169
	v_min_f32_e32 v2, 0x7149f2ca, v0
	v_lshlrev_b32_e32 v0, 16, v231
	v_mul_f32_e32 v0, 0xbfb8aa3b, v0
	v_exp_f32_e32 v0, v0
	v_mul_f32_e32 v52, v52, v166
	v_mul_f32_e32 v53, v53, v167
	v_min_f32_e32 v0, 0x7149f2ca, v0
	v_add_f32_e32 v0, 1.0, v0
	v_rcp_f32_e32 v146, v0
	v_and_b32_e32 v0, 0xffff0000, v233
	v_mul_f32_e32 v0, 0xbfb8aa3b, v0
	v_exp_f32_e32 v0, v0
	s_nop 0
	v_min_f32_e32 v3, 0x7149f2ca, v0
	v_and_b32_e32 v0, 0xffff0000, v231
	v_mul_f32_e32 v0, 0xbfb8aa3b, v0
	v_exp_f32_e32 v0, v0
	v_add_f32_e32 v2, 1.0, v2
	v_add_f32_e32 v3, 1.0, v3
	v_min_f32_e32 v0, 0x7149f2ca, v0
	v_add_f32_e32 v0, 1.0, v0
	v_rcp_f32_e32 v147, v0
	v_mov_b32_e32 v0, v156
	v_mul_f32_e32 v2, v2, v146
	v_mul_f32_e32 v3, v3, v147
	s_nop 0
	v_mul_f32_e32 v54, v54, v2
	v_mul_f32_e32 v55, v55, v3
	s_nop 0
	s_nop 0
	v_mad_u64_u32 v[2:3], s[28:29], v0, s30, v[136:137]
	v_mov_b32_e32 v215, 0
	v_add_u32_e32 v214, s13, v2
	v_lshlrev_b64 v[216:217], 1, v[214:215]
	v_lshl_add_u64 v[218:219], s[4:5], 0, v[216:217]
	v_lshl_add_u64 v[220:221], s[8:9], 0, v[216:217]
	global_load_dwordx2 v[218:219], v[218:219], off
	global_load_dwordx2 v[220:221], v[220:221], off
	v_add_u32_e32 v214, s56, v2
	v_lshlrev_b64 v[216:217], 1, v[214:215]
	v_lshl_add_u64 v[222:223], s[4:5], 0, v[216:217]
	v_lshl_add_u64 v[224:225], s[8:9], 0, v[216:217]
	global_load_dwordx2 v[222:223], v[222:223], off
	global_load_dwordx2 v[224:225], v[224:225], off
	v_add_u32_e32 v214, s57, v2
	v_lshlrev_b64 v[216:217], 1, v[214:215]
	v_lshl_add_u64 v[226:227], s[4:5], 0, v[216:217]
	v_lshl_add_u64 v[228:229], s[8:9], 0, v[216:217]
	global_load_dwordx2 v[226:227], v[226:227], off
	global_load_dwordx2 v[228:229], v[228:229], off
	v_add_u32_e32 v214, s58, v2
	v_lshlrev_b64 v[216:217], 1, v[214:215]
	v_lshl_add_u64 v[230:231], s[4:5], 0, v[216:217]
	v_lshl_add_u64 v[232:233], s[8:9], 0, v[216:217]
	global_load_dwordx2 v[230:231], v[230:231], off
	global_load_dwordx2 v[232:233], v[232:233], off
	s_nop 0
	s_nop 0
	s_nop 0
	s_nop 0
	s_waitcnt vmcnt(6)
	v_lshlrev_b32_e32 v0, 16, v220
	v_mul_f32_e32 v0, 0xbfb8aa3b, v0
	v_exp_f32_e32 v0, v0
	s_nop 0
	v_min_f32_e32 v168, 0x7149f2ca, v0
	v_lshlrev_b32_e32 v0, 16, v218
	v_mul_f32_e32 v0, 0xbfb8aa3b, v0
	v_exp_f32_e32 v0, v0
	s_nop 0
	v_min_f32_e32 v0, 0x7149f2ca, v0
	v_add_f32_e32 v0, 1.0, v0
	v_rcp_f32_e32 v170, v0
	v_and_b32_e32 v0, 0xffff0000, v220
	v_mul_f32_e32 v0, 0xbfb8aa3b, v0
	v_exp_f32_e32 v0, v0
	s_nop 0
	v_min_f32_e32 v169, 0x7149f2ca, v0
	v_and_b32_e32 v0, 0xffff0000, v218
	v_mul_f32_e32 v0, 0xbfb8aa3b, v0
	v_exp_f32_e32 v0, v0
	v_add_f32_e32 v168, 1.0, v168
	v_add_f32_e32 v169, 1.0, v169
	v_min_f32_e32 v0, 0x7149f2ca, v0
	v_add_f32_e32 v0, 1.0, v0
	v_rcp_f32_e32 v171, v0
	v_lshlrev_b32_e32 v0, 16, v221
	v_mul_f32_e32 v0, 0xbfb8aa3b, v0
	v_exp_f32_e32 v0, v0
	v_mul_f32_e32 v168, v168, v170
	v_mul_f32_e32 v169, v169, v171
	v_min_f32_e32 v146, 0x7149f2ca, v0
	v_lshlrev_b32_e32 v0, 16, v219
	v_mul_f32_e32 v0, 0xbfb8aa3b, v0
	v_exp_f32_e32 v0, v0
	v_mul_f32_e32 v48, v48, v168
	v_mul_f32_e32 v49, v49, v169
	v_min_f32_e32 v0, 0x7149f2ca, v0
	v_add_f32_e32 v0, 1.0, v0
	v_rcp_f32_e32 v166, v0
	v_and_b32_e32 v0, 0xffff0000, v221
	v_mul_f32_e32 v0, 0xbfb8aa3b, v0
	v_exp_f32_e32 v0, v0
	s_nop 0
	v_min_f32_e32 v147, 0x7149f2ca, v0
	v_and_b32_e32 v0, 0xffff0000, v219
	v_mul_f32_e32 v0, 0xbfb8aa3b, v0
	v_exp_f32_e32 v0, v0
	v_add_f32_e32 v146, 1.0, v146
	v_add_f32_e32 v147, 1.0, v147
	v_min_f32_e32 v0, 0x7149f2ca, v0
	v_add_f32_e32 v0, 1.0, v0
	v_rcp_f32_e32 v167, v0
	s_nop 0
	v_mul_f32_e32 v146, v146, v166
	v_mul_f32_e32 v147, v147, v167
	s_nop 0
	v_mul_f32_e32 v50, v50, v146
	v_mul_f32_e32 v51, v51, v147
	s_nop 0
	s_nop 0
	s_nop 0
	s_waitcnt vmcnt(4)
	v_lshlrev_b32_e32 v0, 16, v224
	v_mul_f32_e32 v0, 0xbfb8aa3b, v0
	v_exp_f32_e32 v0, v0
	s_nop 0
	v_min_f32_e32 v168, 0x7149f2ca, v0
	v_lshlrev_b32_e32 v0, 16, v222
	v_mul_f32_e32 v0, 0xbfb8aa3b, v0
	v_exp_f32_e32 v0, v0
	s_nop 0
	v_min_f32_e32 v0, 0x7149f2ca, v0
	v_add_f32_e32 v0, 1.0, v0
	v_rcp_f32_e32 v170, v0
	v_and_b32_e32 v0, 0xffff0000, v224
	v_mul_f32_e32 v0, 0xbfb8aa3b, v0
	v_exp_f32_e32 v0, v0
	s_nop 0
	v_min_f32_e32 v169, 0x7149f2ca, v0
	v_and_b32_e32 v0, 0xffff0000, v222
	v_mul_f32_e32 v0, 0xbfb8aa3b, v0
	v_exp_f32_e32 v0, v0
	v_add_f32_e32 v168, 1.0, v168
	v_add_f32_e32 v169, 1.0, v169
	v_min_f32_e32 v0, 0x7149f2ca, v0
	v_add_f32_e32 v0, 1.0, v0
	v_rcp_f32_e32 v171, v0
	v_lshlrev_b32_e32 v0, 16, v225
	v_mul_f32_e32 v0, 0xbfb8aa3b, v0
	v_exp_f32_e32 v0, v0
	v_mul_f32_e32 v168, v168, v170
	v_mul_f32_e32 v169, v169, v171
	v_min_f32_e32 v146, 0x7149f2ca, v0
	v_lshlrev_b32_e32 v0, 16, v223
	v_mul_f32_e32 v0, 0xbfb8aa3b, v0
	v_exp_f32_e32 v0, v0
	v_mul_f32_e32 v44, v44, v168
	v_mul_f32_e32 v45, v45, v169
	v_min_f32_e32 v0, 0x7149f2ca, v0
	v_add_f32_e32 v0, 1.0, v0
	v_rcp_f32_e32 v166, v0
	v_and_b32_e32 v0, 0xffff0000, v225
	v_mul_f32_e32 v0, 0xbfb8aa3b, v0
	v_exp_f32_e32 v0, v0
	s_nop 0
	v_min_f32_e32 v147, 0x7149f2ca, v0
	v_and_b32_e32 v0, 0xffff0000, v223
	v_mul_f32_e32 v0, 0xbfb8aa3b, v0
	v_exp_f32_e32 v0, v0
	v_add_f32_e32 v146, 1.0, v146
	v_add_f32_e32 v147, 1.0, v147
	v_min_f32_e32 v0, 0x7149f2ca, v0
	v_add_f32_e32 v0, 1.0, v0
	v_rcp_f32_e32 v167, v0
	s_nop 0
	v_mul_f32_e32 v146, v146, v166
	v_mul_f32_e32 v147, v147, v167
	s_nop 0
	v_mul_f32_e32 v46, v46, v146
	v_mul_f32_e32 v47, v47, v147
	s_nop 0
	s_nop 0
	s_nop 0
	s_waitcnt vmcnt(2)
	v_lshlrev_b32_e32 v0, 16, v228
	v_mul_f32_e32 v0, 0xbfb8aa3b, v0
	v_exp_f32_e32 v0, v0
	s_nop 0
	v_min_f32_e32 v168, 0x7149f2ca, v0
	v_lshlrev_b32_e32 v0, 16, v226
	v_mul_f32_e32 v0, 0xbfb8aa3b, v0
	v_exp_f32_e32 v0, v0
	s_nop 0
	v_min_f32_e32 v0, 0x7149f2ca, v0
	v_add_f32_e32 v0, 1.0, v0
	v_rcp_f32_e32 v170, v0
	v_and_b32_e32 v0, 0xffff0000, v228
	v_mul_f32_e32 v0, 0xbfb8aa3b, v0
	v_exp_f32_e32 v0, v0
	s_nop 0
	v_min_f32_e32 v169, 0x7149f2ca, v0
	v_and_b32_e32 v0, 0xffff0000, v226
	v_mul_f32_e32 v0, 0xbfb8aa3b, v0
	v_exp_f32_e32 v0, v0
	v_add_f32_e32 v168, 1.0, v168
	v_add_f32_e32 v169, 1.0, v169
	v_min_f32_e32 v0, 0x7149f2ca, v0
	v_add_f32_e32 v0, 1.0, v0
	v_rcp_f32_e32 v171, v0
	v_lshlrev_b32_e32 v0, 16, v229
	v_mul_f32_e32 v0, 0xbfb8aa3b, v0
	v_exp_f32_e32 v0, v0
	v_mul_f32_e32 v168, v168, v170
	v_mul_f32_e32 v169, v169, v171
	v_min_f32_e32 v146, 0x7149f2ca, v0
	v_lshlrev_b32_e32 v0, 16, v227
	v_mul_f32_e32 v0, 0xbfb8aa3b, v0
	v_exp_f32_e32 v0, v0
	v_mul_f32_e32 v40, v40, v168
	v_mul_f32_e32 v41, v41, v169
	v_min_f32_e32 v0, 0x7149f2ca, v0
	v_add_f32_e32 v0, 1.0, v0
	v_rcp_f32_e32 v166, v0
	v_and_b32_e32 v0, 0xffff0000, v229
	v_mul_f32_e32 v0, 0xbfb8aa3b, v0
	v_exp_f32_e32 v0, v0
	s_nop 0
	v_min_f32_e32 v147, 0x7149f2ca, v0
	v_and_b32_e32 v0, 0xffff0000, v227
	v_mul_f32_e32 v0, 0xbfb8aa3b, v0
	v_exp_f32_e32 v0, v0
	v_add_f32_e32 v146, 1.0, v146
	v_add_f32_e32 v147, 1.0, v147
	v_min_f32_e32 v0, 0x7149f2ca, v0
	v_add_f32_e32 v0, 1.0, v0
	v_rcp_f32_e32 v167, v0
	s_nop 0
	s_nop 0
	v_mul_f32_e32 v146, v146, v166
	v_mul_f32_e32 v147, v147, v167
	s_nop 0
	v_mul_f32_e32 v42, v42, v146
	v_mul_f32_e32 v43, v43, v147
	s_nop 0
	s_nop 0
	s_waitcnt vmcnt(0)
	v_lshlrev_b32_e32 v0, 16, v232
	v_mul_f32_e32 v0, 0xbfb8aa3b, v0
	v_exp_f32_e32 v0, v0
	s_nop 0
	v_min_f32_e32 v166, 0x7149f2ca, v0
	v_lshlrev_b32_e32 v0, 16, v230
	v_mul_f32_e32 v0, 0xbfb8aa3b, v0
	v_exp_f32_e32 v0, v0
	s_nop 0
	v_min_f32_e32 v0, 0x7149f2ca, v0
	v_add_f32_e32 v0, 1.0, v0
	v_rcp_f32_e32 v168, v0
	v_and_b32_e32 v0, 0xffff0000, v232
	v_mul_f32_e32 v0, 0xbfb8aa3b, v0
	v_exp_f32_e32 v0, v0
	s_nop 0
	v_min_f32_e32 v167, 0x7149f2ca, v0
	v_and_b32_e32 v0, 0xffff0000, v230
	v_mul_f32_e32 v0, 0xbfb8aa3b, v0
	v_exp_f32_e32 v0, v0
	v_add_f32_e32 v166, 1.0, v166
	v_add_f32_e32 v167, 1.0, v167
	v_min_f32_e32 v0, 0x7149f2ca, v0
	v_add_f32_e32 v0, 1.0, v0
	v_rcp_f32_e32 v169, v0
	v_lshlrev_b32_e32 v0, 16, v233
	v_mul_f32_e32 v0, 0xbfb8aa3b, v0
	v_exp_f32_e32 v0, v0
	v_mul_f32_e32 v166, v166, v168
	v_mul_f32_e32 v167, v167, v169
	v_min_f32_e32 v2, 0x7149f2ca, v0
	v_lshlrev_b32_e32 v0, 16, v231
	v_mul_f32_e32 v0, 0xbfb8aa3b, v0
	v_exp_f32_e32 v0, v0
	v_mul_f32_e32 v36, v36, v166
	v_mul_f32_e32 v37, v37, v167
	v_min_f32_e32 v0, 0x7149f2ca, v0
	v_add_f32_e32 v0, 1.0, v0
	v_rcp_f32_e32 v146, v0
	v_and_b32_e32 v0, 0xffff0000, v233
	v_mul_f32_e32 v0, 0xbfb8aa3b, v0
	v_exp_f32_e32 v0, v0
	s_nop 0
	v_min_f32_e32 v3, 0x7149f2ca, v0
	v_and_b32_e32 v0, 0xffff0000, v231
	v_mul_f32_e32 v0, 0xbfb8aa3b, v0
	v_exp_f32_e32 v0, v0
	v_add_f32_e32 v2, 1.0, v2
	v_add_f32_e32 v3, 1.0, v3
	v_min_f32_e32 v0, 0x7149f2ca, v0
	v_add_f32_e32 v0, 1.0, v0
	v_rcp_f32_e32 v147, v0
	v_mov_b32_e32 v0, v157
	v_mul_f32_e32 v2, v2, v146
	v_mul_f32_e32 v3, v3, v147
	s_nop 0
	v_mul_f32_e32 v38, v38, v2
	v_mul_f32_e32 v39, v39, v3
	s_nop 0
	s_nop 0
	v_mad_u64_u32 v[2:3], s[28:29], v0, s30, v[136:137]
	v_mov_b32_e32 v215, 0
	v_add_u32_e32 v214, s13, v2
	v_lshlrev_b64 v[216:217], 1, v[214:215]
	v_lshl_add_u64 v[218:219], s[4:5], 0, v[216:217]
	v_lshl_add_u64 v[220:221], s[8:9], 0, v[216:217]
	global_load_dwordx2 v[218:219], v[218:219], off
	global_load_dwordx2 v[220:221], v[220:221], off
	v_add_u32_e32 v214, s56, v2
	v_lshlrev_b64 v[216:217], 1, v[214:215]
	v_lshl_add_u64 v[222:223], s[4:5], 0, v[216:217]
	v_lshl_add_u64 v[224:225], s[8:9], 0, v[216:217]
	global_load_dwordx2 v[222:223], v[222:223], off
	global_load_dwordx2 v[224:225], v[224:225], off
	v_add_u32_e32 v214, s57, v2
	v_lshlrev_b64 v[216:217], 1, v[214:215]
	v_lshl_add_u64 v[226:227], s[4:5], 0, v[216:217]
	v_lshl_add_u64 v[228:229], s[8:9], 0, v[216:217]
	global_load_dwordx2 v[226:227], v[226:227], off
	global_load_dwordx2 v[228:229], v[228:229], off
	v_add_u32_e32 v214, s58, v2
	v_lshlrev_b64 v[216:217], 1, v[214:215]
	v_lshl_add_u64 v[230:231], s[4:5], 0, v[216:217]
	v_lshl_add_u64 v[232:233], s[8:9], 0, v[216:217]
	global_load_dwordx2 v[230:231], v[230:231], off
	global_load_dwordx2 v[232:233], v[232:233], off
	s_nop 0
	s_nop 0
	s_nop 0
	s_nop 0
	s_waitcnt vmcnt(6)
	v_lshlrev_b32_e32 v0, 16, v220
	v_mul_f32_e32 v0, 0xbfb8aa3b, v0
	v_exp_f32_e32 v0, v0
	s_nop 0
	v_min_f32_e32 v168, 0x7149f2ca, v0
	v_lshlrev_b32_e32 v0, 16, v218
	v_mul_f32_e32 v0, 0xbfb8aa3b, v0
	v_exp_f32_e32 v0, v0
	s_nop 0
	v_min_f32_e32 v0, 0x7149f2ca, v0
	v_add_f32_e32 v0, 1.0, v0
	v_rcp_f32_e32 v170, v0
	v_and_b32_e32 v0, 0xffff0000, v220
	v_mul_f32_e32 v0, 0xbfb8aa3b, v0
	v_exp_f32_e32 v0, v0
	s_nop 0
	v_min_f32_e32 v169, 0x7149f2ca, v0
	v_and_b32_e32 v0, 0xffff0000, v218
	v_mul_f32_e32 v0, 0xbfb8aa3b, v0
	v_exp_f32_e32 v0, v0
	v_add_f32_e32 v168, 1.0, v168
	v_add_f32_e32 v169, 1.0, v169
	v_min_f32_e32 v0, 0x7149f2ca, v0
	v_add_f32_e32 v0, 1.0, v0
	v_rcp_f32_e32 v171, v0
	v_lshlrev_b32_e32 v0, 16, v221
	v_mul_f32_e32 v0, 0xbfb8aa3b, v0
	v_exp_f32_e32 v0, v0
	v_mul_f32_e32 v168, v168, v170
	v_mul_f32_e32 v169, v169, v171
	v_min_f32_e32 v146, 0x7149f2ca, v0
	v_lshlrev_b32_e32 v0, 16, v219
	v_mul_f32_e32 v0, 0xbfb8aa3b, v0
	v_exp_f32_e32 v0, v0
	v_mul_f32_e32 v32, v32, v168
	v_mul_f32_e32 v33, v33, v169
	v_min_f32_e32 v0, 0x7149f2ca, v0
	v_add_f32_e32 v0, 1.0, v0
	v_rcp_f32_e32 v166, v0
	v_and_b32_e32 v0, 0xffff0000, v221
	v_mul_f32_e32 v0, 0xbfb8aa3b, v0
	v_exp_f32_e32 v0, v0
	s_nop 0
	v_min_f32_e32 v147, 0x7149f2ca, v0
	v_and_b32_e32 v0, 0xffff0000, v219
	v_mul_f32_e32 v0, 0xbfb8aa3b, v0
	v_exp_f32_e32 v0, v0
	v_add_f32_e32 v146, 1.0, v146
	v_add_f32_e32 v147, 1.0, v147
	v_min_f32_e32 v0, 0x7149f2ca, v0
	v_add_f32_e32 v0, 1.0, v0
	v_rcp_f32_e32 v167, v0
	s_nop 0
	v_mul_f32_e32 v146, v146, v166
	v_mul_f32_e32 v147, v147, v167
	s_nop 0
	v_mul_f32_e32 v34, v34, v146
	v_mul_f32_e32 v35, v35, v147
	s_nop 0
	s_nop 0
	s_nop 0
	s_waitcnt vmcnt(4)
	v_lshlrev_b32_e32 v0, 16, v224
	v_mul_f32_e32 v0, 0xbfb8aa3b, v0
	v_exp_f32_e32 v0, v0
	s_nop 0
	v_min_f32_e32 v168, 0x7149f2ca, v0
	v_lshlrev_b32_e32 v0, 16, v222
	v_mul_f32_e32 v0, 0xbfb8aa3b, v0
	v_exp_f32_e32 v0, v0
	s_nop 0
	v_min_f32_e32 v0, 0x7149f2ca, v0
	v_add_f32_e32 v0, 1.0, v0
	v_rcp_f32_e32 v170, v0
	v_and_b32_e32 v0, 0xffff0000, v224
	v_mul_f32_e32 v0, 0xbfb8aa3b, v0
	v_exp_f32_e32 v0, v0
	s_nop 0
	v_min_f32_e32 v169, 0x7149f2ca, v0
	v_and_b32_e32 v0, 0xffff0000, v222
	v_mul_f32_e32 v0, 0xbfb8aa3b, v0
	v_exp_f32_e32 v0, v0
	v_add_f32_e32 v168, 1.0, v168
	v_add_f32_e32 v169, 1.0, v169
	v_min_f32_e32 v0, 0x7149f2ca, v0
	v_add_f32_e32 v0, 1.0, v0
	v_rcp_f32_e32 v171, v0
	v_lshlrev_b32_e32 v0, 16, v225
	v_mul_f32_e32 v0, 0xbfb8aa3b, v0
	v_exp_f32_e32 v0, v0
	v_mul_f32_e32 v168, v168, v170
	v_mul_f32_e32 v169, v169, v171
	v_min_f32_e32 v146, 0x7149f2ca, v0
	v_lshlrev_b32_e32 v0, 16, v223
	v_mul_f32_e32 v0, 0xbfb8aa3b, v0
	v_exp_f32_e32 v0, v0
	v_mul_f32_e32 v28, v28, v168
	v_mul_f32_e32 v29, v29, v169
	v_min_f32_e32 v0, 0x7149f2ca, v0
	v_add_f32_e32 v0, 1.0, v0
	v_rcp_f32_e32 v166, v0
	v_and_b32_e32 v0, 0xffff0000, v225
	v_mul_f32_e32 v0, 0xbfb8aa3b, v0
	v_exp_f32_e32 v0, v0
	s_nop 0
	v_min_f32_e32 v147, 0x7149f2ca, v0
	v_and_b32_e32 v0, 0xffff0000, v223
	v_mul_f32_e32 v0, 0xbfb8aa3b, v0
	v_exp_f32_e32 v0, v0
	v_add_f32_e32 v146, 1.0, v146
	v_add_f32_e32 v147, 1.0, v147
	v_min_f32_e32 v0, 0x7149f2ca, v0
	v_add_f32_e32 v0, 1.0, v0
	v_rcp_f32_e32 v167, v0
	s_nop 0
	v_mul_f32_e32 v146, v146, v166
	v_mul_f32_e32 v147, v147, v167
	s_nop 0
	v_mul_f32_e32 v30, v30, v146
	v_mul_f32_e32 v31, v31, v147
	s_nop 0
	s_nop 0
	s_nop 0
	s_waitcnt vmcnt(2)
	v_lshlrev_b32_e32 v0, 16, v228
	v_mul_f32_e32 v0, 0xbfb8aa3b, v0
	v_exp_f32_e32 v0, v0
	s_nop 0
	v_min_f32_e32 v168, 0x7149f2ca, v0
	v_lshlrev_b32_e32 v0, 16, v226
	v_mul_f32_e32 v0, 0xbfb8aa3b, v0
	v_exp_f32_e32 v0, v0
	s_nop 0
	v_min_f32_e32 v0, 0x7149f2ca, v0
	v_add_f32_e32 v0, 1.0, v0
	v_rcp_f32_e32 v170, v0
	v_and_b32_e32 v0, 0xffff0000, v228
	v_mul_f32_e32 v0, 0xbfb8aa3b, v0
	v_exp_f32_e32 v0, v0
	s_nop 0
	v_min_f32_e32 v169, 0x7149f2ca, v0
	v_and_b32_e32 v0, 0xffff0000, v226
	v_mul_f32_e32 v0, 0xbfb8aa3b, v0
	v_exp_f32_e32 v0, v0
	v_add_f32_e32 v168, 1.0, v168
	v_add_f32_e32 v169, 1.0, v169
	v_min_f32_e32 v0, 0x7149f2ca, v0
	v_add_f32_e32 v0, 1.0, v0
	v_rcp_f32_e32 v171, v0
	v_lshlrev_b32_e32 v0, 16, v229
	v_mul_f32_e32 v0, 0xbfb8aa3b, v0
	v_exp_f32_e32 v0, v0
	v_mul_f32_e32 v168, v168, v170
	v_mul_f32_e32 v169, v169, v171
	v_min_f32_e32 v146, 0x7149f2ca, v0
	v_lshlrev_b32_e32 v0, 16, v227
	v_mul_f32_e32 v0, 0xbfb8aa3b, v0
	v_exp_f32_e32 v0, v0
	v_mul_f32_e32 v24, v24, v168
	v_mul_f32_e32 v25, v25, v169
	v_min_f32_e32 v0, 0x7149f2ca, v0
	v_add_f32_e32 v0, 1.0, v0
	v_rcp_f32_e32 v166, v0
	v_and_b32_e32 v0, 0xffff0000, v229
	v_mul_f32_e32 v0, 0xbfb8aa3b, v0
	v_exp_f32_e32 v0, v0
	s_nop 0
	v_min_f32_e32 v147, 0x7149f2ca, v0
	v_and_b32_e32 v0, 0xffff0000, v227
	v_mul_f32_e32 v0, 0xbfb8aa3b, v0
	v_exp_f32_e32 v0, v0
	v_add_f32_e32 v146, 1.0, v146
	v_add_f32_e32 v147, 1.0, v147
	v_min_f32_e32 v0, 0x7149f2ca, v0
	v_add_f32_e32 v0, 1.0, v0
	v_rcp_f32_e32 v167, v0
	s_nop 0
	s_nop 0
	v_mul_f32_e32 v146, v146, v166
	v_mul_f32_e32 v147, v147, v167
	s_nop 0
	v_mul_f32_e32 v26, v26, v146
	v_mul_f32_e32 v27, v27, v147
	s_nop 0
	s_nop 0
	s_waitcnt vmcnt(0)
	v_lshlrev_b32_e32 v0, 16, v232
	v_mul_f32_e32 v0, 0xbfb8aa3b, v0
	v_exp_f32_e32 v0, v0
	s_nop 0
	v_min_f32_e32 v166, 0x7149f2ca, v0
	v_lshlrev_b32_e32 v0, 16, v230
	v_mul_f32_e32 v0, 0xbfb8aa3b, v0
	v_exp_f32_e32 v0, v0
	s_nop 0
	v_min_f32_e32 v0, 0x7149f2ca, v0
	v_add_f32_e32 v0, 1.0, v0
	v_rcp_f32_e32 v168, v0
	v_and_b32_e32 v0, 0xffff0000, v232
	v_mul_f32_e32 v0, 0xbfb8aa3b, v0
	v_exp_f32_e32 v0, v0
	s_nop 0
	v_min_f32_e32 v167, 0x7149f2ca, v0
	v_and_b32_e32 v0, 0xffff0000, v230
	v_mul_f32_e32 v0, 0xbfb8aa3b, v0
	v_exp_f32_e32 v0, v0
	v_add_f32_e32 v166, 1.0, v166
	v_add_f32_e32 v167, 1.0, v167
	v_min_f32_e32 v0, 0x7149f2ca, v0
	v_add_f32_e32 v0, 1.0, v0
	v_rcp_f32_e32 v169, v0
	v_lshlrev_b32_e32 v0, 16, v233
	v_mul_f32_e32 v0, 0xbfb8aa3b, v0
	v_exp_f32_e32 v0, v0
	v_mul_f32_e32 v166, v166, v168
	v_mul_f32_e32 v167, v167, v169
	v_min_f32_e32 v2, 0x7149f2ca, v0
	v_lshlrev_b32_e32 v0, 16, v231
	v_mul_f32_e32 v0, 0xbfb8aa3b, v0
	v_exp_f32_e32 v0, v0
	v_mul_f32_e32 v20, v20, v166
	v_mul_f32_e32 v21, v21, v167
	v_min_f32_e32 v0, 0x7149f2ca, v0
	v_add_f32_e32 v0, 1.0, v0
	v_rcp_f32_e32 v146, v0
	v_and_b32_e32 v0, 0xffff0000, v233
	v_mul_f32_e32 v0, 0xbfb8aa3b, v0
	v_exp_f32_e32 v0, v0
	s_nop 0
	v_min_f32_e32 v3, 0x7149f2ca, v0
	v_and_b32_e32 v0, 0xffff0000, v231
	v_mul_f32_e32 v0, 0xbfb8aa3b, v0
	v_exp_f32_e32 v0, v0
	v_add_f32_e32 v2, 1.0, v2
	v_add_f32_e32 v3, 1.0, v3
	v_min_f32_e32 v0, 0x7149f2ca, v0
	v_add_f32_e32 v0, 1.0, v0
	v_rcp_f32_e32 v147, v0
	v_mov_b32_e32 v0, v158
	v_mul_f32_e32 v2, v2, v146
	v_mul_f32_e32 v3, v3, v147
	s_nop 0
	v_mul_f32_e32 v22, v22, v2
	v_mul_f32_e32 v23, v23, v3
	s_nop 0
	s_nop 0
	v_mad_u64_u32 v[2:3], s[28:29], v0, s30, v[136:137]
	v_mov_b32_e32 v215, 0
	v_add_u32_e32 v214, s13, v2
	v_lshlrev_b64 v[216:217], 1, v[214:215]
	v_lshl_add_u64 v[218:219], s[4:5], 0, v[216:217]
	v_lshl_add_u64 v[220:221], s[8:9], 0, v[216:217]
	global_load_dwordx2 v[218:219], v[218:219], off
	global_load_dwordx2 v[220:221], v[220:221], off
	v_add_u32_e32 v214, s56, v2
	v_lshlrev_b64 v[216:217], 1, v[214:215]
	v_lshl_add_u64 v[222:223], s[4:5], 0, v[216:217]
	v_lshl_add_u64 v[224:225], s[8:9], 0, v[216:217]
	global_load_dwordx2 v[222:223], v[222:223], off
	global_load_dwordx2 v[224:225], v[224:225], off
	v_add_u32_e32 v214, s57, v2
	v_lshlrev_b64 v[216:217], 1, v[214:215]
	v_lshl_add_u64 v[226:227], s[4:5], 0, v[216:217]
	v_lshl_add_u64 v[228:229], s[8:9], 0, v[216:217]
	global_load_dwordx2 v[226:227], v[226:227], off
	global_load_dwordx2 v[228:229], v[228:229], off
	v_add_u32_e32 v214, s58, v2
	v_lshlrev_b64 v[216:217], 1, v[214:215]
	v_lshl_add_u64 v[230:231], s[4:5], 0, v[216:217]
	v_lshl_add_u64 v[232:233], s[8:9], 0, v[216:217]
	global_load_dwordx2 v[230:231], v[230:231], off
	global_load_dwordx2 v[232:233], v[232:233], off
	s_nop 0
	s_nop 0
	s_nop 0
	s_nop 0
	s_waitcnt vmcnt(6)
	v_lshlrev_b32_e32 v0, 16, v220
	v_mul_f32_e32 v0, 0xbfb8aa3b, v0
	v_exp_f32_e32 v0, v0
	s_nop 0
	v_min_f32_e32 v168, 0x7149f2ca, v0
	v_lshlrev_b32_e32 v0, 16, v218
	v_mul_f32_e32 v0, 0xbfb8aa3b, v0
	v_exp_f32_e32 v0, v0
	s_nop 0
	v_min_f32_e32 v0, 0x7149f2ca, v0
	v_add_f32_e32 v0, 1.0, v0
	v_rcp_f32_e32 v170, v0
	v_and_b32_e32 v0, 0xffff0000, v220
	v_mul_f32_e32 v0, 0xbfb8aa3b, v0
	v_exp_f32_e32 v0, v0
	s_nop 0
	v_min_f32_e32 v169, 0x7149f2ca, v0
	v_and_b32_e32 v0, 0xffff0000, v218
	v_mul_f32_e32 v0, 0xbfb8aa3b, v0
	v_exp_f32_e32 v0, v0
	v_add_f32_e32 v168, 1.0, v168
	v_add_f32_e32 v169, 1.0, v169
	v_min_f32_e32 v0, 0x7149f2ca, v0
	v_add_f32_e32 v0, 1.0, v0
	v_rcp_f32_e32 v171, v0
	v_lshlrev_b32_e32 v0, 16, v221
	v_mul_f32_e32 v0, 0xbfb8aa3b, v0
	v_exp_f32_e32 v0, v0
	v_mul_f32_e32 v168, v168, v170
	v_mul_f32_e32 v169, v169, v171
	v_min_f32_e32 v146, 0x7149f2ca, v0
	v_lshlrev_b32_e32 v0, 16, v219
	v_mul_f32_e32 v0, 0xbfb8aa3b, v0
	v_exp_f32_e32 v0, v0
	v_mul_f32_e32 v16, v16, v168
	v_mul_f32_e32 v17, v17, v169
	v_min_f32_e32 v0, 0x7149f2ca, v0
	v_add_f32_e32 v0, 1.0, v0
	v_rcp_f32_e32 v166, v0
	v_and_b32_e32 v0, 0xffff0000, v221
	v_mul_f32_e32 v0, 0xbfb8aa3b, v0
	v_exp_f32_e32 v0, v0
	s_nop 0
	v_min_f32_e32 v147, 0x7149f2ca, v0
	v_and_b32_e32 v0, 0xffff0000, v219
	v_mul_f32_e32 v0, 0xbfb8aa3b, v0
	v_exp_f32_e32 v0, v0
	v_add_f32_e32 v146, 1.0, v146
	v_add_f32_e32 v147, 1.0, v147
	v_min_f32_e32 v0, 0x7149f2ca, v0
	v_add_f32_e32 v0, 1.0, v0
	v_rcp_f32_e32 v167, v0
	s_nop 0
	v_mul_f32_e32 v146, v146, v166
	v_mul_f32_e32 v147, v147, v167
	s_nop 0
	v_mul_f32_e32 v18, v18, v146
	v_mul_f32_e32 v19, v19, v147
	s_nop 0
	s_nop 0
	s_nop 0
	s_waitcnt vmcnt(4)
	v_lshlrev_b32_e32 v0, 16, v224
	v_mul_f32_e32 v0, 0xbfb8aa3b, v0
	v_exp_f32_e32 v0, v0
	s_nop 0
	v_min_f32_e32 v168, 0x7149f2ca, v0
	v_lshlrev_b32_e32 v0, 16, v222
	v_mul_f32_e32 v0, 0xbfb8aa3b, v0
	v_exp_f32_e32 v0, v0
	s_nop 0
	v_min_f32_e32 v0, 0x7149f2ca, v0
	v_add_f32_e32 v0, 1.0, v0
	v_rcp_f32_e32 v170, v0
	v_and_b32_e32 v0, 0xffff0000, v224
	v_mul_f32_e32 v0, 0xbfb8aa3b, v0
	v_exp_f32_e32 v0, v0
	s_nop 0
	v_min_f32_e32 v169, 0x7149f2ca, v0
	v_and_b32_e32 v0, 0xffff0000, v222
	v_mul_f32_e32 v0, 0xbfb8aa3b, v0
	v_exp_f32_e32 v0, v0
	v_add_f32_e32 v168, 1.0, v168
	v_add_f32_e32 v169, 1.0, v169
	v_min_f32_e32 v0, 0x7149f2ca, v0
	v_add_f32_e32 v0, 1.0, v0
	v_rcp_f32_e32 v171, v0
	v_lshlrev_b32_e32 v0, 16, v225
	v_mul_f32_e32 v0, 0xbfb8aa3b, v0
	v_exp_f32_e32 v0, v0
	v_mul_f32_e32 v168, v168, v170
	v_mul_f32_e32 v169, v169, v171
	v_min_f32_e32 v146, 0x7149f2ca, v0
	v_lshlrev_b32_e32 v0, 16, v223
	v_mul_f32_e32 v0, 0xbfb8aa3b, v0
	v_exp_f32_e32 v0, v0
	v_mul_f32_e32 v12, v12, v168
	v_mul_f32_e32 v13, v13, v169
	v_min_f32_e32 v0, 0x7149f2ca, v0
	v_add_f32_e32 v0, 1.0, v0
	v_rcp_f32_e32 v166, v0
	v_and_b32_e32 v0, 0xffff0000, v225
	v_mul_f32_e32 v0, 0xbfb8aa3b, v0
	v_exp_f32_e32 v0, v0
	s_nop 0
	v_min_f32_e32 v147, 0x7149f2ca, v0
	v_and_b32_e32 v0, 0xffff0000, v223
	v_mul_f32_e32 v0, 0xbfb8aa3b, v0
	v_exp_f32_e32 v0, v0
	v_add_f32_e32 v146, 1.0, v146
	v_add_f32_e32 v147, 1.0, v147
	v_min_f32_e32 v0, 0x7149f2ca, v0
	v_add_f32_e32 v0, 1.0, v0
	v_rcp_f32_e32 v167, v0
	s_nop 0
	v_mul_f32_e32 v146, v146, v166
	v_mul_f32_e32 v147, v147, v167
	s_nop 0
	v_mul_f32_e32 v14, v14, v146
	v_mul_f32_e32 v15, v15, v147
	s_nop 0
	s_nop 0
	s_nop 0
	s_waitcnt vmcnt(2)
	v_lshlrev_b32_e32 v0, 16, v228
	v_mul_f32_e32 v0, 0xbfb8aa3b, v0
	v_exp_f32_e32 v0, v0
	s_nop 0
	v_min_f32_e32 v168, 0x7149f2ca, v0
	v_lshlrev_b32_e32 v0, 16, v226
	v_mul_f32_e32 v0, 0xbfb8aa3b, v0
	v_exp_f32_e32 v0, v0
	s_nop 0
	v_min_f32_e32 v0, 0x7149f2ca, v0
	v_add_f32_e32 v0, 1.0, v0
	v_rcp_f32_e32 v170, v0
	v_and_b32_e32 v0, 0xffff0000, v228
	v_mul_f32_e32 v0, 0xbfb8aa3b, v0
	v_exp_f32_e32 v0, v0
	s_nop 0
	v_min_f32_e32 v169, 0x7149f2ca, v0
	v_and_b32_e32 v0, 0xffff0000, v226
	v_mul_f32_e32 v0, 0xbfb8aa3b, v0
	v_exp_f32_e32 v0, v0
	v_add_f32_e32 v168, 1.0, v168
	v_add_f32_e32 v169, 1.0, v169
	v_min_f32_e32 v0, 0x7149f2ca, v0
	v_add_f32_e32 v0, 1.0, v0
	v_rcp_f32_e32 v171, v0
	v_lshlrev_b32_e32 v0, 16, v229
	v_mul_f32_e32 v0, 0xbfb8aa3b, v0
	v_exp_f32_e32 v0, v0
	v_mul_f32_e32 v168, v168, v170
	v_mul_f32_e32 v169, v169, v171
	v_min_f32_e32 v146, 0x7149f2ca, v0
	v_lshlrev_b32_e32 v0, 16, v227
	v_mul_f32_e32 v0, 0xbfb8aa3b, v0
	v_exp_f32_e32 v0, v0
	v_mul_f32_e32 v8, v8, v168
	v_mul_f32_e32 v9, v9, v169
	v_min_f32_e32 v0, 0x7149f2ca, v0
	v_add_f32_e32 v0, 1.0, v0
	v_rcp_f32_e32 v166, v0
	v_and_b32_e32 v0, 0xffff0000, v229
	v_mul_f32_e32 v0, 0xbfb8aa3b, v0
	v_exp_f32_e32 v0, v0
	s_nop 0
	v_min_f32_e32 v147, 0x7149f2ca, v0
	v_and_b32_e32 v0, 0xffff0000, v227
	v_mul_f32_e32 v0, 0xbfb8aa3b, v0
	v_exp_f32_e32 v0, v0
	v_add_f32_e32 v146, 1.0, v146
	v_add_f32_e32 v147, 1.0, v147
	v_min_f32_e32 v0, 0x7149f2ca, v0
	v_add_f32_e32 v0, 1.0, v0
	v_rcp_f32_e32 v167, v0
	s_nop 0
	v_mul_f32_e32 v146, v146, v166
	v_mul_f32_e32 v147, v147, v167
	s_nop 0
	v_mul_f32_e32 v10, v10, v146
	v_mul_f32_e32 v11, v11, v147
	s_nop 0
	s_nop 0
	s_nop 0
	s_waitcnt vmcnt(0)
	v_lshlrev_b32_e32 v0, 16, v232
	v_mul_f32_e32 v0, 0xbfb8aa3b, v0
	v_exp_f32_e32 v0, v0
	s_nop 0
	v_min_f32_e32 v146, 0x7149f2ca, v0
	v_lshlrev_b32_e32 v0, 16, v230
	v_mul_f32_e32 v0, 0xbfb8aa3b, v0
	v_exp_f32_e32 v0, v0
	s_nop 0
	v_min_f32_e32 v0, 0x7149f2ca, v0
	v_add_f32_e32 v0, 1.0, v0
	v_rcp_f32_e32 v168, v0
	v_and_b32_e32 v0, 0xffff0000, v232
	v_mul_f32_e32 v0, 0xbfb8aa3b, v0
	v_exp_f32_e32 v0, v0
	s_nop 0
	v_min_f32_e32 v147, 0x7149f2ca, v0
	v_and_b32_e32 v0, 0xffff0000, v230
	v_mul_f32_e32 v0, 0xbfb8aa3b, v0
	v_exp_f32_e32 v0, v0
	v_add_f32_e32 v146, 1.0, v146
	v_add_f32_e32 v147, 1.0, v147
	v_min_f32_e32 v0, 0x7149f2ca, v0
	v_add_f32_e32 v0, 1.0, v0
	v_rcp_f32_e32 v169, v0
	v_lshlrev_b32_e32 v0, 16, v233
	v_mul_f32_e32 v0, 0xbfb8aa3b, v0
	v_exp_f32_e32 v0, v0
	v_mul_f32_e32 v146, v146, v168
	v_mul_f32_e32 v147, v147, v169
	v_min_f32_e32 v166, 0x7149f2ca, v0
	v_lshlrev_b32_e32 v0, 16, v231
	v_mul_f32_e32 v0, 0xbfb8aa3b, v0
	v_exp_f32_e32 v0, v0
	v_mul_f32_e32 v4, v4, v146
	v_mul_f32_e32 v5, v5, v147
	v_min_f32_e32 v0, 0x7149f2ca, v0
	v_add_f32_e32 v0, 1.0, v0
	v_rcp_f32_e32 v2, v0
	v_and_b32_e32 v0, 0xffff0000, v233
	v_mul_f32_e32 v0, 0xbfb8aa3b, v0
	v_exp_f32_e32 v0, v0
	s_nop 0
	v_min_f32_e32 v167, 0x7149f2ca, v0
	v_and_b32_e32 v0, 0xffff0000, v231
	v_mul_f32_e32 v0, 0xbfb8aa3b, v0
	v_exp_f32_e32 v0, v0
	v_add_f32_e32 v166, 1.0, v166
	v_add_f32_e32 v167, 1.0, v167
	v_min_f32_e32 v0, 0x7149f2ca, v0
	v_add_f32_e32 v0, 1.0, v0
	v_rcp_f32_e32 v3, v0
	s_nop 0
	v_mul_f32_e32 v2, v166, v2
	v_mul_f32_e32 v3, v167, v3
	s_nop 0
	v_mul_f32_e32 v6, v6, v2
	v_mul_f32_e32 v7, v7, v3
	s_nop 0

.LBB0_1087:
	v_or_b32_e32 v2, s13, v136
	v_mov_b32_e32 v152, v151
	s_movk_i32 s13, 0x1320
	v_mov_b32_e32 v3, v1
	v_mul_lo_u32 v0, v152, s13
	v_lshl_add_u64 v[144:145], v[0:1], 1, s[8:9]
	v_lshlrev_b64 v[142:143], 1, v[2:3]
	v_lshl_add_u64 v[144:145], v[144:145], 0, v[142:143]
	global_load_dwordx2 v[146:147], v[144:145], off
	global_load_dwordx2 v[198:199], v[144:145], off offset:32
	global_load_dwordx2 v[200:201], v[144:145], off offset:256
	global_load_dwordx2 v[202:203], v[144:145], off offset:288
	v_lshlrev_b32_e32 v156, 10, v152
	s_andn2_b64 vcc, exec, s[6:7]
	s_mov_b64 s[6:7], -1
	s_waitcnt vmcnt(3)
	v_lshlrev_b32_e32 v0, 16, v146
	v_and_b32_e32 v3, 0xffff0000, v146
	v_lshlrev_b32_e32 v146, 16, v147
	v_and_b32_e32 v147, 0xffff0000, v147
	v_mul_f32_e32 v0, 0xbfb8aa3b, v0
	v_mul_f32_e32 v3, 0xbfb8aa3b, v3
	v_mul_f32_e32 v146, 0xbfb8aa3b, v146
	v_mul_f32_e32 v147, 0xbfb8aa3b, v147
	v_exp_f32_e32 v0, v0
	v_exp_f32_e32 v3, v3
	v_exp_f32_e32 v146, v146
	v_exp_f32_e32 v147, v147
	v_min_f32_e32 v0, 0x7149f2ca, v0
	v_min_f32_e32 v3, 0x7149f2ca, v3
	v_min_f32_e32 v146, 0x7149f2ca, v146
	v_min_f32_e32 v147, 0x7149f2ca, v147
	v_add_f32_e32 v0, 1.0, v0
	v_add_f32_e32 v3, 1.0, v3
	v_add_f32_e32 v152, 1.0, v146
	v_add_f32_e32 v153, 1.0, v147
	v_rcp_f32_e32 v146, v0
	v_rcp_f32_e32 v147, v3
	v_rcp_f32_e32 v152, v152
	v_rcp_f32_e32 v153, v153
	v_add_u32_e32 v0, v156, v2
	v_mul_f32_e32 v128, v128, v146
	v_mul_f32_e32 v129, v129, v147
	v_lshl_add_u64 v[154:155], v[0:1], 1, s[2:3]
	v_mul_f32_e32 v130, v130, v152
	v_mul_f32_e32 v131, v131, v153
	v_cvt_pk_bf16_f32 v128, v128, v129
	v_cvt_pk_bf16_f32 v129, v130, v131
	global_store_dwordx2 v[154:155], v[128:129], off
	s_nop 0
	v_or_b32_e32 v3, 16, v2
	s_waitcnt vmcnt(3)
	v_lshlrev_b32_e32 v0, 16, v198
	v_and_b32_e32 v128, 0xffff0000, v198
	v_lshlrev_b32_e32 v130, 16, v199
	v_and_b32_e32 v129, 0xffff0000, v199
	v_mul_f32_e32 v0, 0xbfb8aa3b, v0
	v_mul_f32_e32 v128, 0xbfb8aa3b, v128
	v_mul_f32_e32 v130, 0xbfb8aa3b, v130
	v_mul_f32_e32 v129, 0xbfb8aa3b, v129
	v_exp_f32_e32 v0, v0
	v_exp_f32_e32 v128, v128
	v_exp_f32_e32 v130, v130
	v_exp_f32_e32 v129, v129
	v_min_f32_e32 v0, 0x7149f2ca, v0
	v_min_f32_e32 v128, 0x7149f2ca, v128
	v_min_f32_e32 v130, 0x7149f2ca, v130
	v_min_f32_e32 v129, 0x7149f2ca, v129
	v_add_f32_e32 v0, 1.0, v0
	v_add_f32_e32 v131, 1.0, v128
	v_add_f32_e32 v130, 1.0, v130
	v_add_f32_e32 v146, 1.0, v129
	v_rcp_f32_e32 v128, v0
	v_rcp_f32_e32 v129, v131
	v_rcp_f32_e32 v130, v130
	v_rcp_f32_e32 v131, v146
	v_add_u32_e32 v0, v156, v3
	v_mul_f32_e32 v124, v124, v128
	v_mul_f32_e32 v125, v125, v129
	v_lshl_add_u64 v[146:147], v[0:1], 1, s[2:3]
	v_mul_f32_e32 v126, v126, v130
	v_mul_f32_e32 v127, v127, v131
	v_cvt_pk_bf16_f32 v124, v124, v125
	v_cvt_pk_bf16_f32 v125, v126, v127
	global_store_dwordx2 v[146:147], v[124:125], off
	s_nop 0
	v_or_b32_e32 v124, 0x80, v2
	s_waitcnt vmcnt(3)
	v_lshlrev_b32_e32 v0, 16, v200
	v_and_b32_e32 v125, 0xffff0000, v200
	v_lshlrev_b32_e32 v126, 16, v201
	v_and_b32_e32 v127, 0xffff0000, v201
	v_mul_f32_e32 v0, 0xbfb8aa3b, v0
	v_mul_f32_e32 v125, 0xbfb8aa3b, v125
	v_mul_f32_e32 v126, 0xbfb8aa3b, v126
	v_mul_f32_e32 v127, 0xbfb8aa3b, v127
	v_exp_f32_e32 v0, v0
	v_exp_f32_e32 v125, v125
	v_exp_f32_e32 v126, v126
	v_exp_f32_e32 v127, v127
	v_min_f32_e32 v0, 0x7149f2ca, v0
	v_min_f32_e32 v125, 0x7149f2ca, v125
	v_min_f32_e32 v126, 0x7149f2ca, v126
	v_min_f32_e32 v127, 0x7149f2ca, v127
	v_add_f32_e32 v0, 1.0, v0
	v_add_f32_e32 v125, 1.0, v125
	v_add_f32_e32 v128, 1.0, v126
	v_add_f32_e32 v129, 1.0, v127
	v_rcp_f32_e32 v126, v0
	v_rcp_f32_e32 v127, v125
	v_rcp_f32_e32 v128, v128
	v_rcp_f32_e32 v129, v129
	v_add_u32_e32 v0, v156, v124
	v_mul_f32_e32 v120, v120, v126
	v_mul_f32_e32 v121, v121, v127
	v_lshl_add_u64 v[130:131], v[0:1], 1, s[2:3]
	v_mul_f32_e32 v122, v122, v128
	v_mul_f32_e32 v123, v123, v129
	v_cvt_pk_bf16_f32 v120, v120, v121
	v_cvt_pk_bf16_f32 v121, v122, v123
	global_store_dwordx2 v[130:131], v[120:121], off
	s_nop 0
	v_or_b32_e32 v120, 0x90, v2
	v_or_b32_e32 v121, 16, v151
	s_waitcnt vmcnt(3)
	v_lshlrev_b32_e32 v0, 16, v202
	v_and_b32_e32 v122, 0xffff0000, v202
	v_lshlrev_b32_e32 v125, 16, v203
	v_and_b32_e32 v123, 0xffff0000, v203
	v_mul_f32_e32 v0, 0xbfb8aa3b, v0
	v_mul_f32_e32 v122, 0xbfb8aa3b, v122
	v_mul_f32_e32 v125, 0xbfb8aa3b, v125
	v_mul_f32_e32 v123, 0xbfb8aa3b, v123
	v_exp_f32_e32 v0, v0
	v_exp_f32_e32 v122, v122
	v_exp_f32_e32 v125, v125
	v_exp_f32_e32 v123, v123
	v_min_f32_e32 v0, 0x7149f2ca, v0
	v_min_f32_e32 v122, 0x7149f2ca, v122
	v_min_f32_e32 v125, 0x7149f2ca, v125
	v_min_f32_e32 v123, 0x7149f2ca, v123
	v_add_f32_e32 v0, 1.0, v0
	v_add_f32_e32 v126, 1.0, v122
	v_add_f32_e32 v125, 1.0, v125
	v_add_f32_e32 v127, 1.0, v123
	v_rcp_f32_e32 v122, v0
	v_rcp_f32_e32 v123, v126
	v_rcp_f32_e32 v126, v125
	v_rcp_f32_e32 v127, v127
	v_add_u32_e32 v0, v156, v120
	v_mul_f32_e32 v116, v116, v122
	v_mul_f32_e32 v117, v117, v123
	v_lshl_add_u64 v[128:129], v[0:1], 1, s[2:3]
	v_mul_f32_e32 v118, v118, v126
	v_mul_f32_e32 v119, v119, v127
	v_cvt_pk_bf16_f32 v116, v116, v117
	v_cvt_pk_bf16_f32 v117, v118, v119
	global_store_dwordx2 v[128:129], v[116:117], off
	s_nop 0
	v_mul_lo_u32 v0, v121, s13
	v_lshl_add_u64 v[116:117], v[0:1], 1, s[8:9]
	v_lshl_add_u64 v[116:117], v[116:117], 0, v[142:143]
	global_load_dwordx2 v[118:119], v[116:117], off
	global_load_dwordx2 v[198:199], v[116:117], off offset:32
	global_load_dwordx2 v[200:201], v[116:117], off offset:256
	global_load_dwordx2 v[202:203], v[116:117], off offset:288
	v_lshlrev_b32_e32 v121, 10, v121
	s_waitcnt vmcnt(3)
	v_lshlrev_b32_e32 v0, 16, v118
	v_and_b32_e32 v118, 0xffff0000, v118
	v_lshlrev_b32_e32 v122, 16, v119
	v_and_b32_e32 v119, 0xffff0000, v119
	v_mul_f32_e32 v0, 0xbfb8aa3b, v0
	v_mul_f32_e32 v118, 0xbfb8aa3b, v118
	v_mul_f32_e32 v122, 0xbfb8aa3b, v122
	v_mul_f32_e32 v119, 0xbfb8aa3b, v119
	v_exp_f32_e32 v0, v0
	v_exp_f32_e32 v118, v118
	v_exp_f32_e32 v122, v122
	v_exp_f32_e32 v119, v119
	v_min_f32_e32 v0, 0x7149f2ca, v0
	v_min_f32_e32 v118, 0x7149f2ca, v118
	v_min_f32_e32 v122, 0x7149f2ca, v122
	v_min_f32_e32 v119, 0x7149f2ca, v119
	v_add_f32_e32 v0, 1.0, v0
	v_add_f32_e32 v123, 1.0, v118
	v_add_f32_e32 v122, 1.0, v122
	v_add_f32_e32 v125, 1.0, v119
	v_rcp_f32_e32 v118, v0
	v_rcp_f32_e32 v119, v123
	v_rcp_f32_e32 v122, v122
	v_rcp_f32_e32 v123, v125
	v_add_u32_e32 v0, v121, v2
	v_mul_f32_e32 v112, v112, v118
	v_mul_f32_e32 v113, v113, v119
	v_lshl_add_u64 v[126:127], v[0:1], 1, s[2:3]
	v_mul_f32_e32 v114, v114, v122
	v_mul_f32_e32 v115, v115, v123
	v_cvt_pk_bf16_f32 v112, v112, v113
	v_cvt_pk_bf16_f32 v113, v114, v115
	global_store_dwordx2 v[126:127], v[112:113], off
	s_nop 0
	s_waitcnt vmcnt(3)
	v_lshlrev_b32_e32 v0, 16, v198
	v_and_b32_e32 v112, 0xffff0000, v198
	v_lshlrev_b32_e32 v114, 16, v199
	v_and_b32_e32 v113, 0xffff0000, v199
	v_mul_f32_e32 v0, 0xbfb8aa3b, v0
	v_mul_f32_e32 v112, 0xbfb8aa3b, v112
	v_mul_f32_e32 v114, 0xbfb8aa3b, v114
	v_mul_f32_e32 v113, 0xbfb8aa3b, v113
	v_exp_f32_e32 v0, v0
	v_exp_f32_e32 v112, v112
	v_exp_f32_e32 v114, v114
	v_exp_f32_e32 v113, v113
	v_min_f32_e32 v0, 0x7149f2ca, v0
	v_min_f32_e32 v112, 0x7149f2ca, v112
	v_min_f32_e32 v114, 0x7149f2ca, v114
	v_min_f32_e32 v113, 0x7149f2ca, v113
	v_add_f32_e32 v0, 1.0, v0
	v_add_f32_e32 v115, 1.0, v112
	v_add_f32_e32 v114, 1.0, v114
	v_add_f32_e32 v118, 1.0, v113
	v_rcp_f32_e32 v112, v0
	v_rcp_f32_e32 v113, v115
	v_rcp_f32_e32 v114, v114
	v_rcp_f32_e32 v115, v118
	v_add_u32_e32 v0, v121, v3
	v_mul_f32_e32 v108, v108, v112
	v_mul_f32_e32 v109, v109, v113
	v_lshl_add_u64 v[118:119], v[0:1], 1, s[2:3]
	v_mul_f32_e32 v110, v110, v114
	v_mul_f32_e32 v111, v111, v115
	v_cvt_pk_bf16_f32 v108, v108, v109
	v_cvt_pk_bf16_f32 v109, v110, v111
	global_store_dwordx2 v[118:119], v[108:109], off
	s_nop 0
	s_waitcnt vmcnt(3)
	v_lshlrev_b32_e32 v0, 16, v200
	v_and_b32_e32 v108, 0xffff0000, v200
	v_lshlrev_b32_e32 v110, 16, v201
	v_and_b32_e32 v109, 0xffff0000, v201
	v_mul_f32_e32 v0, 0xbfb8aa3b, v0
	v_mul_f32_e32 v108, 0xbfb8aa3b, v108
	v_mul_f32_e32 v110, 0xbfb8aa3b, v110
	v_mul_f32_e32 v109, 0xbfb8aa3b, v109
	v_exp_f32_e32 v0, v0
	v_exp_f32_e32 v108, v108
	v_exp_f32_e32 v110, v110
	v_exp_f32_e32 v109, v109
	v_min_f32_e32 v0, 0x7149f2ca, v0
	v_min_f32_e32 v108, 0x7149f2ca, v108
	v_min_f32_e32 v110, 0x7149f2ca, v110
	v_min_f32_e32 v109, 0x7149f2ca, v109
	v_add_f32_e32 v0, 1.0, v0
	v_add_f32_e32 v111, 1.0, v108
	v_add_f32_e32 v110, 1.0, v110
	v_add_f32_e32 v112, 1.0, v109
	v_rcp_f32_e32 v108, v0
	v_rcp_f32_e32 v109, v111
	v_rcp_f32_e32 v110, v110
	v_rcp_f32_e32 v111, v112
	v_add_u32_e32 v0, v121, v124
	v_mul_f32_e32 v104, v104, v108
	v_mul_f32_e32 v105, v105, v109
	v_lshl_add_u64 v[112:113], v[0:1], 1, s[2:3]
	v_mul_f32_e32 v106, v106, v110
	v_mul_f32_e32 v107, v107, v111
	v_cvt_pk_bf16_f32 v104, v104, v105
	v_cvt_pk_bf16_f32 v105, v106, v107
	global_store_dwordx2 v[112:113], v[104:105], off
	s_nop 0
	v_or_b32_e32 v110, 32, v151
	s_waitcnt vmcnt(3)
	v_lshlrev_b32_e32 v0, 16, v202
	v_and_b32_e32 v104, 0xffff0000, v202
	v_lshlrev_b32_e32 v106, 16, v203
	v_and_b32_e32 v105, 0xffff0000, v203
	v_mul_f32_e32 v0, 0xbfb8aa3b, v0
	v_mul_f32_e32 v104, 0xbfb8aa3b, v104
	v_mul_f32_e32 v106, 0xbfb8aa3b, v106
	v_mul_f32_e32 v105, 0xbfb8aa3b, v105
	v_exp_f32_e32 v0, v0
	v_exp_f32_e32 v104, v104
	v_exp_f32_e32 v106, v106
	v_exp_f32_e32 v105, v105
	v_min_f32_e32 v0, 0x7149f2ca, v0
	v_min_f32_e32 v104, 0x7149f2ca, v104
	v_min_f32_e32 v106, 0x7149f2ca, v106
	v_min_f32_e32 v105, 0x7149f2ca, v105
	v_add_f32_e32 v0, 1.0, v0
	v_add_f32_e32 v107, 1.0, v104
	v_add_f32_e32 v106, 1.0, v106
	v_add_f32_e32 v108, 1.0, v105
	v_rcp_f32_e32 v104, v0
	v_rcp_f32_e32 v105, v107
	v_rcp_f32_e32 v106, v106
	v_rcp_f32_e32 v107, v108
	v_add_u32_e32 v0, v121, v120
	v_mul_f32_e32 v100, v100, v104
	v_mul_f32_e32 v101, v101, v105
	v_lshl_add_u64 v[108:109], v[0:1], 1, s[2:3]
	v_mul_f32_e32 v102, v102, v106
	v_mul_f32_e32 v103, v103, v107
	v_cvt_pk_bf16_f32 v100, v100, v101
	v_cvt_pk_bf16_f32 v101, v102, v103
	global_store_dwordx2 v[108:109], v[100:101], off
	s_nop 0
	v_mul_lo_u32 v0, v110, s13
	v_lshl_add_u64 v[100:101], v[0:1], 1, s[8:9]
	v_lshl_add_u64 v[100:101], v[100:101], 0, v[142:143]
	global_load_dwordx2 v[102:103], v[100:101], off
	global_load_dwordx2 v[198:199], v[100:101], off offset:32
	global_load_dwordx2 v[200:201], v[100:101], off offset:256
	global_load_dwordx2 v[202:203], v[100:101], off offset:288
	v_lshlrev_b32_e32 v108, 10, v110
	s_waitcnt vmcnt(3)
	v_lshlrev_b32_e32 v0, 16, v102
	v_and_b32_e32 v102, 0xffff0000, v102
	v_lshlrev_b32_e32 v104, 16, v103
	v_and_b32_e32 v103, 0xffff0000, v103
	v_mul_f32_e32 v0, 0xbfb8aa3b, v0
	v_mul_f32_e32 v102, 0xbfb8aa3b, v102
	v_mul_f32_e32 v104, 0xbfb8aa3b, v104
	v_mul_f32_e32 v103, 0xbfb8aa3b, v103
	v_exp_f32_e32 v0, v0
	v_exp_f32_e32 v102, v102
	v_exp_f32_e32 v104, v104
	v_exp_f32_e32 v103, v103
	v_min_f32_e32 v0, 0x7149f2ca, v0
	v_min_f32_e32 v102, 0x7149f2ca, v102
	v_min_f32_e32 v104, 0x7149f2ca, v104
	v_min_f32_e32 v103, 0x7149f2ca, v103
	v_add_f32_e32 v0, 1.0, v0
	v_add_f32_e32 v105, 1.0, v102
	v_add_f32_e32 v104, 1.0, v104
	v_add_f32_e32 v106, 1.0, v103
	v_rcp_f32_e32 v102, v0
	v_rcp_f32_e32 v103, v105
	v_rcp_f32_e32 v104, v104
	v_rcp_f32_e32 v105, v106
	v_add_u32_e32 v0, v108, v2
	v_mul_f32_e32 v96, v96, v102
	v_mul_f32_e32 v97, v97, v103
	v_lshl_add_u64 v[106:107], v[0:1], 1, s[2:3]
	v_mul_f32_e32 v98, v98, v104
	v_mul_f32_e32 v99, v99, v105
	v_cvt_pk_bf16_f32 v96, v96, v97
	v_cvt_pk_bf16_f32 v97, v98, v99
	global_store_dwordx2 v[106:107], v[96:97], off
	s_nop 0
	s_waitcnt vmcnt(3)
	v_lshlrev_b32_e32 v0, 16, v198
	v_and_b32_e32 v96, 0xffff0000, v198
	v_lshlrev_b32_e32 v98, 16, v199
	v_and_b32_e32 v97, 0xffff0000, v199
	v_mul_f32_e32 v0, 0xbfb8aa3b, v0
	v_mul_f32_e32 v96, 0xbfb8aa3b, v96
	v_mul_f32_e32 v98, 0xbfb8aa3b, v98
	v_mul_f32_e32 v97, 0xbfb8aa3b, v97
	v_exp_f32_e32 v0, v0
	v_exp_f32_e32 v96, v96
	v_exp_f32_e32 v98, v98
	v_exp_f32_e32 v97, v97
	v_min_f32_e32 v0, 0x7149f2ca, v0
	v_min_f32_e32 v96, 0x7149f2ca, v96
	v_min_f32_e32 v98, 0x7149f2ca, v98
	v_min_f32_e32 v97, 0x7149f2ca, v97
	v_add_f32_e32 v0, 1.0, v0
	v_add_f32_e32 v99, 1.0, v96
	v_add_f32_e32 v98, 1.0, v98
	v_add_f32_e32 v102, 1.0, v97
	v_rcp_f32_e32 v96, v0
	v_rcp_f32_e32 v97, v99
	v_rcp_f32_e32 v98, v98
	v_rcp_f32_e32 v99, v102
	v_add_u32_e32 v0, v108, v3
	v_mul_f32_e32 v92, v92, v96
	v_mul_f32_e32 v93, v93, v97
	v_lshl_add_u64 v[102:103], v[0:1], 1, s[2:3]
	v_mul_f32_e32 v94, v94, v98
	v_mul_f32_e32 v95, v95, v99
	v_cvt_pk_bf16_f32 v92, v92, v93
	v_cvt_pk_bf16_f32 v93, v94, v95
	global_store_dwordx2 v[102:103], v[92:93], off
	s_nop 0
	s_waitcnt vmcnt(3)
	v_lshlrev_b32_e32 v0, 16, v200
	v_and_b32_e32 v92, 0xffff0000, v200
	v_lshlrev_b32_e32 v94, 16, v201
	v_and_b32_e32 v93, 0xffff0000, v201
	v_mul_f32_e32 v0, 0xbfb8aa3b, v0
	v_mul_f32_e32 v92, 0xbfb8aa3b, v92
	v_mul_f32_e32 v94, 0xbfb8aa3b, v94
	v_mul_f32_e32 v93, 0xbfb8aa3b, v93
	v_exp_f32_e32 v0, v0
	v_exp_f32_e32 v92, v92
	v_exp_f32_e32 v94, v94
	v_exp_f32_e32 v93, v93
	v_min_f32_e32 v0, 0x7149f2ca, v0
	v_min_f32_e32 v92, 0x7149f2ca, v92
	v_min_f32_e32 v94, 0x7149f2ca, v94
	v_min_f32_e32 v93, 0x7149f2ca, v93
	v_add_f32_e32 v0, 1.0, v0
	v_add_f32_e32 v95, 1.0, v92
	v_add_f32_e32 v94, 1.0, v94
	v_add_f32_e32 v96, 1.0, v93
	v_rcp_f32_e32 v92, v0
	v_rcp_f32_e32 v93, v95
	v_rcp_f32_e32 v94, v94
	v_rcp_f32_e32 v95, v96
	v_add_u32_e32 v0, v108, v124
	v_mul_f32_e32 v88, v88, v92
	v_mul_f32_e32 v89, v89, v93
	v_lshl_add_u64 v[96:97], v[0:1], 1, s[2:3]
	v_mul_f32_e32 v90, v90, v94
	v_mul_f32_e32 v91, v91, v95
	v_cvt_pk_bf16_f32 v88, v88, v89
	v_cvt_pk_bf16_f32 v89, v90, v91
	global_store_dwordx2 v[96:97], v[88:89], off
	s_nop 0
	v_or_b32_e32 v94, 48, v151
	s_waitcnt vmcnt(3)
	v_lshlrev_b32_e32 v0, 16, v202
	v_and_b32_e32 v88, 0xffff0000, v202
	v_lshlrev_b32_e32 v90, 16, v203
	v_and_b32_e32 v89, 0xffff0000, v203
	v_mul_f32_e32 v0, 0xbfb8aa3b, v0
	v_mul_f32_e32 v88, 0xbfb8aa3b, v88
	v_mul_f32_e32 v90, 0xbfb8aa3b, v90
	v_mul_f32_e32 v89, 0xbfb8aa3b, v89
	v_exp_f32_e32 v0, v0
	v_exp_f32_e32 v88, v88
	v_exp_f32_e32 v90, v90
	v_exp_f32_e32 v89, v89
	v_min_f32_e32 v0, 0x7149f2ca, v0
	v_min_f32_e32 v88, 0x7149f2ca, v88
	v_min_f32_e32 v90, 0x7149f2ca, v90
	v_min_f32_e32 v89, 0x7149f2ca, v89
	v_add_f32_e32 v0, 1.0, v0
	v_add_f32_e32 v91, 1.0, v88
	v_add_f32_e32 v90, 1.0, v90
	v_add_f32_e32 v92, 1.0, v89
	v_rcp_f32_e32 v88, v0
	v_rcp_f32_e32 v89, v91
	v_rcp_f32_e32 v90, v90
	v_rcp_f32_e32 v91, v92
	v_add_u32_e32 v0, v108, v120
	v_mul_f32_e32 v84, v84, v88
	v_mul_f32_e32 v85, v85, v89
	v_lshl_add_u64 v[92:93], v[0:1], 1, s[2:3]
	v_mul_f32_e32 v86, v86, v90
	v_mul_f32_e32 v87, v87, v91
	v_cvt_pk_bf16_f32 v84, v84, v85
	v_cvt_pk_bf16_f32 v85, v86, v87
	global_store_dwordx2 v[92:93], v[84:85], off
	s_nop 0
	v_mul_lo_u32 v0, v94, s13
	v_lshl_add_u64 v[84:85], v[0:1], 1, s[8:9]
	v_lshl_add_u64 v[84:85], v[84:85], 0, v[142:143]
	global_load_dwordx2 v[86:87], v[84:85], off
	global_load_dwordx2 v[198:199], v[84:85], off offset:32
	global_load_dwordx2 v[200:201], v[84:85], off offset:256
	global_load_dwordx2 v[202:203], v[84:85], off offset:288
	v_lshlrev_b32_e32 v92, 10, v94
	s_waitcnt vmcnt(3)
	v_lshlrev_b32_e32 v0, 16, v86
	v_and_b32_e32 v86, 0xffff0000, v86
	v_lshlrev_b32_e32 v88, 16, v87
	v_and_b32_e32 v87, 0xffff0000, v87
	v_mul_f32_e32 v0, 0xbfb8aa3b, v0
	v_mul_f32_e32 v86, 0xbfb8aa3b, v86
	v_mul_f32_e32 v88, 0xbfb8aa3b, v88
	v_mul_f32_e32 v87, 0xbfb8aa3b, v87
	v_exp_f32_e32 v0, v0
	v_exp_f32_e32 v86, v86
	v_exp_f32_e32 v88, v88
	v_exp_f32_e32 v87, v87
	v_min_f32_e32 v0, 0x7149f2ca, v0
	v_min_f32_e32 v86, 0x7149f2ca, v86
	v_min_f32_e32 v88, 0x7149f2ca, v88
	v_min_f32_e32 v87, 0x7149f2ca, v87
	v_add_f32_e32 v0, 1.0, v0
	v_add_f32_e32 v89, 1.0, v86
	v_add_f32_e32 v88, 1.0, v88
	v_add_f32_e32 v90, 1.0, v87
	v_rcp_f32_e32 v86, v0
	v_rcp_f32_e32 v87, v89
	v_rcp_f32_e32 v88, v88
	v_rcp_f32_e32 v89, v90
	v_add_u32_e32 v0, v92, v2
	v_mul_f32_e32 v80, v80, v86
	v_mul_f32_e32 v81, v81, v87
	v_lshl_add_u64 v[90:91], v[0:1], 1, s[2:3]
	v_mul_f32_e32 v82, v82, v88
	v_mul_f32_e32 v83, v83, v89
	v_cvt_pk_bf16_f32 v80, v80, v81
	v_cvt_pk_bf16_f32 v81, v82, v83
	global_store_dwordx2 v[90:91], v[80:81], off
	s_nop 0
	s_waitcnt vmcnt(3)
	v_lshlrev_b32_e32 v0, 16, v198
	v_and_b32_e32 v80, 0xffff0000, v198
	v_lshlrev_b32_e32 v82, 16, v199
	v_and_b32_e32 v81, 0xffff0000, v199
	v_mul_f32_e32 v0, 0xbfb8aa3b, v0
	v_mul_f32_e32 v80, 0xbfb8aa3b, v80
	v_mul_f32_e32 v82, 0xbfb8aa3b, v82
	v_mul_f32_e32 v81, 0xbfb8aa3b, v81
	v_exp_f32_e32 v0, v0
	v_exp_f32_e32 v80, v80
	v_exp_f32_e32 v82, v82
	v_exp_f32_e32 v81, v81
	v_min_f32_e32 v0, 0x7149f2ca, v0
	v_min_f32_e32 v80, 0x7149f2ca, v80
	v_min_f32_e32 v82, 0x7149f2ca, v82
	v_min_f32_e32 v81, 0x7149f2ca, v81
	v_add_f32_e32 v0, 1.0, v0
	v_add_f32_e32 v83, 1.0, v80
	v_add_f32_e32 v82, 1.0, v82
	v_add_f32_e32 v86, 1.0, v81
	v_rcp_f32_e32 v80, v0
	v_rcp_f32_e32 v81, v83
	v_rcp_f32_e32 v82, v82
	v_rcp_f32_e32 v83, v86
	v_add_u32_e32 v0, v92, v3
	v_mul_f32_e32 v76, v76, v80
	v_mul_f32_e32 v77, v77, v81
	v_lshl_add_u64 v[86:87], v[0:1], 1, s[2:3]
	v_mul_f32_e32 v78, v78, v82
	v_mul_f32_e32 v79, v79, v83
	v_cvt_pk_bf16_f32 v76, v76, v77
	v_cvt_pk_bf16_f32 v77, v78, v79
	global_store_dwordx2 v[86:87], v[76:77], off
	s_nop 0
	s_waitcnt vmcnt(3)
	v_lshlrev_b32_e32 v0, 16, v200
	v_and_b32_e32 v76, 0xffff0000, v200
	v_lshlrev_b32_e32 v78, 16, v201
	v_and_b32_e32 v77, 0xffff0000, v201
	v_mul_f32_e32 v0, 0xbfb8aa3b, v0
	v_mul_f32_e32 v76, 0xbfb8aa3b, v76
	v_mul_f32_e32 v78, 0xbfb8aa3b, v78
	v_mul_f32_e32 v77, 0xbfb8aa3b, v77
	v_exp_f32_e32 v0, v0
	v_exp_f32_e32 v76, v76
	v_exp_f32_e32 v78, v78
	v_exp_f32_e32 v77, v77
	v_min_f32_e32 v0, 0x7149f2ca, v0
	v_min_f32_e32 v76, 0x7149f2ca, v76
	v_min_f32_e32 v78, 0x7149f2ca, v78
	v_min_f32_e32 v77, 0x7149f2ca, v77
	v_add_f32_e32 v0, 1.0, v0
	v_add_f32_e32 v79, 1.0, v76
	v_add_f32_e32 v78, 1.0, v78
	v_add_f32_e32 v80, 1.0, v77
	v_rcp_f32_e32 v76, v0
	v_rcp_f32_e32 v77, v79
	v_rcp_f32_e32 v78, v78
	v_rcp_f32_e32 v79, v80
	v_add_u32_e32 v0, v92, v124
	v_mul_f32_e32 v72, v72, v76
	v_mul_f32_e32 v73, v73, v77
	v_lshl_add_u64 v[80:81], v[0:1], 1, s[2:3]
	v_mul_f32_e32 v74, v74, v78
	v_mul_f32_e32 v75, v75, v79
	v_cvt_pk_bf16_f32 v72, v72, v73
	v_cvt_pk_bf16_f32 v73, v74, v75
	global_store_dwordx2 v[80:81], v[72:73], off
	s_nop 0
	v_add_u32_e32 v78, 0x80, v151
	s_waitcnt vmcnt(3)
	v_lshlrev_b32_e32 v0, 16, v202
	v_and_b32_e32 v72, 0xffff0000, v202
	v_lshlrev_b32_e32 v74, 16, v203
	v_and_b32_e32 v73, 0xffff0000, v203
	v_mul_f32_e32 v0, 0xbfb8aa3b, v0
	v_mul_f32_e32 v72, 0xbfb8aa3b, v72
	v_mul_f32_e32 v74, 0xbfb8aa3b, v74
	v_mul_f32_e32 v73, 0xbfb8aa3b, v73
	v_exp_f32_e32 v0, v0
	v_exp_f32_e32 v72, v72
	v_exp_f32_e32 v74, v74
	v_exp_f32_e32 v73, v73
	v_min_f32_e32 v0, 0x7149f2ca, v0
	v_min_f32_e32 v72, 0x7149f2ca, v72
	v_min_f32_e32 v74, 0x7149f2ca, v74
	v_min_f32_e32 v73, 0x7149f2ca, v73
	v_add_f32_e32 v0, 1.0, v0
	v_add_f32_e32 v75, 1.0, v72
	v_add_f32_e32 v74, 1.0, v74
	v_add_f32_e32 v76, 1.0, v73
	v_rcp_f32_e32 v72, v0
	v_rcp_f32_e32 v73, v75
	v_rcp_f32_e32 v74, v74
	v_rcp_f32_e32 v75, v76
	v_add_u32_e32 v0, v92, v120
	v_mul_f32_e32 v68, v68, v72
	v_mul_f32_e32 v69, v69, v73
	v_lshl_add_u64 v[76:77], v[0:1], 1, s[2:3]
	v_mul_f32_e32 v70, v70, v74
	v_mul_f32_e32 v71, v71, v75
	v_cvt_pk_bf16_f32 v68, v68, v69
	v_cvt_pk_bf16_f32 v69, v70, v71
	global_store_dwordx2 v[76:77], v[68:69], off
	s_nop 0
	v_mul_lo_u32 v0, v78, s13
	v_lshl_add_u64 v[68:69], v[0:1], 1, s[8:9]
	v_lshl_add_u64 v[68:69], v[68:69], 0, v[142:143]
	global_load_dwordx2 v[70:71], v[68:69], off
	global_load_dwordx2 v[198:199], v[68:69], off offset:32
	global_load_dwordx2 v[200:201], v[68:69], off offset:256
	global_load_dwordx2 v[202:203], v[68:69], off offset:288
	v_lshlrev_b32_e32 v76, 10, v78
	s_waitcnt vmcnt(3)
	v_lshlrev_b32_e32 v0, 16, v70
	v_and_b32_e32 v70, 0xffff0000, v70
	v_lshlrev_b32_e32 v72, 16, v71
	v_and_b32_e32 v71, 0xffff0000, v71
	v_mul_f32_e32 v0, 0xbfb8aa3b, v0
	v_mul_f32_e32 v70, 0xbfb8aa3b, v70
	v_mul_f32_e32 v72, 0xbfb8aa3b, v72
	v_mul_f32_e32 v71, 0xbfb8aa3b, v71
	v_exp_f32_e32 v0, v0
	v_exp_f32_e32 v70, v70
	v_exp_f32_e32 v72, v72
	v_exp_f32_e32 v71, v71
	v_min_f32_e32 v0, 0x7149f2ca, v0
	v_min_f32_e32 v70, 0x7149f2ca, v70
	v_min_f32_e32 v72, 0x7149f2ca, v72
	v_min_f32_e32 v71, 0x7149f2ca, v71
	v_add_f32_e32 v0, 1.0, v0
	v_add_f32_e32 v73, 1.0, v70
	v_add_f32_e32 v72, 1.0, v72
	v_add_f32_e32 v74, 1.0, v71
	v_rcp_f32_e32 v70, v0
	v_rcp_f32_e32 v71, v73
	v_rcp_f32_e32 v72, v72
	v_rcp_f32_e32 v73, v74
	v_add_u32_e32 v0, v76, v2
	v_mul_f32_e32 v64, v64, v70
	v_mul_f32_e32 v65, v65, v71
	v_lshl_add_u64 v[74:75], v[0:1], 1, s[2:3]
	v_mul_f32_e32 v66, v66, v72
	v_mul_f32_e32 v67, v67, v73
	v_cvt_pk_bf16_f32 v64, v64, v65
	v_cvt_pk_bf16_f32 v65, v66, v67
	global_store_dwordx2 v[74:75], v[64:65], off
	s_nop 0
	s_waitcnt vmcnt(3)
	v_lshlrev_b32_e32 v0, 16, v198
	v_and_b32_e32 v64, 0xffff0000, v198
	v_lshlrev_b32_e32 v66, 16, v199
	v_and_b32_e32 v65, 0xffff0000, v199
	v_mul_f32_e32 v0, 0xbfb8aa3b, v0
	v_mul_f32_e32 v64, 0xbfb8aa3b, v64
	v_mul_f32_e32 v66, 0xbfb8aa3b, v66
	v_mul_f32_e32 v65, 0xbfb8aa3b, v65
	v_exp_f32_e32 v0, v0
	v_exp_f32_e32 v64, v64
	v_exp_f32_e32 v66, v66
	v_exp_f32_e32 v65, v65
	v_min_f32_e32 v0, 0x7149f2ca, v0
	v_min_f32_e32 v64, 0x7149f2ca, v64
	v_min_f32_e32 v66, 0x7149f2ca, v66
	v_min_f32_e32 v65, 0x7149f2ca, v65
	v_add_f32_e32 v0, 1.0, v0
	v_add_f32_e32 v67, 1.0, v64
	v_add_f32_e32 v66, 1.0, v66
	v_add_f32_e32 v70, 1.0, v65
	v_rcp_f32_e32 v64, v0
	v_rcp_f32_e32 v65, v67
	v_rcp_f32_e32 v66, v66
	v_rcp_f32_e32 v67, v70
	v_add_u32_e32 v0, v76, v3
	v_mul_f32_e32 v60, v60, v64
	v_mul_f32_e32 v61, v61, v65
	v_lshl_add_u64 v[70:71], v[0:1], 1, s[2:3]
	v_mul_f32_e32 v62, v62, v66
	v_mul_f32_e32 v63, v63, v67
	v_cvt_pk_bf16_f32 v60, v60, v61
	v_cvt_pk_bf16_f32 v61, v62, v63
	global_store_dwordx2 v[70:71], v[60:61], off
	s_nop 0
	s_waitcnt vmcnt(3)
	v_lshlrev_b32_e32 v0, 16, v200
	v_and_b32_e32 v60, 0xffff0000, v200
	v_lshlrev_b32_e32 v62, 16, v201
	v_and_b32_e32 v61, 0xffff0000, v201
	v_mul_f32_e32 v0, 0xbfb8aa3b, v0
	v_mul_f32_e32 v60, 0xbfb8aa3b, v60
	v_mul_f32_e32 v62, 0xbfb8aa3b, v62
	v_mul_f32_e32 v61, 0xbfb8aa3b, v61
	v_exp_f32_e32 v0, v0
	v_exp_f32_e32 v60, v60
	v_exp_f32_e32 v62, v62
	v_exp_f32_e32 v61, v61
	v_min_f32_e32 v0, 0x7149f2ca, v0
	v_min_f32_e32 v60, 0x7149f2ca, v60
	v_min_f32_e32 v62, 0x7149f2ca, v62
	v_min_f32_e32 v61, 0x7149f2ca, v61
	v_add_f32_e32 v0, 1.0, v0
	v_add_f32_e32 v63, 1.0, v60
	v_add_f32_e32 v62, 1.0, v62
	v_add_f32_e32 v64, 1.0, v61
	v_rcp_f32_e32 v60, v0
	v_rcp_f32_e32 v61, v63
	v_rcp_f32_e32 v62, v62
	v_rcp_f32_e32 v63, v64
	v_add_u32_e32 v0, v76, v124
	v_mul_f32_e32 v56, v56, v60
	v_mul_f32_e32 v57, v57, v61
	v_lshl_add_u64 v[64:65], v[0:1], 1, s[2:3]
	v_mul_f32_e32 v58, v58, v62
	v_mul_f32_e32 v59, v59, v63
	v_cvt_pk_bf16_f32 v56, v56, v57
	v_cvt_pk_bf16_f32 v57, v58, v59
	global_store_dwordx2 v[64:65], v[56:57], off
	s_nop 0
	v_add_u32_e32 v62, 0x90, v151
	s_waitcnt vmcnt(3)
	v_lshlrev_b32_e32 v0, 16, v202
	v_and_b32_e32 v56, 0xffff0000, v202
	v_lshlrev_b32_e32 v58, 16, v203
	v_and_b32_e32 v57, 0xffff0000, v203
	v_mul_f32_e32 v0, 0xbfb8aa3b, v0
	v_mul_f32_e32 v56, 0xbfb8aa3b, v56
	v_mul_f32_e32 v58, 0xbfb8aa3b, v58
	v_mul_f32_e32 v57, 0xbfb8aa3b, v57
	v_exp_f32_e32 v0, v0
	v_exp_f32_e32 v56, v56
	v_exp_f32_e32 v58, v58
	v_exp_f32_e32 v57, v57
	v_min_f32_e32 v0, 0x7149f2ca, v0
	v_min_f32_e32 v56, 0x7149f2ca, v56
	v_min_f32_e32 v58, 0x7149f2ca, v58
	v_min_f32_e32 v57, 0x7149f2ca, v57
	v_add_f32_e32 v0, 1.0, v0
	v_add_f32_e32 v59, 1.0, v56
	v_add_f32_e32 v58, 1.0, v58
	v_add_f32_e32 v60, 1.0, v57
	v_rcp_f32_e32 v56, v0
	v_rcp_f32_e32 v57, v59
	v_rcp_f32_e32 v58, v58
	v_rcp_f32_e32 v59, v60
	v_add_u32_e32 v0, v76, v120
	v_mul_f32_e32 v52, v52, v56
	v_mul_f32_e32 v53, v53, v57
	v_lshl_add_u64 v[60:61], v[0:1], 1, s[2:3]
	v_mul_f32_e32 v54, v54, v58
	v_mul_f32_e32 v55, v55, v59
	v_cvt_pk_bf16_f32 v52, v52, v53
	v_cvt_pk_bf16_f32 v53, v54, v55
	global_store_dwordx2 v[60:61], v[52:53], off
	s_nop 0
	v_mul_lo_u32 v0, v62, s13
	v_lshl_add_u64 v[52:53], v[0:1], 1, s[8:9]
	v_lshl_add_u64 v[52:53], v[52:53], 0, v[142:143]
	global_load_dwordx2 v[54:55], v[52:53], off
	global_load_dwordx2 v[198:199], v[52:53], off offset:32
	global_load_dwordx2 v[200:201], v[52:53], off offset:256
	global_load_dwordx2 v[202:203], v[52:53], off offset:288
	v_lshlrev_b32_e32 v60, 10, v62
	s_waitcnt vmcnt(3)
	v_lshlrev_b32_e32 v0, 16, v54
	v_and_b32_e32 v54, 0xffff0000, v54
	v_lshlrev_b32_e32 v56, 16, v55
	v_and_b32_e32 v55, 0xffff0000, v55
	v_mul_f32_e32 v0, 0xbfb8aa3b, v0
	v_mul_f32_e32 v54, 0xbfb8aa3b, v54
	v_mul_f32_e32 v56, 0xbfb8aa3b, v56
	v_mul_f32_e32 v55, 0xbfb8aa3b, v55
	v_exp_f32_e32 v0, v0
	v_exp_f32_e32 v54, v54
	v_exp_f32_e32 v56, v56
	v_exp_f32_e32 v55, v55
	v_min_f32_e32 v0, 0x7149f2ca, v0
	v_min_f32_e32 v54, 0x7149f2ca, v54
	v_min_f32_e32 v56, 0x7149f2ca, v56
	v_min_f32_e32 v55, 0x7149f2ca, v55
	v_add_f32_e32 v0, 1.0, v0
	v_add_f32_e32 v57, 1.0, v54
	v_add_f32_e32 v56, 1.0, v56
	v_add_f32_e32 v58, 1.0, v55
	v_rcp_f32_e32 v54, v0
	v_rcp_f32_e32 v55, v57
	v_rcp_f32_e32 v56, v56
	v_rcp_f32_e32 v57, v58
	v_add_u32_e32 v0, v60, v2
	v_mul_f32_e32 v48, v48, v54
	v_mul_f32_e32 v49, v49, v55
	v_lshl_add_u64 v[58:59], v[0:1], 1, s[2:3]
	v_mul_f32_e32 v50, v50, v56
	v_mul_f32_e32 v51, v51, v57
	v_cvt_pk_bf16_f32 v48, v48, v49
	v_cvt_pk_bf16_f32 v49, v50, v51
	global_store_dwordx2 v[58:59], v[48:49], off
	s_nop 0
	s_waitcnt vmcnt(3)
	v_lshlrev_b32_e32 v0, 16, v198
	v_and_b32_e32 v48, 0xffff0000, v198
	v_lshlrev_b32_e32 v50, 16, v199
	v_and_b32_e32 v49, 0xffff0000, v199
	v_mul_f32_e32 v0, 0xbfb8aa3b, v0
	v_mul_f32_e32 v48, 0xbfb8aa3b, v48
	v_mul_f32_e32 v50, 0xbfb8aa3b, v50
	v_mul_f32_e32 v49, 0xbfb8aa3b, v49
	v_exp_f32_e32 v0, v0
	v_exp_f32_e32 v48, v48
	v_exp_f32_e32 v50, v50
	v_exp_f32_e32 v49, v49
	v_min_f32_e32 v0, 0x7149f2ca, v0
	v_min_f32_e32 v48, 0x7149f2ca, v48
	v_min_f32_e32 v50, 0x7149f2ca, v50
	v_min_f32_e32 v49, 0x7149f2ca, v49
	v_add_f32_e32 v0, 1.0, v0
	v_add_f32_e32 v51, 1.0, v48
	v_add_f32_e32 v50, 1.0, v50
	v_add_f32_e32 v54, 1.0, v49
	v_rcp_f32_e32 v48, v0
	v_rcp_f32_e32 v49, v51
	v_rcp_f32_e32 v50, v50
	v_rcp_f32_e32 v51, v54
	v_add_u32_e32 v0, v60, v3
	v_mul_f32_e32 v44, v44, v48
	v_mul_f32_e32 v45, v45, v49
	v_lshl_add_u64 v[54:55], v[0:1], 1, s[2:3]
	v_mul_f32_e32 v46, v46, v50
	v_mul_f32_e32 v47, v47, v51
	v_cvt_pk_bf16_f32 v44, v44, v45
	v_cvt_pk_bf16_f32 v45, v46, v47
	global_store_dwordx2 v[54:55], v[44:45], off
	s_nop 0
	s_waitcnt vmcnt(3)
	v_lshlrev_b32_e32 v0, 16, v200
	v_and_b32_e32 v44, 0xffff0000, v200
	v_lshlrev_b32_e32 v46, 16, v201
	v_and_b32_e32 v45, 0xffff0000, v201
	v_mul_f32_e32 v0, 0xbfb8aa3b, v0
	v_mul_f32_e32 v44, 0xbfb8aa3b, v44
	v_mul_f32_e32 v46, 0xbfb8aa3b, v46
	v_mul_f32_e32 v45, 0xbfb8aa3b, v45
	v_exp_f32_e32 v0, v0
	v_exp_f32_e32 v44, v44
	v_exp_f32_e32 v46, v46
	v_exp_f32_e32 v45, v45
	v_min_f32_e32 v0, 0x7149f2ca, v0
	v_min_f32_e32 v44, 0x7149f2ca, v44
	v_min_f32_e32 v46, 0x7149f2ca, v46
	v_min_f32_e32 v45, 0x7149f2ca, v45
	v_add_f32_e32 v0, 1.0, v0
	v_add_f32_e32 v47, 1.0, v44
	v_add_f32_e32 v46, 1.0, v46
	v_add_f32_e32 v48, 1.0, v45
	v_rcp_f32_e32 v44, v0
	v_rcp_f32_e32 v45, v47
	v_rcp_f32_e32 v46, v46
	v_rcp_f32_e32 v47, v48
	v_add_u32_e32 v0, v60, v124
	v_mul_f32_e32 v40, v40, v44
	v_mul_f32_e32 v41, v41, v45
	v_lshl_add_u64 v[48:49], v[0:1], 1, s[2:3]
	v_mul_f32_e32 v42, v42, v46
	v_mul_f32_e32 v43, v43, v47
	v_cvt_pk_bf16_f32 v40, v40, v41
	v_cvt_pk_bf16_f32 v41, v42, v43
	global_store_dwordx2 v[48:49], v[40:41], off
	s_nop 0
	v_add_u32_e32 v46, 0xa0, v151
	s_waitcnt vmcnt(3)
	v_lshlrev_b32_e32 v0, 16, v202
	v_and_b32_e32 v40, 0xffff0000, v202
	v_lshlrev_b32_e32 v42, 16, v203
	v_and_b32_e32 v41, 0xffff0000, v203
	v_mul_f32_e32 v0, 0xbfb8aa3b, v0
	v_mul_f32_e32 v40, 0xbfb8aa3b, v40
	v_mul_f32_e32 v42, 0xbfb8aa3b, v42
	v_mul_f32_e32 v41, 0xbfb8aa3b, v41
	v_exp_f32_e32 v0, v0
	v_exp_f32_e32 v40, v40
	v_exp_f32_e32 v42, v42
	v_exp_f32_e32 v41, v41
	v_min_f32_e32 v0, 0x7149f2ca, v0
	v_min_f32_e32 v40, 0x7149f2ca, v40
	v_min_f32_e32 v42, 0x7149f2ca, v42
	v_min_f32_e32 v41, 0x7149f2ca, v41
	v_add_f32_e32 v0, 1.0, v0
	v_add_f32_e32 v43, 1.0, v40
	v_add_f32_e32 v42, 1.0, v42
	v_add_f32_e32 v44, 1.0, v41
	v_rcp_f32_e32 v40, v0
	v_rcp_f32_e32 v41, v43
	v_rcp_f32_e32 v42, v42
	v_rcp_f32_e32 v43, v44
	v_add_u32_e32 v0, v60, v120
	v_mul_f32_e32 v36, v36, v40
	v_mul_f32_e32 v37, v37, v41
	v_lshl_add_u64 v[44:45], v[0:1], 1, s[2:3]
	v_mul_f32_e32 v38, v38, v42
	v_mul_f32_e32 v39, v39, v43
	v_cvt_pk_bf16_f32 v36, v36, v37
	v_cvt_pk_bf16_f32 v37, v38, v39
	global_store_dwordx2 v[44:45], v[36:37], off
	s_nop 0
	v_mul_lo_u32 v0, v46, s13
	v_lshl_add_u64 v[36:37], v[0:1], 1, s[8:9]
	v_lshl_add_u64 v[36:37], v[36:37], 0, v[142:143]
	global_load_dwordx2 v[38:39], v[36:37], off
	global_load_dwordx2 v[198:199], v[36:37], off offset:32
	global_load_dwordx2 v[200:201], v[36:37], off offset:256
	global_load_dwordx2 v[202:203], v[36:37], off offset:288
	v_lshlrev_b32_e32 v44, 10, v46
	s_waitcnt vmcnt(3)
	v_lshlrev_b32_e32 v0, 16, v38
	v_and_b32_e32 v38, 0xffff0000, v38
	v_lshlrev_b32_e32 v40, 16, v39
	v_and_b32_e32 v39, 0xffff0000, v39
	v_mul_f32_e32 v0, 0xbfb8aa3b, v0
	v_mul_f32_e32 v38, 0xbfb8aa3b, v38
	v_mul_f32_e32 v40, 0xbfb8aa3b, v40
	v_mul_f32_e32 v39, 0xbfb8aa3b, v39
	v_exp_f32_e32 v0, v0
	v_exp_f32_e32 v38, v38
	v_exp_f32_e32 v40, v40
	v_exp_f32_e32 v39, v39
	v_min_f32_e32 v0, 0x7149f2ca, v0
	v_min_f32_e32 v38, 0x7149f2ca, v38
	v_min_f32_e32 v40, 0x7149f2ca, v40
	v_min_f32_e32 v39, 0x7149f2ca, v39
	v_add_f32_e32 v0, 1.0, v0
	v_add_f32_e32 v41, 1.0, v38
	v_add_f32_e32 v40, 1.0, v40
	v_add_f32_e32 v42, 1.0, v39
	v_rcp_f32_e32 v38, v0
	v_rcp_f32_e32 v39, v41
	v_rcp_f32_e32 v40, v40
	v_rcp_f32_e32 v41, v42
	v_add_u32_e32 v0, v44, v2
	v_mul_f32_e32 v32, v32, v38
	v_mul_f32_e32 v33, v33, v39
	v_lshl_add_u64 v[42:43], v[0:1], 1, s[2:3]
	v_mul_f32_e32 v34, v34, v40
	v_mul_f32_e32 v35, v35, v41
	v_cvt_pk_bf16_f32 v32, v32, v33
	v_cvt_pk_bf16_f32 v33, v34, v35
	global_store_dwordx2 v[42:43], v[32:33], off
	s_nop 0
	s_waitcnt vmcnt(3)
	v_lshlrev_b32_e32 v0, 16, v198
	v_and_b32_e32 v32, 0xffff0000, v198
	v_lshlrev_b32_e32 v34, 16, v199
	v_and_b32_e32 v33, 0xffff0000, v199
	v_mul_f32_e32 v0, 0xbfb8aa3b, v0
	v_mul_f32_e32 v32, 0xbfb8aa3b, v32
	v_mul_f32_e32 v34, 0xbfb8aa3b, v34
	v_mul_f32_e32 v33, 0xbfb8aa3b, v33
	v_exp_f32_e32 v0, v0
	v_exp_f32_e32 v32, v32
	v_exp_f32_e32 v34, v34
	v_exp_f32_e32 v33, v33
	v_min_f32_e32 v0, 0x7149f2ca, v0
	v_min_f32_e32 v32, 0x7149f2ca, v32
	v_min_f32_e32 v34, 0x7149f2ca, v34
	v_min_f32_e32 v33, 0x7149f2ca, v33
	v_add_f32_e32 v0, 1.0, v0
	v_add_f32_e32 v35, 1.0, v32
	v_add_f32_e32 v34, 1.0, v34
	v_add_f32_e32 v38, 1.0, v33
	v_rcp_f32_e32 v32, v0
	v_rcp_f32_e32 v33, v35
	v_rcp_f32_e32 v34, v34
	v_rcp_f32_e32 v35, v38
	v_add_u32_e32 v0, v44, v3
	v_mul_f32_e32 v28, v28, v32
	v_mul_f32_e32 v29, v29, v33
	v_lshl_add_u64 v[38:39], v[0:1], 1, s[2:3]
	v_mul_f32_e32 v30, v30, v34
	v_mul_f32_e32 v31, v31, v35
	v_cvt_pk_bf16_f32 v28, v28, v29
	v_cvt_pk_bf16_f32 v29, v30, v31
	global_store_dwordx2 v[38:39], v[28:29], off
	s_nop 0
	s_waitcnt vmcnt(3)
	v_lshlrev_b32_e32 v0, 16, v200
	v_and_b32_e32 v28, 0xffff0000, v200
	v_lshlrev_b32_e32 v30, 16, v201
	v_and_b32_e32 v29, 0xffff0000, v201
	v_mul_f32_e32 v0, 0xbfb8aa3b, v0
	v_mul_f32_e32 v28, 0xbfb8aa3b, v28
	v_mul_f32_e32 v30, 0xbfb8aa3b, v30
	v_mul_f32_e32 v29, 0xbfb8aa3b, v29
	v_exp_f32_e32 v0, v0
	v_exp_f32_e32 v28, v28
	v_exp_f32_e32 v30, v30
	v_exp_f32_e32 v29, v29
	v_min_f32_e32 v0, 0x7149f2ca, v0
	v_min_f32_e32 v28, 0x7149f2ca, v28
	v_min_f32_e32 v30, 0x7149f2ca, v30
	v_min_f32_e32 v29, 0x7149f2ca, v29
	v_add_f32_e32 v0, 1.0, v0
	v_add_f32_e32 v31, 1.0, v28
	v_add_f32_e32 v30, 1.0, v30
	v_add_f32_e32 v32, 1.0, v29
	v_rcp_f32_e32 v28, v0
	v_rcp_f32_e32 v29, v31
	v_rcp_f32_e32 v30, v30
	v_rcp_f32_e32 v31, v32
	v_add_u32_e32 v0, v44, v124
	v_mul_f32_e32 v24, v24, v28
	v_mul_f32_e32 v25, v25, v29
	v_lshl_add_u64 v[32:33], v[0:1], 1, s[2:3]
	v_mul_f32_e32 v26, v26, v30
	v_mul_f32_e32 v27, v27, v31
	v_cvt_pk_bf16_f32 v24, v24, v25
	v_cvt_pk_bf16_f32 v25, v26, v27
	global_store_dwordx2 v[32:33], v[24:25], off
	s_nop 0
	v_add_u32_e32 v30, 0xb0, v151
	s_waitcnt vmcnt(3)
	v_lshlrev_b32_e32 v0, 16, v202
	v_and_b32_e32 v24, 0xffff0000, v202
	v_lshlrev_b32_e32 v26, 16, v203
	v_and_b32_e32 v25, 0xffff0000, v203
	v_mul_f32_e32 v0, 0xbfb8aa3b, v0
	v_mul_f32_e32 v24, 0xbfb8aa3b, v24
	v_mul_f32_e32 v26, 0xbfb8aa3b, v26
	v_mul_f32_e32 v25, 0xbfb8aa3b, v25
	v_exp_f32_e32 v0, v0
	v_exp_f32_e32 v24, v24
	v_exp_f32_e32 v26, v26
	v_exp_f32_e32 v25, v25
	v_min_f32_e32 v0, 0x7149f2ca, v0
	v_min_f32_e32 v24, 0x7149f2ca, v24
	v_min_f32_e32 v26, 0x7149f2ca, v26
	v_min_f32_e32 v25, 0x7149f2ca, v25
	v_add_f32_e32 v0, 1.0, v0
	v_add_f32_e32 v27, 1.0, v24
	v_add_f32_e32 v26, 1.0, v26
	v_add_f32_e32 v28, 1.0, v25
	v_rcp_f32_e32 v24, v0
	v_rcp_f32_e32 v25, v27
	v_rcp_f32_e32 v26, v26
	v_rcp_f32_e32 v27, v28
	v_add_u32_e32 v0, v44, v120
	v_mul_f32_e32 v20, v20, v24
	v_mul_f32_e32 v21, v21, v25
	v_lshl_add_u64 v[28:29], v[0:1], 1, s[2:3]
	v_mul_f32_e32 v22, v22, v26
	v_mul_f32_e32 v23, v23, v27
	v_cvt_pk_bf16_f32 v20, v20, v21
	v_cvt_pk_bf16_f32 v21, v22, v23
	global_store_dwordx2 v[28:29], v[20:21], off
	s_nop 0
	v_mul_lo_u32 v0, v30, s13
	v_lshl_add_u64 v[20:21], v[0:1], 1, s[8:9]
	v_lshl_add_u64 v[20:21], v[20:21], 0, v[142:143]
	global_load_dwordx2 v[22:23], v[20:21], off
	global_load_dwordx2 v[198:199], v[20:21], off offset:32
	global_load_dwordx2 v[200:201], v[20:21], off offset:256
	global_load_dwordx2 v[202:203], v[20:21], off offset:288
	v_lshlrev_b32_e32 v28, 10, v30
	s_waitcnt vmcnt(3)
	v_lshlrev_b32_e32 v0, 16, v22
	v_and_b32_e32 v22, 0xffff0000, v22
	v_lshlrev_b32_e32 v24, 16, v23
	v_and_b32_e32 v23, 0xffff0000, v23
	v_mul_f32_e32 v0, 0xbfb8aa3b, v0
	v_mul_f32_e32 v22, 0xbfb8aa3b, v22
	v_mul_f32_e32 v24, 0xbfb8aa3b, v24
	v_mul_f32_e32 v23, 0xbfb8aa3b, v23
	v_exp_f32_e32 v0, v0
	v_exp_f32_e32 v22, v22
	v_exp_f32_e32 v24, v24
	v_exp_f32_e32 v23, v23
	v_min_f32_e32 v0, 0x7149f2ca, v0
	v_min_f32_e32 v22, 0x7149f2ca, v22
	v_min_f32_e32 v24, 0x7149f2ca, v24
	v_min_f32_e32 v23, 0x7149f2ca, v23
	v_add_f32_e32 v0, 1.0, v0
	v_add_f32_e32 v25, 1.0, v22
	v_add_f32_e32 v24, 1.0, v24
	v_add_f32_e32 v26, 1.0, v23
	v_rcp_f32_e32 v22, v0
	v_rcp_f32_e32 v23, v25
	v_rcp_f32_e32 v24, v24
	v_rcp_f32_e32 v25, v26
	v_add_u32_e32 v0, v28, v2
	v_mul_f32_e32 v16, v16, v22
	v_mul_f32_e32 v17, v17, v23
	v_lshl_add_u64 v[26:27], v[0:1], 1, s[2:3]
	v_mul_f32_e32 v18, v18, v24
	v_mul_f32_e32 v19, v19, v25
	v_cvt_pk_bf16_f32 v16, v16, v17
	v_cvt_pk_bf16_f32 v17, v18, v19
	global_store_dwordx2 v[26:27], v[16:17], off
	s_nop 0
	s_waitcnt vmcnt(3)
	v_lshlrev_b32_e32 v0, 16, v198
	v_and_b32_e32 v2, 0xffff0000, v198
	v_lshlrev_b32_e32 v16, 16, v199
	v_and_b32_e32 v17, 0xffff0000, v199
	v_mul_f32_e32 v0, 0xbfb8aa3b, v0
	v_mul_f32_e32 v2, 0xbfb8aa3b, v2
	v_mul_f32_e32 v16, 0xbfb8aa3b, v16
	v_mul_f32_e32 v17, 0xbfb8aa3b, v17
	v_exp_f32_e32 v0, v0
	v_exp_f32_e32 v2, v2
	v_exp_f32_e32 v16, v16
	v_exp_f32_e32 v17, v17
	v_min_f32_e32 v0, 0x7149f2ca, v0
	v_min_f32_e32 v2, 0x7149f2ca, v2
	v_min_f32_e32 v16, 0x7149f2ca, v16
	v_min_f32_e32 v17, 0x7149f2ca, v17
	v_add_f32_e32 v0, 1.0, v0
	v_add_f32_e32 v2, 1.0, v2
	v_add_f32_e32 v18, 1.0, v16
	v_add_f32_e32 v19, 1.0, v17
	v_rcp_f32_e32 v16, v0
	v_rcp_f32_e32 v17, v2
	v_rcp_f32_e32 v18, v18
	v_rcp_f32_e32 v19, v19
	v_add_u32_e32 v0, v28, v3
	v_mul_f32_e32 v12, v12, v16
	v_mul_f32_e32 v13, v13, v17
	v_lshl_add_u64 v[2:3], v[0:1], 1, s[2:3]
	v_mul_f32_e32 v14, v14, v18
	v_mul_f32_e32 v15, v15, v19
	v_cvt_pk_bf16_f32 v12, v12, v13
	v_cvt_pk_bf16_f32 v13, v14, v15
	global_store_dwordx2 v[2:3], v[12:13], off
	s_nop 0
	s_waitcnt vmcnt(3)
	v_lshlrev_b32_e32 v0, 16, v200
	v_and_b32_e32 v2, 0xffff0000, v200
	v_lshlrev_b32_e32 v12, 16, v201
	v_and_b32_e32 v3, 0xffff0000, v201
	v_mul_f32_e32 v0, 0xbfb8aa3b, v0
	v_mul_f32_e32 v2, 0xbfb8aa3b, v2
	v_mul_f32_e32 v12, 0xbfb8aa3b, v12
	v_mul_f32_e32 v3, 0xbfb8aa3b, v3
	v_exp_f32_e32 v0, v0
	v_exp_f32_e32 v2, v2
	v_exp_f32_e32 v12, v12
	v_exp_f32_e32 v3, v3
	v_min_f32_e32 v0, 0x7149f2ca, v0
	v_min_f32_e32 v2, 0x7149f2ca, v2
	v_min_f32_e32 v12, 0x7149f2ca, v12
	v_min_f32_e32 v3, 0x7149f2ca, v3
	v_add_f32_e32 v0, 1.0, v0
	v_add_f32_e32 v13, 1.0, v2
	v_add_f32_e32 v12, 1.0, v12
	v_add_f32_e32 v14, 1.0, v3
	v_rcp_f32_e32 v2, v0
	v_rcp_f32_e32 v3, v13
	v_rcp_f32_e32 v12, v12
	v_rcp_f32_e32 v13, v14
	v_add_u32_e32 v0, v28, v124
	v_mul_f32_e32 v2, v8, v2
	v_mul_f32_e32 v3, v9, v3
	v_lshl_add_u64 v[14:15], v[0:1], 1, s[2:3]
	v_mul_f32_e32 v8, v10, v12
	v_mul_f32_e32 v9, v11, v13
	v_cvt_pk_bf16_f32 v2, v2, v3
	v_cvt_pk_bf16_f32 v3, v8, v9
	global_store_dwordx2 v[14:15], v[2:3], off
	s_nop 0
	s_waitcnt vmcnt(3)
	v_lshlrev_b32_e32 v0, 16, v202
	v_and_b32_e32 v2, 0xffff0000, v202
	v_lshlrev_b32_e32 v8, 16, v203
	v_and_b32_e32 v3, 0xffff0000, v203
	v_mul_f32_e32 v0, 0xbfb8aa3b, v0
	v_mul_f32_e32 v2, 0xbfb8aa3b, v2
	v_mul_f32_e32 v8, 0xbfb8aa3b, v8
	v_mul_f32_e32 v3, 0xbfb8aa3b, v3
	v_exp_f32_e32 v0, v0
	v_exp_f32_e32 v2, v2
	v_exp_f32_e32 v8, v8
	v_exp_f32_e32 v3, v3
	v_min_f32_e32 v0, 0x7149f2ca, v0
	v_min_f32_e32 v2, 0x7149f2ca, v2
	v_min_f32_e32 v8, 0x7149f2ca, v8
	v_min_f32_e32 v3, 0x7149f2ca, v3
	v_add_f32_e32 v0, 1.0, v0
	v_add_f32_e32 v9, 1.0, v2
	v_add_f32_e32 v8, 1.0, v8
	v_add_f32_e32 v10, 1.0, v3
	v_rcp_f32_e32 v2, v0
	v_rcp_f32_e32 v3, v9
	v_rcp_f32_e32 v8, v8
	v_rcp_f32_e32 v9, v10
	v_add_u32_e32 v0, v28, v120
	v_mul_f32_e32 v2, v4, v2
	v_mul_f32_e32 v3, v5, v3
	v_lshl_add_u64 v[10:11], v[0:1], 1, s[2:3]
	v_mul_f32_e32 v4, v6, v8
	v_mul_f32_e32 v5, v7, v9
	v_cvt_pk_bf16_f32 v2, v2, v3
	v_cvt_pk_bf16_f32 v3, v4, v5
	global_store_dwordx2 v[10:11], v[2:3], off
	s_cbranch_vccnz .LBB0_1071
	s_andn2_b64 vcc, exec, s[0:1]
	s_cbranch_vccnz .LBB0_1070
	s_barrier
	s_branch .LBB0_1070

.LBB0_1243:
	v_lshl_add_u32 v142, s8, 8, v146
	v_and_b32_e32 v140, -16, v142
	v_lshlrev_b32_e32 v140, 6, v140
	v_lshl_add_u32 v140, v186, 4, v140
	v_add_u32_e32 v230, 0x2000, v140
	global_load_dwordx4 v[198:201], v140, s[2:3]
	global_load_dwordx4 v[202:205], v140, s[2:3] offset:1024
	global_load_dwordx4 v[206:209], v140, s[2:3] offset:2048
	global_load_dwordx4 v[210:213], v140, s[2:3] offset:3072
	global_load_dwordx4 v[214:217], v230, s[2:3]
	global_load_dwordx4 v[218:221], v230, s[2:3] offset:1024
	global_load_dwordx4 v[222:225], v230, s[2:3] offset:2048
	global_load_dwordx4 v[226:229], v230, s[2:3] offset:3072
	v_and_b32_e32 v231, 15, v186
	v_lshlrev_b32_e32 v231, 4, v231
	s_waitcnt vmcnt(0)
	v_add_f32_e32 v198, v198, v199
	v_add_f32_e32 v200, v200, v201
	v_add_f32_e32 v202, v202, v203
	v_add_f32_e32 v204, v204, v205
	v_add_f32_e32 v206, v206, v207
	v_add_f32_e32 v208, v208, v209
	v_add_f32_e32 v210, v210, v211
	v_add_f32_e32 v212, v212, v213
	v_add_f32_e32 v214, v214, v215
	v_add_f32_e32 v216, v216, v217
	v_add_f32_e32 v218, v218, v219
	v_add_f32_e32 v220, v220, v221
	v_add_f32_e32 v222, v222, v223
	v_add_f32_e32 v224, v224, v225
	v_add_f32_e32 v226, v226, v227
	v_add_f32_e32 v228, v228, v229
	v_add_f32_e32 v198, v198, v200
	v_add_f32_e32 v202, v202, v204
	v_add_f32_e32 v206, v206, v208
	v_add_f32_e32 v210, v210, v212
	v_add_f32_e32 v214, v214, v216
	v_add_f32_e32 v218, v218, v220
	v_add_f32_e32 v222, v222, v224
	v_add_f32_e32 v226, v226, v228
	v_add_f32_dpp v198, v198, v198 quad_perm:[1,0,3,2] row_mask:0xf bank_mask:0xf
	v_add_f32_dpp v202, v202, v202 quad_perm:[1,0,3,2] row_mask:0xf bank_mask:0xf
	v_add_f32_dpp v206, v206, v206 quad_perm:[1,0,3,2] row_mask:0xf bank_mask:0xf
	v_add_f32_dpp v210, v210, v210 quad_perm:[1,0,3,2] row_mask:0xf bank_mask:0xf
	v_add_f32_dpp v214, v214, v214 quad_perm:[1,0,3,2] row_mask:0xf bank_mask:0xf
	v_add_f32_dpp v218, v218, v218 quad_perm:[1,0,3,2] row_mask:0xf bank_mask:0xf
	v_add_f32_dpp v222, v222, v222 quad_perm:[1,0,3,2] row_mask:0xf bank_mask:0xf
	v_add_f32_dpp v226, v226, v226 quad_perm:[1,0,3,2] row_mask:0xf bank_mask:0xf
	v_add_f32_dpp v198, v198, v198 quad_perm:[2,3,0,1] row_mask:0xf bank_mask:0xf
	v_add_f32_dpp v202, v202, v202 quad_perm:[2,3,0,1] row_mask:0xf bank_mask:0xf
	v_add_f32_dpp v206, v206, v206 quad_perm:[2,3,0,1] row_mask:0xf bank_mask:0xf
	v_add_f32_dpp v210, v210, v210 quad_perm:[2,3,0,1] row_mask:0xf bank_mask:0xf
	v_add_f32_dpp v214, v214, v214 quad_perm:[2,3,0,1] row_mask:0xf bank_mask:0xf
	v_add_f32_dpp v218, v218, v218 quad_perm:[2,3,0,1] row_mask:0xf bank_mask:0xf
	v_add_f32_dpp v222, v222, v222 quad_perm:[2,3,0,1] row_mask:0xf bank_mask:0xf
	v_add_f32_dpp v226, v226, v226 quad_perm:[2,3,0,1] row_mask:0xf bank_mask:0xf
	v_fmamk_f32 v198, v198, 0x3a800000, v182
	v_fmamk_f32 v202, v202, 0x3a800000, v182
	v_fmamk_f32 v206, v206, 0x3a800000, v182
	v_fmamk_f32 v210, v210, 0x3a800000, v182
	v_fmamk_f32 v214, v214, 0x3a800000, v182
	v_fmamk_f32 v218, v218, 0x3a800000, v182
	v_fmamk_f32 v222, v222, 0x3a800000, v182
	v_fmamk_f32 v226, v226, 0x3a800000, v182
	v_mul_f32_e32 v199, 0x4b800000, v198
	v_mul_f32_e32 v203, 0x4b800000, v202
	v_mul_f32_e32 v207, 0x4b800000, v206
	v_mul_f32_e32 v211, 0x4b800000, v210
	v_mul_f32_e32 v215, 0x4b800000, v214
	v_mul_f32_e32 v219, 0x4b800000, v218
	v_mul_f32_e32 v223, 0x4b800000, v222
	v_mul_f32_e32 v227, 0x4b800000, v226
	v_cmp_gt_f32_e32 vcc, 0x800000, v198
	s_nop 1
	v_cndmask_b32_e32 v200, v198, v199, vcc
	v_rsq_f32_e32 v200, v200
	s_nop 0
	v_mul_f32_e32 v201, 0x45800000, v200
	v_cndmask_b32_e32 v200, v200, v201, vcc
	v_cmp_gt_f32_e32 vcc, 0x800000, v202
	s_nop 1
	v_cndmask_b32_e32 v204, v202, v203, vcc
	v_rsq_f32_e32 v204, v204
	s_nop 0
	v_mul_f32_e32 v205, 0x45800000, v204
	v_cndmask_b32_e32 v204, v204, v205, vcc
	v_cmp_gt_f32_e32 vcc, 0x800000, v206
	s_nop 1
	v_cndmask_b32_e32 v208, v206, v207, vcc
	v_rsq_f32_e32 v208, v208
	s_nop 0
	v_mul_f32_e32 v209, 0x45800000, v208
	v_cndmask_b32_e32 v208, v208, v209, vcc
	v_cmp_gt_f32_e32 vcc, 0x800000, v210
	s_nop 1
	v_cndmask_b32_e32 v212, v210, v211, vcc
	v_rsq_f32_e32 v212, v212
	s_nop 0
	v_mul_f32_e32 v213, 0x45800000, v212
	v_cndmask_b32_e32 v212, v212, v213, vcc
	v_cmp_gt_f32_e32 vcc, 0x800000, v214
	s_nop 1
	v_cndmask_b32_e32 v216, v214, v215, vcc
	v_rsq_f32_e32 v216, v216
	s_nop 0
	v_mul_f32_e32 v217, 0x45800000, v216
	v_cndmask_b32_e32 v216, v216, v217, vcc
	v_cmp_gt_f32_e32 vcc, 0x800000, v218
	s_nop 1
	v_cndmask_b32_e32 v220, v218, v219, vcc
	v_rsq_f32_e32 v220, v220
	s_nop 0
	v_mul_f32_e32 v221, 0x45800000, v220
	v_cndmask_b32_e32 v220, v220, v221, vcc
	v_cmp_gt_f32_e32 vcc, 0x800000, v222
	s_nop 1
	v_cndmask_b32_e32 v224, v222, v223, vcc
	v_rsq_f32_e32 v224, v224
	s_nop 0
	v_mul_f32_e32 v225, 0x45800000, v224
	v_cndmask_b32_e32 v224, v224, v225, vcc
	v_cmp_gt_f32_e32 vcc, 0x800000, v226
	s_nop 1
	v_cndmask_b32_e32 v228, v226, v227, vcc
	v_rsq_f32_e32 v228, v228
	s_nop 0
	v_mul_f32_e32 v229, 0x45800000, v228
	v_cndmask_b32_e32 v228, v228, v229, vcc
	s_nop 1
	ds_bpermute_b32 v242, v231, v200
	ds_bpermute_b32 v243, v231, v204
	ds_bpermute_b32 v244, v231, v208
	ds_bpermute_b32 v245, v231, v212
	ds_bpermute_b32 v246, v231, v216
	ds_bpermute_b32 v247, v231, v220
	ds_bpermute_b32 v248, v231, v224
	ds_bpermute_b32 v249, v231, v228
	s_waitcnt lgkmcnt(0)
	v_ashrrev_i32_e32 v143, 31, v142
	v_lshlrev_b64 v[140:141], 6, v[142:143]
	v_lshl_add_u64 v[140:141], s[2:3], 0, v[140:141]
	v_lshl_or_b32 v140, s0, 8, v148
	s_movk_i32 s0, 0x1000
	v_mov_b32_e32 v144, v242
	v_mov_b32_e32 v145, v144
	v_cmp_gt_i32_e32 vcc, s0, v140
	s_and_saveexec_b64 s[0:1], vcc
	s_cbranch_execz .LBB0_1245
	v_mov_b32_e32 v150, v144
	v_mov_b32_e32 v151, v144
	v_mul_f32_e32 v126, v126, v144
	v_mul_f32_e32 v127, v127, v145
	v_mul_f32_e32 v122, v122, v144
	v_mul_f32_e32 v123, v123, v145
	v_mul_f32_e32 v128, v128, v150
	v_mul_f32_e32 v129, v129, v151
	v_max_f32_e32 v126, 0, v126
	v_max_f32_e32 v122, 0, v122
	v_max_f32_e32 v127, 0, v127
	v_max_f32_e32 v123, 0, v123
	v_mul_f32_e32 v124, v124, v150
	v_mul_f32_e32 v125, v125, v151
	v_mul_f32_e32 v126, v126, v126
	v_mul_f32_e32 v127, v127, v127
	v_mul_f32_e32 v150, v122, v122
	v_mul_f32_e32 v151, v123, v123
	v_max_f32_e32 v122, 0, v128
	v_max_f32_e32 v123, 0, v129
	v_max_f32_e32 v124, 0, v124
	v_max_f32_e32 v125, 0, v125
	v_mul_f32_e32 v128, v122, v122
	v_mul_f32_e32 v129, v123, v123
	v_cvt_pk_bf16_f32 v122, v126, v127
	v_lshlrev_b64 v[126:127], 13, v[142:143]
	v_mul_f32_e32 v152, v124, v124
	v_mul_f32_e32 v153, v125, v125
	v_lshl_add_u64 v[126:127], s[10:11], 0, v[126:127]
	v_ashrrev_i32_e32 v141, 31, v140
	v_cvt_pk_bf16_f32 v123, v128, v129
	v_cvt_pk_bf16_f32 v124, v150, v151
	v_cvt_pk_bf16_f32 v125, v152, v153
	v_lshl_add_u64 v[126:127], v[140:141], 1, v[126:127]
	global_store_dwordx4 v[126:127], v[122:125], off
.LBB0_1245:
	s_or_b64 exec, exec, s[0:1]
	s_nop 0
	v_or_b32_e32 v122, 0x80, v140
	s_movk_i32 s0, 0x1000
	v_cmp_gt_i32_e64 s[8:9], s0, v122
	s_and_saveexec_b64 s[0:1], s[8:9]
	s_cbranch_execz .LBB0_1247
	v_mov_b32_e32 v122, v144
	v_mov_b32_e32 v123, v144
	v_mul_f32_e32 v118, v118, v144
	v_mul_f32_e32 v119, v119, v145
	v_mul_f32_e32 v114, v114, v144
	v_mul_f32_e32 v115, v115, v145
	v_mul_f32_e32 v120, v120, v122
	v_mul_f32_e32 v121, v121, v123
	v_max_f32_e32 v118, 0, v118
	v_max_f32_e32 v114, 0, v114
	v_max_f32_e32 v119, 0, v119
	v_max_f32_e32 v115, 0, v115
	v_mul_f32_e32 v116, v116, v122
	v_mul_f32_e32 v117, v117, v123
	v_mul_f32_e32 v118, v118, v118
	v_mul_f32_e32 v119, v119, v119
	v_mul_f32_e32 v122, v114, v114
	v_mul_f32_e32 v123, v115, v115
	v_max_f32_e32 v114, 0, v120
	v_max_f32_e32 v115, 0, v121
	v_max_f32_e32 v116, 0, v116
	v_max_f32_e32 v117, 0, v117
	v_mul_f32_e32 v120, v114, v114
	v_mul_f32_e32 v121, v115, v115
	v_cvt_pk_bf16_f32 v114, v118, v119
	v_lshlrev_b64 v[118:119], 13, v[142:143]
	v_mul_f32_e32 v124, v116, v116
	v_mul_f32_e32 v125, v117, v117
	v_lshl_add_u64 v[118:119], s[10:11], 0, v[118:119]
	v_ashrrev_i32_e32 v141, 31, v140
	v_cvt_pk_bf16_f32 v115, v120, v121
	v_cvt_pk_bf16_f32 v116, v122, v123
	v_cvt_pk_bf16_f32 v117, v124, v125
	v_lshl_add_u64 v[118:119], v[140:141], 1, v[118:119]
	global_store_dwordx4 v[118:119], v[114:117], off offset:256
.LBB0_1247:
	s_or_b64 exec, exec, s[0:1]
	s_nop 0
	v_or_b32_e32 v114, 16, v142
	v_ashrrev_i32_e32 v115, 31, v114
	v_lshlrev_b64 v[116:117], 6, v[114:115]
	v_lshl_add_u64 v[128:129], s[2:3], 0, v[116:117]
	v_mov_b32_e32 v116, v243
	v_mov_b32_e32 v117, v116
	s_and_saveexec_b64 s[0:1], vcc
	s_cbranch_execz .LBB0_1249
	v_mov_b32_e32 v118, v116
	v_mov_b32_e32 v119, v116
	v_mul_f32_e32 v110, v110, v116
	v_mul_f32_e32 v111, v111, v117
	v_mul_f32_e32 v106, v106, v116
	v_mul_f32_e32 v107, v107, v117
	v_mul_f32_e32 v112, v112, v118
	v_mul_f32_e32 v113, v113, v119
	v_max_f32_e32 v110, 0, v110
	v_max_f32_e32 v106, 0, v106
	v_max_f32_e32 v111, 0, v111
	v_max_f32_e32 v107, 0, v107
	v_mul_f32_e32 v108, v108, v118
	v_mul_f32_e32 v109, v109, v119
	v_mul_f32_e32 v110, v110, v110
	v_mul_f32_e32 v111, v111, v111
	v_mul_f32_e32 v118, v106, v106
	v_mul_f32_e32 v119, v107, v107
	v_max_f32_e32 v106, 0, v112
	v_max_f32_e32 v107, 0, v113
	v_max_f32_e32 v108, 0, v108
	v_max_f32_e32 v109, 0, v109
	v_mul_f32_e32 v112, v106, v106
	v_mul_f32_e32 v113, v107, v107
	v_cvt_pk_bf16_f32 v106, v110, v111
	v_lshlrev_b64 v[110:111], 13, v[114:115]
	v_mul_f32_e32 v120, v108, v108
	v_mul_f32_e32 v121, v109, v109
	v_lshl_add_u64 v[110:111], s[10:11], 0, v[110:111]
	v_ashrrev_i32_e32 v141, 31, v140
	v_cvt_pk_bf16_f32 v107, v112, v113
	v_cvt_pk_bf16_f32 v108, v118, v119
	v_cvt_pk_bf16_f32 v109, v120, v121
	v_lshl_add_u64 v[110:111], v[140:141], 1, v[110:111]
	global_store_dwordx4 v[110:111], v[106:109], off
.LBB0_1249:
	s_or_b64 exec, exec, s[0:1]
	s_and_saveexec_b64 s[0:1], s[8:9]
	s_cbranch_execz .LBB0_1251
	v_mov_b32_e32 v106, v116
	v_mov_b32_e32 v107, v116
	v_mul_f32_e32 v102, v102, v116
	v_mul_f32_e32 v103, v103, v117
	v_mul_f32_e32 v98, v98, v116
	v_mul_f32_e32 v99, v99, v117
	v_mul_f32_e32 v104, v104, v106
	v_mul_f32_e32 v105, v105, v107
	v_max_f32_e32 v102, 0, v102
	v_max_f32_e32 v98, 0, v98
	v_max_f32_e32 v103, 0, v103
	v_max_f32_e32 v99, 0, v99
	v_mul_f32_e32 v100, v100, v106
	v_mul_f32_e32 v101, v101, v107
	v_mul_f32_e32 v102, v102, v102
	v_mul_f32_e32 v103, v103, v103
	v_mul_f32_e32 v106, v98, v98
	v_mul_f32_e32 v107, v99, v99
	v_max_f32_e32 v98, 0, v104
	v_max_f32_e32 v99, 0, v105
	v_max_f32_e32 v100, 0, v100
	v_max_f32_e32 v101, 0, v101
	v_mul_f32_e32 v104, v98, v98
	v_mul_f32_e32 v105, v99, v99
	v_cvt_pk_bf16_f32 v98, v102, v103
	v_lshlrev_b64 v[102:103], 13, v[114:115]
	v_mul_f32_e32 v108, v100, v100
	v_mul_f32_e32 v109, v101, v101
	v_lshl_add_u64 v[102:103], s[10:11], 0, v[102:103]
	v_ashrrev_i32_e32 v141, 31, v140
	v_cvt_pk_bf16_f32 v99, v104, v105
	v_cvt_pk_bf16_f32 v100, v106, v107
	v_cvt_pk_bf16_f32 v101, v108, v109
	v_lshl_add_u64 v[102:103], v[140:141], 1, v[102:103]
	global_store_dwordx4 v[102:103], v[98:101], off offset:256
.LBB0_1251:
	s_or_b64 exec, exec, s[0:1]
	s_nop 0
	v_or_b32_e32 v98, 32, v142
	v_ashrrev_i32_e32 v99, 31, v98
	v_lshlrev_b64 v[100:101], 6, v[98:99]
	v_lshl_add_u64 v[112:113], s[2:3], 0, v[100:101]
	v_mov_b32_e32 v100, v244
	v_mov_b32_e32 v101, v100
	s_and_saveexec_b64 s[0:1], vcc
	s_cbranch_execz .LBB0_1253
	v_mov_b32_e32 v102, v100
	v_mov_b32_e32 v103, v100
	v_mul_f32_e32 v94, v94, v100
	v_mul_f32_e32 v95, v95, v101
	v_mul_f32_e32 v90, v90, v100
	v_mul_f32_e32 v91, v91, v101
	v_mul_f32_e32 v96, v96, v102
	v_mul_f32_e32 v97, v97, v103
	v_max_f32_e32 v94, 0, v94
	v_max_f32_e32 v90, 0, v90
	v_max_f32_e32 v95, 0, v95
	v_max_f32_e32 v91, 0, v91
	v_mul_f32_e32 v92, v92, v102
	v_mul_f32_e32 v93, v93, v103
	v_mul_f32_e32 v94, v94, v94
	v_mul_f32_e32 v95, v95, v95
	v_mul_f32_e32 v102, v90, v90
	v_mul_f32_e32 v103, v91, v91
	v_max_f32_e32 v90, 0, v96
	v_max_f32_e32 v91, 0, v97
	v_max_f32_e32 v92, 0, v92
	v_max_f32_e32 v93, 0, v93
	v_mul_f32_e32 v96, v90, v90
	v_mul_f32_e32 v97, v91, v91
	v_cvt_pk_bf16_f32 v90, v94, v95
	v_lshlrev_b64 v[94:95], 13, v[98:99]
	v_mul_f32_e32 v104, v92, v92
	v_mul_f32_e32 v105, v93, v93
	v_lshl_add_u64 v[94:95], s[10:11], 0, v[94:95]
	v_ashrrev_i32_e32 v141, 31, v140
	v_cvt_pk_bf16_f32 v91, v96, v97
	v_cvt_pk_bf16_f32 v92, v102, v103
	v_cvt_pk_bf16_f32 v93, v104, v105
	v_lshl_add_u64 v[94:95], v[140:141], 1, v[94:95]
	global_store_dwordx4 v[94:95], v[90:93], off
.LBB0_1253:
	s_or_b64 exec, exec, s[0:1]
	s_and_saveexec_b64 s[0:1], s[8:9]
	s_cbranch_execz .LBB0_1255
	v_mov_b32_e32 v90, v100
	v_mov_b32_e32 v91, v100
	v_mul_f32_e32 v86, v86, v100
	v_mul_f32_e32 v87, v87, v101
	v_mul_f32_e32 v82, v82, v100
	v_mul_f32_e32 v83, v83, v101
	v_mul_f32_e32 v88, v88, v90
	v_mul_f32_e32 v89, v89, v91
	v_max_f32_e32 v86, 0, v86
	v_max_f32_e32 v82, 0, v82
	v_max_f32_e32 v87, 0, v87
	v_max_f32_e32 v83, 0, v83
	v_mul_f32_e32 v84, v84, v90
	v_mul_f32_e32 v85, v85, v91
	v_mul_f32_e32 v86, v86, v86
	v_mul_f32_e32 v87, v87, v87
	v_mul_f32_e32 v90, v82, v82
	v_mul_f32_e32 v91, v83, v83
	v_max_f32_e32 v82, 0, v88
	v_max_f32_e32 v83, 0, v89
	v_max_f32_e32 v84, 0, v84
	v_max_f32_e32 v85, 0, v85
	v_mul_f32_e32 v88, v82, v82
	v_mul_f32_e32 v89, v83, v83
	v_cvt_pk_bf16_f32 v82, v86, v87
	v_lshlrev_b64 v[86:87], 13, v[98:99]
	v_mul_f32_e32 v92, v84, v84
	v_mul_f32_e32 v93, v85, v85
	v_lshl_add_u64 v[86:87], s[10:11], 0, v[86:87]
	v_ashrrev_i32_e32 v141, 31, v140
	v_cvt_pk_bf16_f32 v83, v88, v89
	v_cvt_pk_bf16_f32 v84, v90, v91
	v_cvt_pk_bf16_f32 v85, v92, v93
	v_lshl_add_u64 v[86:87], v[140:141], 1, v[86:87]
	global_store_dwordx4 v[86:87], v[82:85], off offset:256
.LBB0_1255:
	s_or_b64 exec, exec, s[0:1]
	s_nop 0
	v_or_b32_e32 v82, 48, v142
	v_ashrrev_i32_e32 v83, 31, v82
	v_lshlrev_b64 v[84:85], 6, v[82:83]
	v_lshl_add_u64 v[96:97], s[2:3], 0, v[84:85]
	v_mov_b32_e32 v84, v245
	v_mov_b32_e32 v85, v84
	s_and_saveexec_b64 s[0:1], vcc
	s_cbranch_execz .LBB0_1257
	v_mov_b32_e32 v86, v84
	v_mov_b32_e32 v87, v84
	v_mul_f32_e32 v78, v78, v84
	v_mul_f32_e32 v79, v79, v85
	v_mul_f32_e32 v74, v74, v84
	v_mul_f32_e32 v75, v75, v85
	v_mul_f32_e32 v80, v80, v86
	v_mul_f32_e32 v81, v81, v87
	v_max_f32_e32 v78, 0, v78
	v_max_f32_e32 v74, 0, v74
	v_max_f32_e32 v79, 0, v79
	v_max_f32_e32 v75, 0, v75
	v_mul_f32_e32 v76, v76, v86
	v_mul_f32_e32 v77, v77, v87
	v_mul_f32_e32 v78, v78, v78
	v_mul_f32_e32 v79, v79, v79
	v_mul_f32_e32 v86, v74, v74
	v_mul_f32_e32 v87, v75, v75
	v_max_f32_e32 v74, 0, v80
	v_max_f32_e32 v75, 0, v81
	v_max_f32_e32 v76, 0, v76
	v_max_f32_e32 v77, 0, v77
	v_mul_f32_e32 v80, v74, v74
	v_mul_f32_e32 v81, v75, v75
	v_cvt_pk_bf16_f32 v74, v78, v79
	v_lshlrev_b64 v[78:79], 13, v[82:83]
	v_mul_f32_e32 v88, v76, v76
	v_mul_f32_e32 v89, v77, v77
	v_lshl_add_u64 v[78:79], s[10:11], 0, v[78:79]
	v_ashrrev_i32_e32 v141, 31, v140
	v_cvt_pk_bf16_f32 v75, v80, v81
	v_cvt_pk_bf16_f32 v76, v86, v87
	v_cvt_pk_bf16_f32 v77, v88, v89
	v_lshl_add_u64 v[78:79], v[140:141], 1, v[78:79]
	global_store_dwordx4 v[78:79], v[74:77], off
.LBB0_1257:
	s_or_b64 exec, exec, s[0:1]
	s_and_saveexec_b64 s[0:1], s[8:9]
	s_cbranch_execz .LBB0_1259
	v_mov_b32_e32 v74, v84
	v_mov_b32_e32 v75, v84
	v_mul_f32_e32 v70, v70, v84
	v_mul_f32_e32 v71, v71, v85
	v_mul_f32_e32 v66, v66, v84
	v_mul_f32_e32 v67, v67, v85
	v_mul_f32_e32 v72, v72, v74
	v_mul_f32_e32 v73, v73, v75
	v_max_f32_e32 v70, 0, v70
	v_max_f32_e32 v66, 0, v66
	v_max_f32_e32 v71, 0, v71
	v_max_f32_e32 v67, 0, v67
	v_mul_f32_e32 v68, v68, v74
	v_mul_f32_e32 v69, v69, v75
	v_mul_f32_e32 v70, v70, v70
	v_mul_f32_e32 v71, v71, v71
	v_mul_f32_e32 v74, v66, v66
	v_mul_f32_e32 v75, v67, v67
	v_max_f32_e32 v66, 0, v72
	v_max_f32_e32 v67, 0, v73
	v_max_f32_e32 v68, 0, v68
	v_max_f32_e32 v69, 0, v69
	v_mul_f32_e32 v72, v66, v66
	v_mul_f32_e32 v73, v67, v67
	v_cvt_pk_bf16_f32 v66, v70, v71
	v_lshlrev_b64 v[70:71], 13, v[82:83]
	v_mul_f32_e32 v76, v68, v68
	v_mul_f32_e32 v77, v69, v69
	v_lshl_add_u64 v[70:71], s[10:11], 0, v[70:71]
	v_ashrrev_i32_e32 v141, 31, v140
	v_cvt_pk_bf16_f32 v67, v72, v73
	v_cvt_pk_bf16_f32 v68, v74, v75
	v_cvt_pk_bf16_f32 v69, v76, v77
	v_lshl_add_u64 v[70:71], v[140:141], 1, v[70:71]
	global_store_dwordx4 v[70:71], v[66:69], off offset:256
.LBB0_1259:
	s_or_b64 exec, exec, s[0:1]
	s_nop 0
	v_add_u32_e32 v66, 0x80, v142
	v_ashrrev_i32_e32 v67, 31, v66
	v_lshlrev_b64 v[68:69], 6, v[66:67]
	v_lshl_add_u64 v[80:81], s[2:3], 0, v[68:69]
	v_mov_b32_e32 v68, v246
	v_mov_b32_e32 v69, v68
	s_and_saveexec_b64 s[0:1], vcc
	s_cbranch_execz .LBB0_1261
	v_mov_b32_e32 v70, v68
	v_mov_b32_e32 v71, v68
	v_mul_f32_e32 v62, v62, v68
	v_mul_f32_e32 v63, v63, v69
	v_mul_f32_e32 v58, v58, v68
	v_mul_f32_e32 v59, v59, v69
	v_mul_f32_e32 v64, v64, v70
	v_mul_f32_e32 v65, v65, v71
	v_max_f32_e32 v62, 0, v62
	v_max_f32_e32 v58, 0, v58
	v_max_f32_e32 v63, 0, v63
	v_max_f32_e32 v59, 0, v59
	v_mul_f32_e32 v60, v60, v70
	v_mul_f32_e32 v61, v61, v71
	v_mul_f32_e32 v62, v62, v62
	v_mul_f32_e32 v63, v63, v63
	v_mul_f32_e32 v70, v58, v58
	v_mul_f32_e32 v71, v59, v59
	v_max_f32_e32 v58, 0, v64
	v_max_f32_e32 v59, 0, v65
	v_max_f32_e32 v60, 0, v60
	v_max_f32_e32 v61, 0, v61
	v_mul_f32_e32 v64, v58, v58
	v_mul_f32_e32 v65, v59, v59
	v_cvt_pk_bf16_f32 v58, v62, v63
	v_lshlrev_b64 v[62:63], 13, v[66:67]
	v_mul_f32_e32 v72, v60, v60
	v_mul_f32_e32 v73, v61, v61
	v_lshl_add_u64 v[62:63], s[10:11], 0, v[62:63]
	v_ashrrev_i32_e32 v141, 31, v140
	v_cvt_pk_bf16_f32 v59, v64, v65
	v_cvt_pk_bf16_f32 v60, v70, v71
	v_cvt_pk_bf16_f32 v61, v72, v73
	v_lshl_add_u64 v[62:63], v[140:141], 1, v[62:63]
	global_store_dwordx4 v[62:63], v[58:61], off
.LBB0_1261:
	s_or_b64 exec, exec, s[0:1]
	s_and_saveexec_b64 s[0:1], s[8:9]
	s_cbranch_execz .LBB0_1263
	v_mov_b32_e32 v58, v68
	v_mov_b32_e32 v59, v68
	v_mul_f32_e32 v54, v54, v68
	v_mul_f32_e32 v55, v55, v69
	v_mul_f32_e32 v50, v50, v68
	v_mul_f32_e32 v51, v51, v69
	v_mul_f32_e32 v56, v56, v58
	v_mul_f32_e32 v57, v57, v59
	v_max_f32_e32 v54, 0, v54
	v_max_f32_e32 v50, 0, v50
	v_max_f32_e32 v55, 0, v55
	v_max_f32_e32 v51, 0, v51
	v_mul_f32_e32 v52, v52, v58
	v_mul_f32_e32 v53, v53, v59
	v_mul_f32_e32 v54, v54, v54
	v_mul_f32_e32 v55, v55, v55
	v_mul_f32_e32 v58, v50, v50
	v_mul_f32_e32 v59, v51, v51
	v_max_f32_e32 v50, 0, v56
	v_max_f32_e32 v51, 0, v57
	v_max_f32_e32 v52, 0, v52
	v_max_f32_e32 v53, 0, v53
	v_mul_f32_e32 v56, v50, v50
	v_mul_f32_e32 v57, v51, v51
	v_cvt_pk_bf16_f32 v50, v54, v55
	v_lshlrev_b64 v[54:55], 13, v[66:67]
	v_mul_f32_e32 v60, v52, v52
	v_mul_f32_e32 v61, v53, v53
	v_lshl_add_u64 v[54:55], s[10:11], 0, v[54:55]
	v_ashrrev_i32_e32 v141, 31, v140
	v_cvt_pk_bf16_f32 v51, v56, v57
	v_cvt_pk_bf16_f32 v52, v58, v59
	v_cvt_pk_bf16_f32 v53, v60, v61
	v_lshl_add_u64 v[54:55], v[140:141], 1, v[54:55]
	global_store_dwordx4 v[54:55], v[50:53], off offset:256
.LBB0_1263:
	s_or_b64 exec, exec, s[0:1]
	s_nop 0
	v_add_u32_e32 v50, 0x90, v142
	v_ashrrev_i32_e32 v51, 31, v50
	v_lshlrev_b64 v[52:53], 6, v[50:51]
	v_lshl_add_u64 v[64:65], s[2:3], 0, v[52:53]
	v_mov_b32_e32 v52, v247
	v_mov_b32_e32 v53, v52
	s_and_saveexec_b64 s[0:1], vcc
	s_cbranch_execz .LBB0_1265
	v_mov_b32_e32 v54, v52
	v_mov_b32_e32 v55, v52
	v_mul_f32_e32 v46, v46, v52
	v_mul_f32_e32 v47, v47, v53
	v_mul_f32_e32 v42, v42, v52
	v_mul_f32_e32 v43, v43, v53
	v_mul_f32_e32 v48, v48, v54
	v_mul_f32_e32 v49, v49, v55
	v_max_f32_e32 v46, 0, v46
	v_max_f32_e32 v42, 0, v42
	v_max_f32_e32 v47, 0, v47
	v_max_f32_e32 v43, 0, v43
	v_mul_f32_e32 v44, v44, v54
	v_mul_f32_e32 v45, v45, v55
	v_mul_f32_e32 v46, v46, v46
	v_mul_f32_e32 v47, v47, v47
	v_mul_f32_e32 v54, v42, v42
	v_mul_f32_e32 v55, v43, v43
	v_max_f32_e32 v42, 0, v48
	v_max_f32_e32 v43, 0, v49
	v_max_f32_e32 v44, 0, v44
	v_max_f32_e32 v45, 0, v45
	v_mul_f32_e32 v48, v42, v42
	v_mul_f32_e32 v49, v43, v43
	v_cvt_pk_bf16_f32 v42, v46, v47
	v_lshlrev_b64 v[46:47], 13, v[50:51]
	v_mul_f32_e32 v56, v44, v44
	v_mul_f32_e32 v57, v45, v45
	v_lshl_add_u64 v[46:47], s[10:11], 0, v[46:47]
	v_ashrrev_i32_e32 v141, 31, v140
	v_cvt_pk_bf16_f32 v43, v48, v49
	v_cvt_pk_bf16_f32 v44, v54, v55
	v_cvt_pk_bf16_f32 v45, v56, v57
	v_lshl_add_u64 v[46:47], v[140:141], 1, v[46:47]
	global_store_dwordx4 v[46:47], v[42:45], off
.LBB0_1265:
	s_or_b64 exec, exec, s[0:1]
	s_and_saveexec_b64 s[0:1], s[8:9]
	s_cbranch_execz .LBB0_1267
	v_mov_b32_e32 v42, v52
	v_mov_b32_e32 v43, v52
	v_mul_f32_e32 v38, v38, v52
	v_mul_f32_e32 v39, v39, v53
	v_mul_f32_e32 v34, v34, v52
	v_mul_f32_e32 v35, v35, v53
	v_mul_f32_e32 v40, v40, v42
	v_mul_f32_e32 v41, v41, v43
	v_max_f32_e32 v38, 0, v38
	v_max_f32_e32 v34, 0, v34
	v_max_f32_e32 v39, 0, v39
	v_max_f32_e32 v35, 0, v35
	v_mul_f32_e32 v36, v36, v42
	v_mul_f32_e32 v37, v37, v43
	v_mul_f32_e32 v38, v38, v38
	v_mul_f32_e32 v39, v39, v39
	v_mul_f32_e32 v42, v34, v34
	v_mul_f32_e32 v43, v35, v35
	v_max_f32_e32 v34, 0, v40
	v_max_f32_e32 v35, 0, v41
	v_max_f32_e32 v36, 0, v36
	v_max_f32_e32 v37, 0, v37
	v_mul_f32_e32 v40, v34, v34
	v_mul_f32_e32 v41, v35, v35
	v_cvt_pk_bf16_f32 v34, v38, v39
	v_lshlrev_b64 v[38:39], 13, v[50:51]
	v_mul_f32_e32 v44, v36, v36
	v_mul_f32_e32 v45, v37, v37
	v_lshl_add_u64 v[38:39], s[10:11], 0, v[38:39]
	v_ashrrev_i32_e32 v141, 31, v140
	v_cvt_pk_bf16_f32 v35, v40, v41
	v_cvt_pk_bf16_f32 v36, v42, v43
	v_cvt_pk_bf16_f32 v37, v44, v45
	v_lshl_add_u64 v[38:39], v[140:141], 1, v[38:39]
	global_store_dwordx4 v[38:39], v[34:37], off offset:256
.LBB0_1267:
	s_or_b64 exec, exec, s[0:1]
	s_nop 0
	v_add_u32_e32 v34, 0xa0, v142
	v_ashrrev_i32_e32 v35, 31, v34
	v_lshlrev_b64 v[36:37], 6, v[34:35]
	v_lshl_add_u64 v[48:49], s[2:3], 0, v[36:37]
	v_mov_b32_e32 v36, v248
	v_mov_b32_e32 v37, v36
	s_and_saveexec_b64 s[0:1], vcc
	s_cbranch_execz .LBB0_1269
	v_mov_b32_e32 v38, v36
	v_mov_b32_e32 v39, v36
	v_mul_f32_e32 v30, v30, v36
	v_mul_f32_e32 v31, v31, v37
	v_mul_f32_e32 v26, v26, v36
	v_mul_f32_e32 v27, v27, v37
	v_mul_f32_e32 v32, v32, v38
	v_mul_f32_e32 v33, v33, v39
	v_max_f32_e32 v30, 0, v30
	v_max_f32_e32 v26, 0, v26
	v_max_f32_e32 v31, 0, v31
	v_max_f32_e32 v27, 0, v27
	v_mul_f32_e32 v28, v28, v38
	v_mul_f32_e32 v29, v29, v39
	v_mul_f32_e32 v30, v30, v30
	v_mul_f32_e32 v31, v31, v31
	v_mul_f32_e32 v38, v26, v26
	v_mul_f32_e32 v39, v27, v27
	v_max_f32_e32 v26, 0, v32
	v_max_f32_e32 v27, 0, v33
	v_max_f32_e32 v28, 0, v28
	v_max_f32_e32 v29, 0, v29
	v_mul_f32_e32 v32, v26, v26
	v_mul_f32_e32 v33, v27, v27
	v_cvt_pk_bf16_f32 v26, v30, v31
	v_lshlrev_b64 v[30:31], 13, v[34:35]
	v_mul_f32_e32 v40, v28, v28
	v_mul_f32_e32 v41, v29, v29
	v_lshl_add_u64 v[30:31], s[10:11], 0, v[30:31]
	v_ashrrev_i32_e32 v141, 31, v140
	v_cvt_pk_bf16_f32 v27, v32, v33
	v_cvt_pk_bf16_f32 v28, v38, v39
	v_cvt_pk_bf16_f32 v29, v40, v41
	v_lshl_add_u64 v[30:31], v[140:141], 1, v[30:31]
	global_store_dwordx4 v[30:31], v[26:29], off
.LBB0_1269:
	s_or_b64 exec, exec, s[0:1]
	s_and_saveexec_b64 s[0:1], s[8:9]
	s_cbranch_execz .LBB0_1271
	v_mov_b32_e32 v26, v36
	v_mov_b32_e32 v27, v36
	v_mul_f32_e32 v22, v22, v36
	v_mul_f32_e32 v23, v23, v37
	v_mul_f32_e32 v18, v18, v36
	v_mul_f32_e32 v19, v19, v37
	v_mul_f32_e32 v24, v24, v26
	v_mul_f32_e32 v25, v25, v27
	v_max_f32_e32 v22, 0, v22
	v_max_f32_e32 v18, 0, v18
	v_max_f32_e32 v23, 0, v23
	v_max_f32_e32 v19, 0, v19
	v_mul_f32_e32 v20, v20, v26
	v_mul_f32_e32 v21, v21, v27
	v_mul_f32_e32 v22, v22, v22
	v_mul_f32_e32 v23, v23, v23
	v_mul_f32_e32 v26, v18, v18
	v_mul_f32_e32 v27, v19, v19
	v_max_f32_e32 v18, 0, v24
	v_max_f32_e32 v19, 0, v25
	v_max_f32_e32 v20, 0, v20
	v_max_f32_e32 v21, 0, v21
	v_mul_f32_e32 v24, v18, v18
	v_mul_f32_e32 v25, v19, v19
	v_cvt_pk_bf16_f32 v18, v22, v23
	v_lshlrev_b64 v[22:23], 13, v[34:35]
	v_mul_f32_e32 v28, v20, v20
	v_mul_f32_e32 v29, v21, v21
	v_lshl_add_u64 v[22:23], s[10:11], 0, v[22:23]
	v_ashrrev_i32_e32 v141, 31, v140
	v_cvt_pk_bf16_f32 v19, v24, v25
	v_cvt_pk_bf16_f32 v20, v26, v27
	v_cvt_pk_bf16_f32 v21, v28, v29
	v_lshl_add_u64 v[22:23], v[140:141], 1, v[22:23]
	global_store_dwordx4 v[22:23], v[18:21], off offset:256
.LBB0_1271:
	s_or_b64 exec, exec, s[0:1]
	s_nop 0
	v_add_u32_e32 v18, 0xb0, v142
	v_ashrrev_i32_e32 v19, 31, v18
	v_lshlrev_b64 v[20:21], 6, v[18:19]
	v_lshl_add_u64 v[32:33], s[2:3], 0, v[20:21]
	v_mov_b32_e32 v20, v249
	v_mov_b32_e32 v21, v20
	s_and_saveexec_b64 s[0:1], vcc
	s_cbranch_execz .LBB0_1273
	v_mov_b32_e32 v22, v20
	v_mov_b32_e32 v23, v20
	v_mul_f32_e32 v14, v14, v20
	v_mul_f32_e32 v15, v15, v21
	v_mul_f32_e32 v10, v10, v20
	v_mul_f32_e32 v11, v11, v21
	v_mul_f32_e32 v16, v16, v22
	v_mul_f32_e32 v17, v17, v23
	v_max_f32_e32 v14, 0, v14
	v_max_f32_e32 v10, 0, v10
	v_max_f32_e32 v15, 0, v15
	v_max_f32_e32 v11, 0, v11
	v_mul_f32_e32 v12, v12, v22
	v_mul_f32_e32 v13, v13, v23
	v_mul_f32_e32 v14, v14, v14
	v_mul_f32_e32 v15, v15, v15
	v_mul_f32_e32 v22, v10, v10
	v_mul_f32_e32 v23, v11, v11
	v_max_f32_e32 v10, 0, v16
	v_max_f32_e32 v11, 0, v17
	v_max_f32_e32 v12, 0, v12
	v_max_f32_e32 v13, 0, v13
	v_mul_f32_e32 v16, v10, v10
	v_mul_f32_e32 v17, v11, v11
	v_cvt_pk_bf16_f32 v10, v14, v15
	v_lshlrev_b64 v[14:15], 13, v[18:19]
	v_mul_f32_e32 v24, v12, v12
	v_mul_f32_e32 v25, v13, v13
	v_lshl_add_u64 v[14:15], s[10:11], 0, v[14:15]
	v_ashrrev_i32_e32 v141, 31, v140
	v_cvt_pk_bf16_f32 v11, v16, v17
	v_cvt_pk_bf16_f32 v12, v22, v23
	v_cvt_pk_bf16_f32 v13, v24, v25
	v_lshl_add_u64 v[14:15], v[140:141], 1, v[14:15]
	global_store_dwordx4 v[14:15], v[10:13], off
.LBB0_1273:
	s_or_b64 exec, exec, s[0:1]
	s_and_saveexec_b64 s[0:1], s[8:9]
	s_cbranch_execz .LBB0_1275
	v_mov_b32_e32 v10, v20
	v_mov_b32_e32 v11, v20
	v_mul_f32_e32 v6, v6, v20
	v_mul_f32_e32 v7, v7, v21
	v_mul_f32_e32 v2, v2, v20
	v_mul_f32_e32 v3, v3, v21
	v_mul_f32_e32 v8, v8, v10
	v_mul_f32_e32 v9, v9, v11
	v_max_f32_e32 v6, 0, v6
	v_max_f32_e32 v2, 0, v2
	v_max_f32_e32 v7, 0, v7
	v_max_f32_e32 v3, 0, v3
	v_mul_f32_e32 v4, v4, v10
	v_mul_f32_e32 v5, v5, v11
	v_mul_f32_e32 v6, v6, v6
	v_mul_f32_e32 v7, v7, v7
	v_mul_f32_e32 v10, v2, v2
	v_mul_f32_e32 v11, v3, v3
	v_max_f32_e32 v2, 0, v8
	v_max_f32_e32 v3, 0, v9
	v_max_f32_e32 v4, 0, v4
	v_max_f32_e32 v5, 0, v5
	v_mul_f32_e32 v8, v2, v2
	v_mul_f32_e32 v9, v3, v3
	v_cvt_pk_bf16_f32 v2, v6, v7
	v_lshlrev_b64 v[6:7], 13, v[18:19]
	v_mul_f32_e32 v12, v4, v4
	v_mul_f32_e32 v13, v5, v5
	v_lshl_add_u64 v[6:7], s[10:11], 0, v[6:7]
	v_ashrrev_i32_e32 v141, 31, v140
	v_cvt_pk_bf16_f32 v3, v8, v9
	v_cvt_pk_bf16_f32 v4, v10, v11
	v_cvt_pk_bf16_f32 v5, v12, v13
	v_lshl_add_u64 v[6:7], v[140:141], 1, v[6:7]
	global_store_dwordx4 v[6:7], v[2:5], off offset:256
